# flash loops: temp-free LDS-DMA issue split over both exchange stalls (first load after the row-max bpermute, other two after the row-sum bpermute)
# baseline (speedup 1.0000x reference)
;     ...
;   float mx = fmaxf(S[0][0], S[0][1]);
; #pragma unroll
;   for (int ks = 0; ks < 2; ++ks)
; #pragma unroll
;     for (int i = (ks ? 0 : 2); i < 16; i += 2) mx = fmaxf(fmaxf(mx, S[ks][i]), S[ks][i + 1]);
;   mx = fmaxf(mx, __shfl_xor(mx, 32));
;   if (MODE == 2) mx = selbit ? mx : -1e30f;
;   const float mn = fmaxf(m, mx);
;   if (__any((mn - m) * c2 > 8.f)) {
;     const float alpha = __builtin_amdgcn_exp2f((m - mn) * c2);
;     m = mn;
;     l *= alpha;
; #pragma unroll
;     for (int d = 0; d < DV / 32; ++d) O[d] = O[d] * alpha;
;   }
;   float mc = m * c2;
;   if (MODE == 2) mc = selbit ? mc : 1e30f;
;   const f32x2v c2v = {c2, c2}, mcv = {-mc, -mc};
;   f32x2v rs2 = {0.f, 0.f};
.LBB0_360:
	s_or_b64 exec, exec, s[12:13]
	v_max_f32_e32 v104, v51, v51
	v_max_f32_e32 v117, v50, v50
	v_max_f32_e32 v104, v117, v104
	v_max3_f32 v104, v104, v52, v53
	v_max3_f32 v104, v104, v54, v55
	v_max3_f32 v104, v104, v56, v57
	v_max3_f32 v104, v104, v58, v59
	v_max3_f32 v104, v104, v60, v61
	v_max3_f32 v104, v104, v62, v63
	v_max3_f32 v104, v104, v64, v65
	v_max3_f32 v104, v104, v34, v35
	v_max3_f32 v104, v104, v36, v37
	v_max3_f32 v104, v104, v38, v39
	v_max3_f32 v104, v104, v40, v41
	v_and_b32_e32 v118, 64, v207
	v_max3_f32 v104, v104, v42, v43
	v_xor_b32_e32 v117, 32, v207
	v_add_u32_e32 v118, 64, v118
	v_max3_f32 v104, v104, v44, v45
	v_cmp_lt_i32_e32 vcc, v117, v118
	v_max3_f32 v104, v104, v46, v47
	v_max3_f32 v104, v104, v48, v49
	v_cndmask_b32_e32 v117, v207, v117, vcc
	v_lshlrev_b32_e32 v117, 2, v117
	ds_bpermute_b32 v118, v117, v104
	ds_read2_b64 v[216:219], v131 offset0:128 offset1:130
	ds_read2_b64 v[220:223], v130 offset0:192 offset1:194
	ds_read2_b64 v[224:227], v131 offset0:132 offset1:134
	ds_read2_b64 v[228:231], v130 offset0:196 offset1:198
	ds_read2_b64 v[232:235], v131 offset0:136 offset1:138
	ds_read2_b64 v[236:239], v130 offset0:200 offset1:202
	ds_read2_b64 v[240:243], v131 offset0:140 offset1:142
	ds_read2_b64 v[244:247], v130 offset0:204 offset1:206
	s_cmp_ge_u32 s16, s19
	s_cbranch_scc1 .Ldma_x_mla1
	s_add_i32 s98, s6, 0xffffa800
	s_cmp_lg_u32 s22, 0
	s_cselect_b32 s98, s98, 0x10800
	v_readfirstlane_b32 s99, v107
	s_add_i32 m0, s99, s98
	s_nop 0
	global_load_lds_dwordx4 v[102:103], off
.Ldma_x_mla1:
	s_waitcnt lgkmcnt(8)
	v_max3_f32 v104, v116, v104, v118
	v_sub_f32_e32 v118, v104, v116
	v_mul_f32_e32 v118, 0x3e16c740, v118
	v_cmp_lt_f32_e32 vcc, s51, v118
	s_cbranch_vccz .LBB0_377
	v_sub_f32_e32 v116, v116, v104
	v_mul_f32_e32 v116, 0x3e16c740, v116
	v_exp_f32_e32 v116, v116
	s_nop 0
	v_mul_f32_e32 v109, v109, v116
	v_pk_mul_f32 v[16:17], v[16:17], v[116:117] op_sel_hi:[1,0]
	v_pk_mul_f32 v[14:15], v[14:15], v[116:117] op_sel_hi:[1,0]
	v_pk_mul_f32 v[12:13], v[12:13], v[116:117] op_sel_hi:[1,0]
	v_pk_mul_f32 v[10:11], v[10:11], v[116:117] op_sel_hi:[1,0]
	v_pk_mul_f32 v[8:9], v[8:9], v[116:117] op_sel_hi:[1,0]
	v_pk_mul_f32 v[6:7], v[6:7], v[116:117] op_sel_hi:[1,0]
	v_pk_mul_f32 v[4:5], v[4:5], v[116:117] op_sel_hi:[1,0]
	v_pk_mul_f32 v[2:3], v[2:3], v[116:117] op_sel_hi:[1,0]
	v_pk_mul_f32 v[32:33], v[32:33], v[116:117] op_sel_hi:[1,0]
	v_pk_mul_f32 v[30:31], v[30:31], v[116:117] op_sel_hi:[1,0]
	v_pk_mul_f32 v[28:29], v[28:29], v[116:117] op_sel_hi:[1,0]
	v_pk_mul_f32 v[26:27], v[26:27], v[116:117] op_sel_hi:[1,0]
	v_pk_mul_f32 v[24:25], v[24:25], v[116:117] op_sel_hi:[1,0]
	v_pk_mul_f32 v[22:23], v[22:23], v[116:117] op_sel_hi:[1,0]
	v_pk_mul_f32 v[20:21], v[20:21], v[116:117] op_sel_hi:[1,0]
	v_pk_mul_f32 v[18:19], v[18:19], v[116:117] op_sel_hi:[1,0]
	v_mov_b32_e32 v116, v104
.LBB0_362:
	s_cmp_eq_u64 s[8:9], 0
	s_cbranch_scc1 .Lfast_mla1
	v_mul_f32_e32 v104, 0xbe16c740, v104
	s_mov_b32 s12, 0x3e16c740
	v_pk_fma_f32 v[118:119], v[50:51], s[12:13], v[104:105] op_sel_hi:[1,0,0]
	v_cmp_lt_f32_e32 vcc, s33, v50
	v_exp_f32_e32 v118, v118
	v_exp_f32_e32 v119, v119
	v_cndmask_b32_e32 v50, 0, v118, vcc
	v_cmp_lt_f32_e32 vcc, s33, v51
	v_cndmask_b32_e64 v126, v118, v50, s[8:9]
	s_nop 0
	v_cndmask_b32_e32 v51, 0, v119, vcc
	v_cndmask_b32_e64 v127, v119, v51, s[8:9]
	v_pk_fma_f32 v[50:51], v[52:53], s[12:13], v[104:105] op_sel_hi:[1,0,0]
	v_cmp_lt_f32_e32 vcc, s33, v52
	v_exp_f32_e32 v50, v50
	v_exp_f32_e32 v51, v51
	v_cvt_pk_bf16_f32 v118, v126, v127
	v_cndmask_b32_e32 v52, 0, v50, vcc
	v_cmp_lt_f32_e32 vcc, s33, v53
	v_cndmask_b32_e64 v128, v50, v52, s[8:9]
	s_nop 0
	v_cndmask_b32_e32 v53, 0, v51, vcc
	v_cndmask_b32_e64 v129, v51, v53, s[8:9]
	v_pk_fma_f32 v[50:51], v[54:55], s[12:13], v[104:105] op_sel_hi:[1,0,0]
	v_cmp_lt_f32_e32 vcc, s33, v54
	v_exp_f32_e32 v50, v50
	v_exp_f32_e32 v51, v51
	v_cvt_pk_bf16_f32 v119, v128, v129
	v_cndmask_b32_e32 v52, 0, v50, vcc
	v_cmp_lt_f32_e32 vcc, s33, v55
	v_cndmask_b32_e64 v130, v50, v52, s[8:9]
	s_nop 0
	v_cndmask_b32_e32 v53, 0, v51, vcc
	v_cndmask_b32_e64 v131, v51, v53, s[8:9]
	v_pk_fma_f32 v[50:51], v[56:57], s[12:13], v[104:105] op_sel_hi:[1,0,0]
	v_cmp_lt_f32_e32 vcc, s33, v56
	v_exp_f32_e32 v50, v50
	v_exp_f32_e32 v51, v51
	v_cvt_pk_bf16_f32 v120, v130, v131
	v_cndmask_b32_e32 v52, 0, v50, vcc
	v_cmp_lt_f32_e32 vcc, s33, v57
	v_cndmask_b32_e64 v56, v50, v52, s[8:9]
	s_nop 0
	v_cndmask_b32_e32 v53, 0, v51, vcc
	v_cndmask_b32_e64 v57, v51, v53, s[8:9]
	v_cvt_pk_bf16_f32 v121, v56, v57
	v_cmp_lt_f32_e32 vcc, s33, v58
	s_waitcnt lgkmcnt(0)
	v_mfma_f32_32x32x16_bf16 v[18:33], v[216:219], v[118:121], v[18:33]
	s_waitcnt lgkmcnt(0)
; #define MFMA(a, b, c) __builtin_amdgcn_mfma_f32_32x32x16_bf16((a), (b), (c), 0, 0, 0)
;     ...
;   for (int ks = 0; ks < 2; ++ks)
; #pragma unroll
;     for (int st = 0; st < 2; ++st) {
;       union { unsigned u[4]; bf16x8 v; } pf;
; #pragma unroll
;       for (int j = 0; j < 4; ++j) {
;         const int i0 = 8 * st + 2 * j;
;         f32x2v t = {S[ks][i0], S[ks][i0 + 1]};
;         t = __builtin_elementwise_fma(t, c2v, mcv);
;         f32x2v pv;
;         if (variant == 1) { pv = t; } else {
;         pv.x = __builtin_amdgcn_exp2f(t.x);
;         pv.y = __builtin_amdgcn_exp2f(t.y);
;         }
;         if (MODE != 0) {
;           if (need_mask) {
;             pv.x = (S[ks][i0] > -1e29f) ? pv.x : 0.f;
;             pv.y = (S[ks][i0 + 1] > -1e29f) ? pv.y : 0.f;
;           }
;         }
;         rs2 += pv;
;         pf.u[j] = __builtin_bit_cast(unsigned, __builtin_convertvector(pv, hwbf16x2));
;       }
; #pragma unroll
;       for (int d = 0; d < DV / 32; ++d) {
;         const char* vp = base + C::KBYTES + (d * 32 + lr) * C::VSTR + (ks * 32 + 16 * st + 4 * lh) * 2;
;         const s16x4 lo = *(const s16x4*)vp, hi = *(const s16x4*)(vp + 16);
;         const bf16x8 vf = __builtin_shufflevector(lo, hi, 0, 1, 2, 3, 4, 5, 6, 7);
;         O[d] = MFMA(vf, pf.v, O[d]);
;       }
;     }
;   float rs = rs2.x + rs2.y;
;   rs += __shfl_xor(rs, 32);
;   l += rs;
;     ...
;     if (t + NST - 1 < ntile) {
;       const int sn = (stage == 0) ? NST - 1 : stage - 1;
;       FA_ISSUE(t + NST - 1, sn)
;     }
	v_mfma_f32_32x32x16_bf16 v[2:17], v[220:223], v[118:121], v[2:17]
	v_add_f32_e64 v52, v126, 0
	v_add_f32_e64 v53, v127, 0
	v_add_f32_e64 v52, v128, v52
	v_add_f32_e64 v53, v129, v53
	v_add_f32_e64 v52, v130, v52
	v_add_f32_e64 v53, v131, v53
	v_pk_add_f32 v[118:119], v[56:57], v[52:53]
	v_pk_fma_f32 v[52:53], v[58:59], s[12:13], v[104:105] op_sel_hi:[1,0,0]
	s_nop 0
	v_exp_f32_e32 v52, v52
	v_exp_f32_e32 v53, v53
	v_cndmask_b32_e32 v54, 0, v52, vcc
	v_cmp_lt_f32_e32 vcc, s33, v59
	v_cndmask_b32_e64 v120, v52, v54, s[8:9]
	s_nop 0
	v_cndmask_b32_e32 v55, 0, v53, vcc
	v_cndmask_b32_e64 v121, v53, v55, s[8:9]
	v_pk_fma_f32 v[54:55], v[60:61], s[12:13], v[104:105] op_sel_hi:[1,0,0]
	v_cmp_lt_f32_e32 vcc, s33, v60
	v_exp_f32_e32 v53, v54
	v_exp_f32_e32 v54, v55
	v_cvt_pk_bf16_f32 v52, v120, v121
	v_cndmask_b32_e32 v55, 0, v53, vcc
	v_cmp_lt_f32_e32 vcc, s33, v61
	v_cndmask_b32_e64 v60, v53, v55, s[8:9]
	s_nop 0
	v_cndmask_b32_e32 v56, 0, v54, vcc
	v_cndmask_b32_e64 v61, v54, v56, s[8:9]
	v_pk_fma_f32 v[54:55], v[62:63], s[12:13], v[104:105] op_sel_hi:[1,0,0]
	v_cmp_lt_f32_e32 vcc, s33, v62
	v_exp_f32_e32 v54, v54
	v_exp_f32_e32 v55, v55
	v_cvt_pk_bf16_f32 v53, v60, v61
	v_cndmask_b32_e32 v56, 0, v54, vcc
	v_cmp_lt_f32_e32 vcc, s33, v63
	v_cndmask_b32_e64 v62, v54, v56, s[8:9]
	s_nop 0
	v_cndmask_b32_e32 v57, 0, v55, vcc
	v_cndmask_b32_e64 v63, v55, v57, s[8:9]
	v_pk_fma_f32 v[56:57], v[64:65], s[12:13], v[104:105] op_sel_hi:[1,0,0]
	v_cmp_lt_f32_e32 vcc, s33, v64
	v_exp_f32_e32 v55, v56
	v_exp_f32_e32 v56, v57
	v_cvt_pk_bf16_f32 v54, v62, v63
	v_cndmask_b32_e32 v57, 0, v55, vcc
	v_cmp_lt_f32_e32 vcc, s33, v65
	v_cndmask_b32_e64 v64, v55, v57, s[8:9]
	s_nop 0
	v_cndmask_b32_e32 v58, 0, v56, vcc
	v_cndmask_b32_e64 v65, v56, v58, s[8:9]
	v_cvt_pk_bf16_f32 v55, v64, v65
	v_cmp_lt_f32_e32 vcc, s33, v34
	s_nop 0
	v_mfma_f32_32x32x16_bf16 v[18:33], v[224:227], v[52:55], v[18:33]
	s_waitcnt lgkmcnt(0)
	v_mfma_f32_32x32x16_bf16 v[2:17], v[228:231], v[52:55], v[2:17]
	v_fma_f32 v54, v34, s12, v104
	v_fma_f32 v55, v35, s12, v104
	v_fma_f32 v56, v36, s12, v104
	v_fma_f32 v57, v37, s12, v104
	v_exp_f32_e32 v54, v54
	v_exp_f32_e32 v55, v55
	v_pk_add_f32 v[52:53], v[120:121], v[118:119]
	v_cndmask_b32_e32 v34, 0, v54, vcc
	v_cmp_lt_f32_e32 vcc, s33, v35
	v_pk_add_f32 v[52:53], v[60:61], v[52:53]
	v_cndmask_b32_e64 v54, v54, v34, s[8:9]
	v_cndmask_b32_e32 v35, 0, v55, vcc
	v_cndmask_b32_e64 v55, v55, v35, s[8:9]
	v_exp_f32_e32 v35, v56
	v_exp_f32_e32 v56, v57
	v_cmp_lt_f32_e32 vcc, s33, v36
	v_cvt_pk_bf16_f32 v34, v54, v55
	v_pk_add_f32 v[52:53], v[62:63], v[52:53]
	v_cndmask_b32_e32 v36, 0, v35, vcc
	v_cmp_lt_f32_e32 vcc, s33, v37
	v_pk_add_f32 v[52:53], v[64:65], v[52:53]
	s_nop 0
	v_cndmask_b32_e32 v37, 0, v56, vcc
	v_cndmask_b32_e64 v57, v56, v37, s[8:9]
	v_cndmask_b32_e64 v56, v35, v36, s[8:9]
	v_pk_fma_f32 v[36:37], v[38:39], s[12:13], v[104:105] op_sel_hi:[1,0,0]
	v_cmp_lt_f32_e32 vcc, s33, v38
	v_exp_f32_e32 v36, v36
	v_exp_f32_e32 v37, v37
	v_cvt_pk_bf16_f32 v35, v56, v57
	v_cndmask_b32_e32 v38, 0, v36, vcc
	v_cmp_lt_f32_e32 vcc, s33, v39
	v_cndmask_b32_e64 v58, v36, v38, s[8:9]
	s_nop 0
	v_cndmask_b32_e32 v39, 0, v37, vcc
	v_cndmask_b32_e64 v59, v37, v39, s[8:9]
	v_pk_fma_f32 v[38:39], v[40:41], s[12:13], v[104:105] op_sel_hi:[1,0,0]
	v_cmp_lt_f32_e32 vcc, s33, v40
	v_exp_f32_e32 v37, v38
	v_exp_f32_e32 v38, v39
	v_cvt_pk_bf16_f32 v36, v58, v59
	v_cndmask_b32_e32 v39, 0, v37, vcc
	v_cmp_lt_f32_e32 vcc, s33, v41
	v_cndmask_b32_e64 v60, v37, v39, s[8:9]
	s_nop 0
	v_cndmask_b32_e32 v40, 0, v38, vcc
	v_cndmask_b32_e64 v61, v38, v40, s[8:9]
	v_cvt_pk_bf16_f32 v37, v60, v61
	v_cmp_lt_f32_e32 vcc, s33, v42
	s_waitcnt lgkmcnt(0)
	v_mfma_f32_32x32x16_bf16 v[18:33], v[232:235], v[34:37], v[18:33]
	s_waitcnt lgkmcnt(0)
	v_mfma_f32_32x32x16_bf16 v[2:17], v[236:239], v[34:37], v[2:17]
	v_add_f32_e64 v34, v54, v52
	v_add_f32_e64 v35, v55, v53
	v_add_f32_e64 v34, v56, v34
	v_add_f32_e64 v35, v57, v35
	v_add_f32_e64 v34, v58, v34
	v_add_f32_e64 v35, v59, v35
	v_pk_add_f32 v[52:53], v[60:61], v[34:35]
	v_pk_fma_f32 v[34:35], v[42:43], s[12:13], v[104:105] op_sel_hi:[1,0,0]
	s_nop 0
	v_exp_f32_e32 v34, v34
	v_exp_f32_e32 v35, v35
	v_cndmask_b32_e32 v36, 0, v34, vcc
	v_cmp_lt_f32_e32 vcc, s33, v43
	v_cndmask_b32_e64 v42, v34, v36, s[8:9]
	s_nop 0
	v_cndmask_b32_e32 v37, 0, v35, vcc
	v_cndmask_b32_e64 v43, v35, v37, s[8:9]
	v_pk_fma_f32 v[36:37], v[44:45], s[12:13], v[104:105] op_sel_hi:[1,0,0]
	v_cmp_lt_f32_e32 vcc, s33, v44
	v_exp_f32_e32 v35, v36
	v_exp_f32_e32 v36, v37
	v_cvt_pk_bf16_f32 v34, v42, v43
	v_cndmask_b32_e32 v37, 0, v35, vcc
	v_cmp_lt_f32_e32 vcc, s33, v45
	v_cndmask_b32_e64 v44, v35, v37, s[8:9]
	s_nop 0
	v_cndmask_b32_e32 v38, 0, v36, vcc
	v_cndmask_b32_e64 v45, v36, v38, s[8:9]
	v_pk_fma_f32 v[36:37], v[46:47], s[12:13], v[104:105] op_sel_hi:[1,0,0]
	v_cmp_lt_f32_e32 vcc, s33, v46
	v_exp_f32_e32 v36, v36
	v_exp_f32_e32 v37, v37
	v_cvt_pk_bf16_f32 v35, v44, v45
	v_cndmask_b32_e32 v38, 0, v36, vcc
	v_cmp_lt_f32_e32 vcc, s33, v47
	v_cndmask_b32_e64 v46, v36, v38, s[8:9]
	s_nop 0
	v_cndmask_b32_e32 v39, 0, v37, vcc
	v_cndmask_b32_e64 v47, v37, v39, s[8:9]
	v_pk_fma_f32 v[38:39], v[48:49], s[12:13], v[104:105] op_sel_hi:[1,0,0]
	v_cmp_lt_f32_e32 vcc, s33, v48
	v_exp_f32_e32 v37, v38
	v_exp_f32_e32 v38, v39
	v_cvt_pk_bf16_f32 v36, v46, v47
	v_cndmask_b32_e32 v39, 0, v37, vcc
	v_cmp_lt_f32_e32 vcc, s33, v49
	v_cndmask_b32_e64 v48, v37, v39, s[8:9]
	s_nop 0
	v_cndmask_b32_e32 v40, 0, v38, vcc
	v_cndmask_b32_e64 v49, v38, v40, s[8:9]
	v_cvt_pk_bf16_f32 v37, v48, v49
	s_waitcnt lgkmcnt(0)
	s_nop 0
	v_mfma_f32_32x32x16_bf16 v[18:33], v[240:243], v[34:37], v[18:33]
	s_waitcnt lgkmcnt(0)
	v_mfma_f32_32x32x16_bf16 v[2:17], v[244:247], v[34:37], v[2:17]
	v_add_f32_e64 v34, v42, v52
	v_add_f32_e64 v35, v43, v53
	v_add_f32_e64 v34, v44, v34
	v_add_f32_e64 v35, v45, v35
	v_add_f32_e64 v34, v46, v34
	v_add_f32_e64 v35, v47, v35
	v_pk_add_f32 v[34:35], v[48:49], v[34:35]
	s_nop 0
	v_add_f32_e32 v34, v34, v35
	ds_bpermute_b32 v35, v117, v34
	s_cmp_ge_u32 s16, s19
	s_cbranch_scc1 .Ldma_m_mla1
	v_readfirstlane_b32 s99, v93
	s_add_i32 m0, s99, s98
	v_readfirstlane_b32 s99, v108
	global_load_lds_dwordx4 v[100:101], off
	s_add_i32 m0, s99, s98
	s_nop 0
	global_load_lds_dwordx4 v[98:99], off

; #define MFMA(a, b, c) __builtin_amdgcn_mfma_f32_32x32x16_bf16((a), (b), (c), 0, 0, 0)
;     ...
;   for (int ks = 0; ks < 2; ++ks)
; #pragma unroll
;     for (int st = 0; st < 2; ++st) {
;       union { unsigned u[4]; bf16x8 v; } pf;
; #pragma unroll
;       for (int j = 0; j < 4; ++j) {
;         const int i0 = 8 * st + 2 * j;
;         f32x2v t = {S[ks][i0], S[ks][i0 + 1]};
;         t = __builtin_elementwise_fma(t, c2v, mcv);
;         f32x2v pv;
;         if (variant == 1) { pv = t; } else {
;         pv.x = __builtin_amdgcn_exp2f(t.x);
;         pv.y = __builtin_amdgcn_exp2f(t.y);
;         }
;         if (MODE != 0) {
;           if (need_mask) {
;             pv.x = (S[ks][i0] > -1e29f) ? pv.x : 0.f;
;             pv.y = (S[ks][i0 + 1] > -1e29f) ? pv.y : 0.f;
;           }
;         }
;         rs2 += pv;
;         pf.u[j] = __builtin_bit_cast(unsigned, __builtin_convertvector(pv, hwbf16x2));
;       }
; #pragma unroll
;       for (int d = 0; d < DV / 32; ++d) {
;         const char* vp = base + C::KBYTES + (d * 32 + lr) * C::VSTR + (ks * 32 + 16 * st + 4 * lh) * 2;
;         const s16x4 lo = *(const s16x4*)vp, hi = *(const s16x4*)(vp + 16);
;         const bf16x8 vf = __builtin_shufflevector(lo, hi, 0, 1, 2, 3, 4, 5, 6, 7);
;         O[d] = MFMA(vf, pf.v, O[d]);
;       }
;     }
;   float rs = rs2.x + rs2.y;
;   rs += __shfl_xor(rs, 32);
;   l += rs;
;     ...
;     if (t + NST - 1 < ntile) {
;       const int sn = (stage == 0) ? NST - 1 : stage - 1;
;       FA_ISSUE(t + NST - 1, sn)
;     }
.Lfast_mla1:
	v_mul_f32_e32 v104, 0xbe16c740, v104
	s_mov_b32 s12, 0x3e16c740
	v_pk_fma_f32 v[118:119], v[50:51], s[12:13], v[104:105] op_sel_hi:[1,0,0]
	v_exp_f32_e32 v126, v118
	v_exp_f32_e32 v127, v119
	v_pk_fma_f32 v[50:51], v[52:53], s[12:13], v[104:105] op_sel_hi:[1,0,0]
	v_exp_f32_e32 v128, v50
	v_exp_f32_e32 v129, v51
	v_cvt_pk_bf16_f32 v118, v126, v127
	v_pk_fma_f32 v[50:51], v[54:55], s[12:13], v[104:105] op_sel_hi:[1,0,0]
	v_exp_f32_e32 v130, v50
	v_exp_f32_e32 v131, v51
	v_cvt_pk_bf16_f32 v119, v128, v129
	v_pk_fma_f32 v[50:51], v[56:57], s[12:13], v[104:105] op_sel_hi:[1,0,0]
	v_exp_f32_e32 v56, v50
	v_exp_f32_e32 v57, v51
	v_cvt_pk_bf16_f32 v120, v130, v131
	v_cvt_pk_bf16_f32 v121, v56, v57
	s_waitcnt lgkmcnt(0)
	s_nop 0
	v_mfma_f32_32x32x16_bf16 v[18:33], v[216:219], v[118:121], v[18:33]
	s_waitcnt lgkmcnt(0)
	v_mfma_f32_32x32x16_bf16 v[2:17], v[220:223], v[118:121], v[2:17]
	v_add_f32_e64 v52, v126, 0
	v_add_f32_e64 v53, v127, 0
	v_add_f32_e64 v52, v128, v52
	v_add_f32_e64 v53, v129, v53
	v_add_f32_e64 v52, v130, v52
	v_add_f32_e64 v53, v131, v53
	v_pk_add_f32 v[118:119], v[56:57], v[52:53]
	v_pk_fma_f32 v[52:53], v[58:59], s[12:13], v[104:105] op_sel_hi:[1,0,0]
	v_exp_f32_e32 v120, v52
	v_exp_f32_e32 v121, v53
	v_pk_fma_f32 v[54:55], v[60:61], s[12:13], v[104:105] op_sel_hi:[1,0,0]
	v_exp_f32_e32 v60, v54
	v_exp_f32_e32 v61, v55
	v_cvt_pk_bf16_f32 v52, v120, v121
	v_pk_fma_f32 v[54:55], v[62:63], s[12:13], v[104:105] op_sel_hi:[1,0,0]
	v_exp_f32_e32 v62, v54
	v_exp_f32_e32 v63, v55
	v_cvt_pk_bf16_f32 v53, v60, v61
	v_pk_fma_f32 v[56:57], v[64:65], s[12:13], v[104:105] op_sel_hi:[1,0,0]
	v_exp_f32_e32 v64, v56
	v_exp_f32_e32 v65, v57
	v_cvt_pk_bf16_f32 v54, v62, v63
	v_cvt_pk_bf16_f32 v55, v64, v65
	s_nop 1
	v_mfma_f32_32x32x16_bf16 v[18:33], v[224:227], v[52:55], v[18:33]
	s_waitcnt lgkmcnt(0)
	v_mfma_f32_32x32x16_bf16 v[2:17], v[228:231], v[52:55], v[2:17]
	v_fma_f32 v54, v34, s12, v104
	v_fma_f32 v55, v35, s12, v104
	v_fma_f32 v56, v36, s12, v104
	v_fma_f32 v57, v37, s12, v104
	v_exp_f32_e32 v54, v54
	v_exp_f32_e32 v55, v55
	v_pk_add_f32 v[52:53], v[120:121], v[118:119]
	v_pk_add_f32 v[52:53], v[60:61], v[52:53]
	v_exp_f32_e32 v56, v56
	v_exp_f32_e32 v57, v57
	v_cvt_pk_bf16_f32 v34, v54, v55
	v_pk_add_f32 v[52:53], v[62:63], v[52:53]
	v_pk_add_f32 v[52:53], v[64:65], v[52:53]
	v_pk_fma_f32 v[36:37], v[38:39], s[12:13], v[104:105] op_sel_hi:[1,0,0]
	v_exp_f32_e32 v58, v36
	v_exp_f32_e32 v59, v37
	v_cvt_pk_bf16_f32 v35, v56, v57
	v_pk_fma_f32 v[38:39], v[40:41], s[12:13], v[104:105] op_sel_hi:[1,0,0]
	v_exp_f32_e32 v60, v38
	v_exp_f32_e32 v61, v39
	v_cvt_pk_bf16_f32 v36, v58, v59
	v_cvt_pk_bf16_f32 v37, v60, v61
	s_waitcnt lgkmcnt(0)
	s_nop 0
	v_mfma_f32_32x32x16_bf16 v[18:33], v[232:235], v[34:37], v[18:33]
	s_waitcnt lgkmcnt(0)
	v_mfma_f32_32x32x16_bf16 v[2:17], v[236:239], v[34:37], v[2:17]
	v_add_f32_e64 v34, v54, v52
	v_add_f32_e64 v35, v55, v53
	v_add_f32_e64 v34, v56, v34
	v_add_f32_e64 v35, v57, v35
	v_add_f32_e64 v34, v58, v34
	v_add_f32_e64 v35, v59, v35
	v_pk_add_f32 v[52:53], v[60:61], v[34:35]
	v_pk_fma_f32 v[34:35], v[42:43], s[12:13], v[104:105] op_sel_hi:[1,0,0]
	v_exp_f32_e32 v42, v34
	v_exp_f32_e32 v43, v35
	v_pk_fma_f32 v[36:37], v[44:45], s[12:13], v[104:105] op_sel_hi:[1,0,0]
	v_exp_f32_e32 v44, v36
	v_exp_f32_e32 v45, v37
	v_cvt_pk_bf16_f32 v34, v42, v43
	v_pk_fma_f32 v[36:37], v[46:47], s[12:13], v[104:105] op_sel_hi:[1,0,0]
	v_exp_f32_e32 v46, v36
	v_exp_f32_e32 v47, v37
	v_cvt_pk_bf16_f32 v35, v44, v45
	v_pk_fma_f32 v[38:39], v[48:49], s[12:13], v[104:105] op_sel_hi:[1,0,0]
	v_exp_f32_e32 v48, v38
	v_exp_f32_e32 v49, v39
	v_cvt_pk_bf16_f32 v36, v46, v47
	v_cvt_pk_bf16_f32 v37, v48, v49
	s_waitcnt lgkmcnt(0)
	s_nop 0
	v_mfma_f32_32x32x16_bf16 v[18:33], v[240:243], v[34:37], v[18:33]
	s_waitcnt lgkmcnt(0)
	v_mfma_f32_32x32x16_bf16 v[2:17], v[244:247], v[34:37], v[2:17]
	v_add_f32_e64 v34, v42, v52
	v_add_f32_e64 v35, v43, v53
	v_add_f32_e64 v34, v44, v34
	v_add_f32_e64 v35, v45, v35
	v_add_f32_e64 v34, v46, v34
	v_add_f32_e64 v35, v47, v35
	v_pk_add_f32 v[34:35], v[48:49], v[34:35]
	v_add_f32_e32 v34, v34, v35
	ds_bpermute_b32 v35, v117, v34
	s_cmp_ge_u32 s16, s19
	s_cbranch_scc1 .Ldma_f_mla1
	v_readfirstlane_b32 s99, v93
	s_add_i32 m0, s99, s98
	v_readfirstlane_b32 s99, v108
	global_load_lds_dwordx4 v[100:101], off
	s_add_i32 m0, s99, s98
	s_nop 0
	global_load_lds_dwordx4 v[98:99], off

; #define MFMA(a, b, c) __builtin_amdgcn_mfma_f32_32x32x16_bf16((a), (b), (c), 0, 0, 0)
;     ...
;   float mc = m * c2;
;   if (MODE == 2) mc = selbit ? mc : 1e30f;
;   const f32x2v c2v = {c2, c2}, mcv = {-mc, -mc};
;   f32x2v rs2 = {0.f, 0.f};
; #pragma unroll
;   for (int ks = 0; ks < 2; ++ks)
; #pragma unroll
;     for (int st = 0; st < 2; ++st) {
;       union { unsigned u[4]; bf16x8 v; } pf;
; #pragma unroll
;       for (int j = 0; j < 4; ++j) {
;         const int i0 = 8 * st + 2 * j;
;         f32x2v t = {S[ks][i0], S[ks][i0 + 1]};
;         t = __builtin_elementwise_fma(t, c2v, mcv);
;         f32x2v pv;
;         if (variant == 1) { pv = t; } else {
;         pv.x = __builtin_amdgcn_exp2f(t.x);
;         pv.y = __builtin_amdgcn_exp2f(t.y);
;         }
;         if (MODE != 0) {
;           if (need_mask) {
;             pv.x = (S[ks][i0] > -1e29f) ? pv.x : 0.f;
;             pv.y = (S[ks][i0 + 1] > -1e29f) ? pv.y : 0.f;
;           }
;         }
;         rs2 += pv;
;         pf.u[j] = __builtin_bit_cast(unsigned, __builtin_convertvector(pv, hwbf16x2));
;       }
; #pragma unroll
;       for (int d = 0; d < DV / 32; ++d) {
;         const char* vp = base + C::KBYTES + (d * 32 + lr) * C::VSTR + (ks * 32 + 16 * st + 4 * lh) * 2;
;         const s16x4 lo = *(const s16x4*)vp, hi = *(const s16x4*)(vp + 16);
;         const bf16x8 vf = __builtin_shufflevector(lo, hi, 0, 1, 2, 3, 4, 5, 6, 7);
;         O[d] = MFMA(vf, pf.v, O[d]);
;       }
;     }
.LBB0_424:
	s_cmp_eq_u64 s[8:9], 0
	s_cbranch_scc1 .Lfast_sel1
	v_mul_f32_e32 v110, 0xbe38aa3b, v110
	v_cndmask_b32_e64 v110, v208, v110, s[10:11]
	v_pk_fma_f32 v[120:121], v[82:83], s[96:97], v[110:111] op_sel_hi:[1,0,0]
	v_cmp_lt_f32_e32 vcc, s33, v82
	v_exp_f32_e32 v119, v120
	v_exp_f32_e32 v120, v121
	v_cndmask_b32_e32 v82, 0, v119, vcc
	v_cmp_lt_f32_e32 vcc, s33, v83
	v_cndmask_b32_e64 v128, v119, v82, s[8:9]
	s_nop 0
	v_cndmask_b32_e32 v83, 0, v120, vcc
	v_cndmask_b32_e64 v129, v120, v83, s[8:9]
	v_pk_fma_f32 v[82:83], v[84:85], s[96:97], v[110:111] op_sel_hi:[1,0,0]
	v_cmp_lt_f32_e32 vcc, s33, v84
	v_exp_f32_e32 v82, v82
	v_exp_f32_e32 v83, v83
	v_cvt_pk_bf16_f32 v120, v128, v129
	v_cndmask_b32_e32 v84, 0, v82, vcc
	v_cmp_lt_f32_e32 vcc, s33, v85
	v_cndmask_b32_e64 v152, v82, v84, s[8:9]
	s_nop 0
	v_cndmask_b32_e32 v85, 0, v83, vcc
	v_cndmask_b32_e64 v153, v83, v85, s[8:9]
	v_pk_fma_f32 v[82:83], v[86:87], s[96:97], v[110:111] op_sel_hi:[1,0,0]
	v_cmp_lt_f32_e32 vcc, s33, v86
	v_exp_f32_e32 v82, v82
	v_exp_f32_e32 v83, v83
	v_cvt_pk_bf16_f32 v121, v152, v153
	v_cndmask_b32_e32 v84, 0, v82, vcc
	v_cmp_lt_f32_e32 vcc, s33, v87
	v_cndmask_b32_e64 v154, v82, v84, s[8:9]
	s_nop 0
	v_cndmask_b32_e32 v85, 0, v83, vcc
	v_cndmask_b32_e64 v155, v83, v85, s[8:9]
	v_pk_fma_f32 v[82:83], v[88:89], s[96:97], v[110:111] op_sel_hi:[1,0,0]
	v_cmp_lt_f32_e32 vcc, s33, v88
	v_exp_f32_e32 v82, v82
	v_exp_f32_e32 v83, v83
	v_cvt_pk_bf16_f32 v122, v154, v155
	v_cndmask_b32_e32 v84, 0, v82, vcc
	v_cmp_lt_f32_e32 vcc, s33, v89
	v_cndmask_b32_e64 v88, v82, v84, s[8:9]
	s_nop 0
	v_cndmask_b32_e32 v85, 0, v83, vcc
	v_cndmask_b32_e64 v89, v83, v85, s[8:9]
	s_nop 0
	s_nop 0
	s_nop 0
	s_nop 0
	v_cvt_pk_bf16_f32 v123, v88, v89
	s_nop 0
	v_cmp_lt_f32_e32 vcc, s33, v90
	s_waitcnt lgkmcnt(0)
	v_mfma_f32_32x32x16_bf16 v[50:65], v[216:219], v[120:123], v[50:65]
	s_nop 0
	s_waitcnt lgkmcnt(0)
	v_mfma_f32_32x32x16_bf16 v[34:49], v[220:223], v[120:123], v[34:49]
	v_add_f32_e64 v84, v128, 0
	v_add_f32_e64 v85, v129, 0
	v_add_f32_e64 v84, v152, v84
	v_add_f32_e64 v85, v153, v85
	v_add_f32_e64 v84, v154, v84
	v_add_f32_e64 v85, v155, v85
	v_pk_add_f32 v[120:121], v[88:89], v[84:85]
	v_pk_fma_f32 v[84:85], v[90:91], s[96:97], v[110:111] op_sel_hi:[1,0,0]
	s_nop 0
	v_exp_f32_e32 v84, v84
	v_exp_f32_e32 v85, v85
	v_cndmask_b32_e32 v86, 0, v84, vcc
	v_cmp_lt_f32_e32 vcc, s33, v91
	v_cndmask_b32_e64 v122, v84, v86, s[8:9]
	s_nop 0
	v_cndmask_b32_e32 v87, 0, v85, vcc
	v_cndmask_b32_e64 v123, v85, v87, s[8:9]
	v_pk_fma_f32 v[86:87], v[92:93], s[96:97], v[110:111] op_sel_hi:[1,0,0]
	v_cmp_lt_f32_e32 vcc, s33, v92
	v_exp_f32_e32 v85, v86
	v_exp_f32_e32 v86, v87
	v_cvt_pk_bf16_f32 v84, v122, v123
	v_cndmask_b32_e32 v87, 0, v85, vcc
	v_cmp_lt_f32_e32 vcc, s33, v93
	v_cndmask_b32_e64 v92, v85, v87, s[8:9]
	s_nop 0
	v_cndmask_b32_e32 v88, 0, v86, vcc
	v_cndmask_b32_e64 v93, v86, v88, s[8:9]
	v_pk_fma_f32 v[86:87], v[94:95], s[96:97], v[110:111] op_sel_hi:[1,0,0]
	v_cmp_lt_f32_e32 vcc, s33, v94
	v_exp_f32_e32 v86, v86
	v_exp_f32_e32 v87, v87
	v_cvt_pk_bf16_f32 v85, v92, v93
	v_cndmask_b32_e32 v88, 0, v86, vcc
	v_cmp_lt_f32_e32 vcc, s33, v95
	v_cndmask_b32_e64 v94, v86, v88, s[8:9]
	s_nop 0
	v_cndmask_b32_e32 v89, 0, v87, vcc
	v_cndmask_b32_e64 v95, v87, v89, s[8:9]
	v_pk_fma_f32 v[88:89], v[96:97], s[96:97], v[110:111] op_sel_hi:[1,0,0]
	v_cmp_lt_f32_e32 vcc, s33, v96
	v_exp_f32_e32 v87, v88
	v_exp_f32_e32 v88, v89
	v_cvt_pk_bf16_f32 v86, v94, v95
	v_cndmask_b32_e32 v89, 0, v87, vcc
	v_cmp_lt_f32_e32 vcc, s33, v97
	v_cndmask_b32_e64 v96, v87, v89, s[8:9]
	s_nop 0
	v_cndmask_b32_e32 v90, 0, v88, vcc
	v_cndmask_b32_e64 v97, v88, v90, s[8:9]
	s_nop 0
	v_cvt_pk_bf16_f32 v87, v96, v97
	v_cmp_lt_f32_e32 vcc, s33, v66
	s_nop 0
	v_mfma_f32_32x32x16_bf16 v[50:65], v[224:227], v[84:87], v[50:65]
	s_waitcnt lgkmcnt(0)
; #define MFMA(a, b, c) __builtin_amdgcn_mfma_f32_32x32x16_bf16((a), (b), (c), 0, 0, 0)
;     ...
;   for (int ks = 0; ks < 2; ++ks)
; #pragma unroll
;     for (int st = 0; st < 2; ++st) {
;       union { unsigned u[4]; bf16x8 v; } pf;
; #pragma unroll
;       for (int j = 0; j < 4; ++j) {
;         const int i0 = 8 * st + 2 * j;
;         f32x2v t = {S[ks][i0], S[ks][i0 + 1]};
;         t = __builtin_elementwise_fma(t, c2v, mcv);
;         f32x2v pv;
;         if (variant == 1) { pv = t; } else {
;         pv.x = __builtin_amdgcn_exp2f(t.x);
;         pv.y = __builtin_amdgcn_exp2f(t.y);
;         }
;         if (MODE != 0) {
;           if (need_mask) {
;             pv.x = (S[ks][i0] > -1e29f) ? pv.x : 0.f;
;             pv.y = (S[ks][i0 + 1] > -1e29f) ? pv.y : 0.f;
;           }
;         }
;         rs2 += pv;
;         pf.u[j] = __builtin_bit_cast(unsigned, __builtin_convertvector(pv, hwbf16x2));
;       }
; #pragma unroll
;       for (int d = 0; d < DV / 32; ++d) {
;         const char* vp = base + C::KBYTES + (d * 32 + lr) * C::VSTR + (ks * 32 + 16 * st + 4 * lh) * 2;
;         const s16x4 lo = *(const s16x4*)vp, hi = *(const s16x4*)(vp + 16);
;         const bf16x8 vf = __builtin_shufflevector(lo, hi, 0, 1, 2, 3, 4, 5, 6, 7);
;         O[d] = MFMA(vf, pf.v, O[d]);
;       }
;     }
;   float rs = rs2.x + rs2.y;
;   rs += __shfl_xor(rs, 32);
;   l += rs;
;     ...
;     if (t + NST - 1 < ntile) {
;       const int sn = (stage == 0) ? NST - 1 : stage - 1;
;       FA_ISSUE(t + NST - 1, sn)
;     }
	v_mfma_f32_32x32x16_bf16 v[34:49], v[228:231], v[84:87], v[34:49]
	v_fma_f32 v86, v66, s96, v110
	v_fma_f32 v87, v67, s96, v110
	v_fma_f32 v88, v68, s96, v110
	v_fma_f32 v89, v69, s96, v110
	v_exp_f32_e32 v86, v86
	v_exp_f32_e32 v87, v87
	v_pk_add_f32 v[84:85], v[122:123], v[120:121]
	v_cndmask_b32_e32 v66, 0, v86, vcc
	v_cmp_lt_f32_e32 vcc, s33, v67
	v_pk_add_f32 v[84:85], v[92:93], v[84:85]
	v_cndmask_b32_e64 v86, v86, v66, s[8:9]
	v_cndmask_b32_e32 v67, 0, v87, vcc
	v_cndmask_b32_e64 v87, v87, v67, s[8:9]
	v_exp_f32_e32 v67, v88
	v_exp_f32_e32 v88, v89
	v_cmp_lt_f32_e32 vcc, s33, v68
	v_cvt_pk_bf16_f32 v66, v86, v87
	v_pk_add_f32 v[84:85], v[94:95], v[84:85]
	v_cndmask_b32_e32 v68, 0, v67, vcc
	v_cmp_lt_f32_e32 vcc, s33, v69
	v_pk_add_f32 v[84:85], v[96:97], v[84:85]
	s_nop 0
	v_cndmask_b32_e32 v69, 0, v88, vcc
	v_cndmask_b32_e64 v89, v88, v69, s[8:9]
	v_cndmask_b32_e64 v88, v67, v68, s[8:9]
	v_pk_fma_f32 v[68:69], v[70:71], s[96:97], v[110:111] op_sel_hi:[1,0,0]
	v_cmp_lt_f32_e32 vcc, s33, v70
	v_exp_f32_e32 v68, v68
	v_exp_f32_e32 v69, v69
	v_cvt_pk_bf16_f32 v67, v88, v89
	v_cndmask_b32_e32 v70, 0, v68, vcc
	v_cmp_lt_f32_e32 vcc, s33, v71
	v_cndmask_b32_e64 v90, v68, v70, s[8:9]
	s_nop 0
	v_cndmask_b32_e32 v71, 0, v69, vcc
	v_cndmask_b32_e64 v91, v69, v71, s[8:9]
	v_pk_fma_f32 v[70:71], v[72:73], s[96:97], v[110:111] op_sel_hi:[1,0,0]
	v_cmp_lt_f32_e32 vcc, s33, v72
	v_exp_f32_e32 v69, v70
	v_exp_f32_e32 v70, v71
	v_cvt_pk_bf16_f32 v68, v90, v91
	v_cndmask_b32_e32 v71, 0, v69, vcc
	v_cmp_lt_f32_e32 vcc, s33, v73
	v_cndmask_b32_e64 v92, v69, v71, s[8:9]
	s_nop 0
	v_cndmask_b32_e32 v72, 0, v70, vcc
	v_cndmask_b32_e64 v93, v70, v72, s[8:9]
	s_nop 0
	v_cvt_pk_bf16_f32 v69, v92, v93
	v_cmp_lt_f32_e32 vcc, s33, v74
	s_waitcnt lgkmcnt(0)
	v_mfma_f32_32x32x16_bf16 v[50:65], v[232:235], v[66:69], v[50:65]
	s_nop 0
	s_waitcnt lgkmcnt(0)
	v_mfma_f32_32x32x16_bf16 v[34:49], v[236:239], v[66:69], v[34:49]
	v_add_f32_e64 v66, v86, v84
	v_add_f32_e64 v67, v87, v85
	v_add_f32_e64 v66, v88, v66
	v_add_f32_e64 v67, v89, v67
	v_add_f32_e64 v66, v90, v66
	v_add_f32_e64 v67, v91, v67
	v_pk_add_f32 v[84:85], v[92:93], v[66:67]
	v_pk_fma_f32 v[66:67], v[74:75], s[96:97], v[110:111] op_sel_hi:[1,0,0]
	s_nop 0
	v_exp_f32_e32 v66, v66
	v_exp_f32_e32 v67, v67
	v_cndmask_b32_e32 v68, 0, v66, vcc
	v_cmp_lt_f32_e32 vcc, s33, v75
	v_cndmask_b32_e64 v74, v66, v68, s[8:9]
	s_nop 0
	v_cndmask_b32_e32 v69, 0, v67, vcc
	v_cndmask_b32_e64 v75, v67, v69, s[8:9]
	v_pk_fma_f32 v[68:69], v[76:77], s[96:97], v[110:111] op_sel_hi:[1,0,0]
	v_cmp_lt_f32_e32 vcc, s33, v76
	v_exp_f32_e32 v67, v68
	v_exp_f32_e32 v68, v69
	v_cvt_pk_bf16_f32 v66, v74, v75
	v_cndmask_b32_e32 v69, 0, v67, vcc
	v_cmp_lt_f32_e32 vcc, s33, v77
	v_cndmask_b32_e64 v76, v67, v69, s[8:9]
	s_nop 0
	v_cndmask_b32_e32 v70, 0, v68, vcc
	v_cndmask_b32_e64 v77, v68, v70, s[8:9]
	v_pk_fma_f32 v[68:69], v[78:79], s[96:97], v[110:111] op_sel_hi:[1,0,0]
	v_cmp_lt_f32_e32 vcc, s33, v78
	v_exp_f32_e32 v68, v68
	v_exp_f32_e32 v69, v69
	v_cvt_pk_bf16_f32 v67, v76, v77
	v_cndmask_b32_e32 v70, 0, v68, vcc
	v_cmp_lt_f32_e32 vcc, s33, v79
	v_cndmask_b32_e64 v78, v68, v70, s[8:9]
	s_nop 0
	v_cndmask_b32_e32 v71, 0, v69, vcc
	v_cndmask_b32_e64 v79, v69, v71, s[8:9]
	v_pk_fma_f32 v[70:71], v[80:81], s[96:97], v[110:111] op_sel_hi:[1,0,0]
	v_cmp_lt_f32_e32 vcc, s33, v80
	v_exp_f32_e32 v69, v70
	v_exp_f32_e32 v70, v71
	v_cvt_pk_bf16_f32 v68, v78, v79
	v_cndmask_b32_e32 v71, 0, v69, vcc
	v_cmp_lt_f32_e32 vcc, s33, v81
	v_cndmask_b32_e64 v80, v69, v71, s[8:9]
	s_nop 0
	v_cndmask_b32_e32 v72, 0, v70, vcc
	v_cndmask_b32_e64 v81, v70, v72, s[8:9]
	s_nop 0
	v_cvt_pk_bf16_f32 v69, v80, v81
	s_waitcnt lgkmcnt(0)
	s_nop 0
	v_mfma_f32_32x32x16_bf16 v[50:65], v[240:243], v[66:69], v[50:65]
	s_nop 0
	s_waitcnt lgkmcnt(0)
	v_mfma_f32_32x32x16_bf16 v[34:49], v[244:247], v[66:69], v[34:49]
	v_add_f32_e64 v66, v74, v84
	v_add_f32_e64 v67, v75, v85
	v_add_f32_e64 v66, v76, v66
	v_add_f32_e64 v67, v77, v67
	v_add_f32_e64 v66, v78, v66
	v_add_f32_e64 v67, v79, v67
	v_pk_add_f32 v[66:67], v[80:81], v[66:67]
	s_nop 0
	v_add_f32_e32 v66, v66, v67
	ds_bpermute_b32 v67, v165, v66
	s_add_i32 s99, s0, 3
	s_cmp_gt_u32 s99, s46
	s_cbranch_scc1 .Ldma_m_sel1
	v_readfirstlane_b32 s99, v111
	s_add_i32 m0, s99, s98
	v_readfirstlane_b32 s99, v113
	global_load_lds_dwordx4 v[106:107], off
	s_add_i32 m0, s99, s98
	s_nop 0
	global_load_lds_dwordx4 v[104:105], off

; #define MFMA(a, b, c) __builtin_amdgcn_mfma_f32_32x32x16_bf16((a), (b), (c), 0, 0, 0)
;     ...
;   for (int ks = 0; ks < 2; ++ks)
; #pragma unroll
;     for (int st = 0; st < 2; ++st) {
;       union { unsigned u[4]; bf16x8 v; } pf;
; #pragma unroll
;       for (int j = 0; j < 4; ++j) {
;         const int i0 = 8 * st + 2 * j;
;         f32x2v t = {S[ks][i0], S[ks][i0 + 1]};
;         t = __builtin_elementwise_fma(t, c2v, mcv);
;         f32x2v pv;
;         if (variant == 1) { pv = t; } else {
;         pv.x = __builtin_amdgcn_exp2f(t.x);
;         pv.y = __builtin_amdgcn_exp2f(t.y);
;         }
;         if (MODE != 0) {
;           if (need_mask) {
;             pv.x = (S[ks][i0] > -1e29f) ? pv.x : 0.f;
;             pv.y = (S[ks][i0 + 1] > -1e29f) ? pv.y : 0.f;
;           }
;         }
;         rs2 += pv;
;         pf.u[j] = __builtin_bit_cast(unsigned, __builtin_convertvector(pv, hwbf16x2));
;       }
; #pragma unroll
;       for (int d = 0; d < DV / 32; ++d) {
;         const char* vp = base + C::KBYTES + (d * 32 + lr) * C::VSTR + (ks * 32 + 16 * st + 4 * lh) * 2;
;         const s16x4 lo = *(const s16x4*)vp, hi = *(const s16x4*)(vp + 16);
;         const bf16x8 vf = __builtin_shufflevector(lo, hi, 0, 1, 2, 3, 4, 5, 6, 7);
;         O[d] = MFMA(vf, pf.v, O[d]);
;       }
;     }
;   float rs = rs2.x + rs2.y;
;   rs += __shfl_xor(rs, 32);
;   l += rs;
;     ...
;     if (t + NST - 1 < ntile) {
;       const int sn = (stage == 0) ? NST - 1 : stage - 1;
;       FA_ISSUE(t + NST - 1, sn)
;     }
.Lfast_sel1:
	v_mul_f32_e32 v110, 0xbe38aa3b, v110
	v_cndmask_b32_e64 v110, v208, v110, s[10:11]
	v_pk_fma_f32 v[120:121], v[82:83], s[96:97], v[110:111] op_sel_hi:[1,0,0]
	v_exp_f32_e32 v128, v120
	v_exp_f32_e32 v129, v121
	v_pk_fma_f32 v[82:83], v[84:85], s[96:97], v[110:111] op_sel_hi:[1,0,0]
	v_exp_f32_e32 v152, v82
	v_exp_f32_e32 v153, v83
	v_cvt_pk_bf16_f32 v120, v128, v129
	v_pk_fma_f32 v[82:83], v[86:87], s[96:97], v[110:111] op_sel_hi:[1,0,0]
	v_exp_f32_e32 v154, v82
	v_exp_f32_e32 v155, v83
	v_cvt_pk_bf16_f32 v121, v152, v153
	v_pk_fma_f32 v[82:83], v[88:89], s[96:97], v[110:111] op_sel_hi:[1,0,0]
	v_exp_f32_e32 v88, v82
	v_exp_f32_e32 v89, v83
	v_cvt_pk_bf16_f32 v122, v154, v155
	v_cvt_pk_bf16_f32 v123, v88, v89
	s_waitcnt lgkmcnt(0)
	s_nop 0
	v_mfma_f32_32x32x16_bf16 v[50:65], v[216:219], v[120:123], v[50:65]
	s_waitcnt lgkmcnt(0)
	v_mfma_f32_32x32x16_bf16 v[34:49], v[220:223], v[120:123], v[34:49]
	v_add_f32_e64 v84, v128, 0
	v_add_f32_e64 v85, v129, 0
	v_add_f32_e64 v84, v152, v84
	v_add_f32_e64 v85, v153, v85
	v_add_f32_e64 v84, v154, v84
	v_add_f32_e64 v85, v155, v85
	v_pk_add_f32 v[120:121], v[88:89], v[84:85]
	v_pk_fma_f32 v[84:85], v[90:91], s[96:97], v[110:111] op_sel_hi:[1,0,0]
	v_exp_f32_e32 v122, v84
	v_exp_f32_e32 v123, v85
	v_pk_fma_f32 v[86:87], v[92:93], s[96:97], v[110:111] op_sel_hi:[1,0,0]
	v_exp_f32_e32 v92, v86
	v_exp_f32_e32 v93, v87
	v_cvt_pk_bf16_f32 v84, v122, v123
	v_pk_fma_f32 v[86:87], v[94:95], s[96:97], v[110:111] op_sel_hi:[1,0,0]
	v_exp_f32_e32 v94, v86
	v_exp_f32_e32 v95, v87
	v_cvt_pk_bf16_f32 v85, v92, v93
	v_pk_fma_f32 v[88:89], v[96:97], s[96:97], v[110:111] op_sel_hi:[1,0,0]
	v_exp_f32_e32 v96, v88
	v_exp_f32_e32 v97, v89
	v_cvt_pk_bf16_f32 v86, v94, v95
	v_cvt_pk_bf16_f32 v87, v96, v97
	s_nop 1
	v_mfma_f32_32x32x16_bf16 v[50:65], v[224:227], v[84:87], v[50:65]
	s_waitcnt lgkmcnt(0)
	v_mfma_f32_32x32x16_bf16 v[34:49], v[228:231], v[84:87], v[34:49]
	v_fma_f32 v86, v66, s96, v110
	v_fma_f32 v87, v67, s96, v110
	v_fma_f32 v88, v68, s96, v110
	v_fma_f32 v89, v69, s96, v110
	v_exp_f32_e32 v86, v86
	v_exp_f32_e32 v87, v87
	v_pk_add_f32 v[84:85], v[122:123], v[120:121]
	v_pk_add_f32 v[84:85], v[92:93], v[84:85]
	v_exp_f32_e32 v88, v88
	v_exp_f32_e32 v89, v89
	v_cvt_pk_bf16_f32 v66, v86, v87
	v_pk_add_f32 v[84:85], v[94:95], v[84:85]
	v_pk_add_f32 v[84:85], v[96:97], v[84:85]
	v_pk_fma_f32 v[68:69], v[70:71], s[96:97], v[110:111] op_sel_hi:[1,0,0]
	v_exp_f32_e32 v90, v68
	v_exp_f32_e32 v91, v69
	v_cvt_pk_bf16_f32 v67, v88, v89
	v_pk_fma_f32 v[70:71], v[72:73], s[96:97], v[110:111] op_sel_hi:[1,0,0]
	v_exp_f32_e32 v92, v70
	v_exp_f32_e32 v93, v71
	v_cvt_pk_bf16_f32 v68, v90, v91
	v_cvt_pk_bf16_f32 v69, v92, v93
	s_waitcnt lgkmcnt(0)
	s_nop 0
	v_mfma_f32_32x32x16_bf16 v[50:65], v[232:235], v[66:69], v[50:65]
	s_waitcnt lgkmcnt(0)
	v_mfma_f32_32x32x16_bf16 v[34:49], v[236:239], v[66:69], v[34:49]
	v_add_f32_e64 v66, v86, v84
	v_add_f32_e64 v67, v87, v85
	v_add_f32_e64 v66, v88, v66
	v_add_f32_e64 v67, v89, v67
	v_add_f32_e64 v66, v90, v66
	v_add_f32_e64 v67, v91, v67
	v_pk_add_f32 v[84:85], v[92:93], v[66:67]
	v_pk_fma_f32 v[66:67], v[74:75], s[96:97], v[110:111] op_sel_hi:[1,0,0]
	v_exp_f32_e32 v74, v66
	v_exp_f32_e32 v75, v67
	v_pk_fma_f32 v[68:69], v[76:77], s[96:97], v[110:111] op_sel_hi:[1,0,0]
	v_exp_f32_e32 v76, v68
	v_exp_f32_e32 v77, v69
	v_cvt_pk_bf16_f32 v66, v74, v75
	v_pk_fma_f32 v[68:69], v[78:79], s[96:97], v[110:111] op_sel_hi:[1,0,0]
	v_exp_f32_e32 v78, v68
	v_exp_f32_e32 v79, v69
	v_cvt_pk_bf16_f32 v67, v76, v77
	v_pk_fma_f32 v[70:71], v[80:81], s[96:97], v[110:111] op_sel_hi:[1,0,0]
	v_exp_f32_e32 v80, v70
	v_exp_f32_e32 v81, v71
	v_cvt_pk_bf16_f32 v68, v78, v79
	v_cvt_pk_bf16_f32 v69, v80, v81
	s_waitcnt lgkmcnt(0)
	s_nop 0
	v_mfma_f32_32x32x16_bf16 v[50:65], v[240:243], v[66:69], v[50:65]
	s_waitcnt lgkmcnt(0)
	v_mfma_f32_32x32x16_bf16 v[34:49], v[244:247], v[66:69], v[34:49]
	v_add_f32_e64 v66, v74, v84
	v_add_f32_e64 v67, v75, v85
	v_add_f32_e64 v66, v76, v66
	v_add_f32_e64 v67, v77, v67
	v_add_f32_e64 v66, v78, v66
	v_add_f32_e64 v67, v79, v67
	v_pk_add_f32 v[66:67], v[80:81], v[66:67]
	v_add_f32_e32 v66, v66, v67
	ds_bpermute_b32 v67, v165, v66
	s_add_i32 s99, s0, 3
	s_cmp_gt_u32 s99, s46
	s_cbranch_scc1 .Ldma_f_sel1
	v_readfirstlane_b32 s99, v111
	s_add_i32 m0, s99, s98
	v_readfirstlane_b32 s99, v113
	global_load_lds_dwordx4 v[106:107], off
	s_add_i32 m0, s99, s98
	s_nop 0
	global_load_lds_dwordx4 v[104:105], off

;     ...
;   float mx = fmaxf(S[0][0], S[0][1]);
; #pragma unroll
;   for (int ks = 0; ks < 2; ++ks)
; #pragma unroll
;     for (int i = (ks ? 0 : 2); i < 16; i += 2) mx = fmaxf(fmaxf(mx, S[ks][i]), S[ks][i + 1]);
;   mx = fmaxf(mx, __shfl_xor(mx, 32));
;   if (MODE == 2) mx = selbit ? mx : -1e30f;
;   const float mn = fmaxf(m, mx);
;   if (__any((mn - m) * c2 > 8.f)) {
;     const float alpha = __builtin_amdgcn_exp2f((m - mn) * c2);
;     m = mn;
;     l *= alpha;
; #pragma unroll
;     for (int d = 0; d < DV / 32; ++d) O[d] = O[d] * alpha;
;   }
;   float mc = m * c2;
;   if (MODE == 2) mc = selbit ? mc : 1e30f;
;   const f32x2v c2v = {c2, c2}, mcv = {-mc, -mc};
;   f32x2v rs2 = {0.f, 0.f};
;     ...
;     if (t + NST - 1 < ntile) {
;       const int sn = (stage == 0) ? NST - 1 : stage - 1;
;       FA_ISSUE(t + NST - 1, sn)
;     }
.LBB0_439:
	s_nop 0
	v_max_f32_e32 v110, v83, v83
	v_max_f32_e32 v119, v82, v82
	v_max_f32_e32 v110, v119, v110
	v_max3_f32 v110, v110, v84, v85
	v_max3_f32 v110, v110, v86, v87
	v_max3_f32 v110, v110, v88, v89
	v_max3_f32 v110, v110, v90, v91
	v_max3_f32 v110, v110, v92, v93
	v_max3_f32 v110, v110, v94, v95
	v_max3_f32 v110, v110, v96, v97
	v_max3_f32 v110, v110, v66, v67
	v_max3_f32 v110, v110, v68, v69
	v_max3_f32 v110, v110, v70, v71
	v_max3_f32 v110, v110, v72, v73
	v_max3_f32 v110, v110, v74, v75
	v_max3_f32 v110, v110, v76, v77
	v_max3_f32 v110, v110, v78, v79
	v_max3_f32 v110, v110, v80, v81
	ds_bpermute_b32 v119, v165, v110
	ds_read2_b64 v[216:219], v243 offset0:128 offset1:130
	ds_read2_b64 v[220:223], v247 offset0:192 offset1:194
	ds_read2_b64 v[224:227], v243 offset0:132 offset1:134
	ds_read2_b64 v[228:231], v247 offset0:196 offset1:198
	ds_read2_b64 v[232:235], v243 offset0:136 offset1:138
	ds_read2_b64 v[236:239], v247 offset0:200 offset1:202
	ds_read2_b64 v[240:243], v243 offset0:140 offset1:142
	ds_read2_b64 v[244:247], v247 offset0:204 offset1:206
	s_add_i32 s98, s0, 3
	s_cmp_gt_u32 s98, s46
	s_cbranch_scc1 .Ldma_x_sel1
	s_add_i32 s98, s6, 0xffffb800
	s_cmp_lg_u32 s48, 0
	s_cselect_b32 s98, s98, 0xd800
	v_readfirstlane_b32 s99, v112
	s_add_i32 m0, s99, s98
	s_nop 0
	global_load_lds_dwordx4 v[108:109], off
.Ldma_x_sel1:
	s_waitcnt lgkmcnt(8)
	v_max_f32_e32 v119, v119, v119
	v_max_f32_e32 v110, v110, v119
	v_cndmask_b32_e64 v110, v208, v110, s[10:11]
	v_max_f32_e32 v119, v118, v118
	v_max_f32_e32 v110, v119, v110
	v_sub_f32_e32 v119, v110, v118
	v_mul_f32_e32 v119, 0x3e38aa3b, v119
	v_cmp_lt_f32_e32 vcc, s51, v119
	s_cbranch_vccnz .LBB0_423
	v_mov_b32_e32 v110, v118
	s_branch .LBB0_424

; #define MFMA(a, b, c) __builtin_amdgcn_mfma_f32_32x32x16_bf16((a), (b), (c), 0, 0, 0)
;     ...
;   float mc = m * c2;
;   if (MODE == 2) mc = selbit ? mc : 1e30f;
;   const f32x2v c2v = {c2, c2}, mcv = {-mc, -mc};
;   f32x2v rs2 = {0.f, 0.f};
; #pragma unroll
;   for (int ks = 0; ks < 2; ++ks)
; #pragma unroll
;     for (int st = 0; st < 2; ++st) {
;       union { unsigned u[4]; bf16x8 v; } pf;
; #pragma unroll
;       for (int j = 0; j < 4; ++j) {
;         const int i0 = 8 * st + 2 * j;
;         f32x2v t = {S[ks][i0], S[ks][i0 + 1]};
;         t = __builtin_elementwise_fma(t, c2v, mcv);
;         f32x2v pv;
;         if (variant == 1) { pv = t; } else {
;         pv.x = __builtin_amdgcn_exp2f(t.x);
;         pv.y = __builtin_amdgcn_exp2f(t.y);
;         }
;         if (MODE != 0) {
;           if (need_mask) {
;             pv.x = (S[ks][i0] > -1e29f) ? pv.x : 0.f;
;             pv.y = (S[ks][i0 + 1] > -1e29f) ? pv.y : 0.f;
;           }
;         }
;         rs2 += pv;
;         pf.u[j] = __builtin_bit_cast(unsigned, __builtin_convertvector(pv, hwbf16x2));
;       }
; #pragma unroll
;       for (int d = 0; d < DV / 32; ++d) {
;         const char* vp = base + C::KBYTES + (d * 32 + lr) * C::VSTR + (ks * 32 + 16 * st + 4 * lh) * 2;
;         const s16x4 lo = *(const s16x4*)vp, hi = *(const s16x4*)(vp + 16);
;         const bf16x8 vf = __builtin_shufflevector(lo, hi, 0, 1, 2, 3, 4, 5, 6, 7);
;         O[d] = MFMA(vf, pf.v, O[d]);
;       }
;     }
.LBB0_455:
	s_cmp_eq_u64 s[8:9], 0
	s_cbranch_scc1 .Lfast_win1
	v_mul_f32_e32 v162, 0xbe38aa3b, v162
	v_pk_fma_f32 v[180:181], v[114:115], s[96:97], v[162:163] op_sel_hi:[1,0,0]
	v_cmp_lt_f32_e32 vcc, s33, v114
	v_exp_f32_e32 v179, v180
	v_exp_f32_e32 v180, v181
	v_cndmask_b32_e32 v114, 0, v179, vcc
	v_cmp_lt_f32_e32 vcc, s33, v115
	v_cndmask_b32_e64 v188, v179, v114, s[8:9]
	s_nop 0
	v_cndmask_b32_e32 v115, 0, v180, vcc
	v_cndmask_b32_e64 v189, v180, v115, s[8:9]
	v_pk_fma_f32 v[114:115], v[116:117], s[96:97], v[162:163] op_sel_hi:[1,0,0]
	v_cmp_lt_f32_e32 vcc, s33, v116
	v_exp_f32_e32 v114, v114
	v_exp_f32_e32 v115, v115
	v_cvt_pk_bf16_f32 v180, v188, v189
	v_cndmask_b32_e32 v116, 0, v114, vcc
	v_cmp_lt_f32_e32 vcc, s33, v117
	v_cndmask_b32_e64 v190, v114, v116, s[8:9]
	s_nop 0
	v_cndmask_b32_e32 v117, 0, v115, vcc
	v_cndmask_b32_e64 v191, v115, v117, s[8:9]
	v_pk_fma_f32 v[114:115], v[118:119], s[96:97], v[162:163] op_sel_hi:[1,0,0]
	v_cmp_lt_f32_e32 vcc, s33, v118
	v_exp_f32_e32 v114, v114
	v_exp_f32_e32 v115, v115
	v_cvt_pk_bf16_f32 v181, v190, v191
	v_cndmask_b32_e32 v116, 0, v114, vcc
	v_cmp_lt_f32_e32 vcc, s33, v119
	v_cndmask_b32_e64 v192, v114, v116, s[8:9]
	s_nop 0
	v_cndmask_b32_e32 v117, 0, v115, vcc
	v_cndmask_b32_e64 v193, v115, v117, s[8:9]
	v_pk_fma_f32 v[114:115], v[120:121], s[96:97], v[162:163] op_sel_hi:[1,0,0]
	v_cmp_lt_f32_e32 vcc, s33, v120
	v_exp_f32_e32 v114, v114
	v_exp_f32_e32 v115, v115
	v_cvt_pk_bf16_f32 v182, v192, v193
	v_cndmask_b32_e32 v116, 0, v114, vcc
	v_cmp_lt_f32_e32 vcc, s33, v121
	v_cndmask_b32_e64 v120, v114, v116, s[8:9]
	s_nop 0
	v_cndmask_b32_e32 v117, 0, v115, vcc
	v_cndmask_b32_e64 v121, v115, v117, s[8:9]
	s_nop 0
	s_nop 0
	s_nop 0
	s_nop 0
	v_cvt_pk_bf16_f32 v183, v120, v121
	s_nop 0
	v_cmp_lt_f32_e32 vcc, s33, v122
	s_waitcnt lgkmcnt(0)
	v_mfma_f32_32x32x16_bf16 v[82:97], v[216:219], v[180:183], v[82:97]
	s_nop 0
	s_waitcnt lgkmcnt(0)
	v_mfma_f32_32x32x16_bf16 v[66:81], v[220:223], v[180:183], v[66:81]
	v_add_f32_e64 v116, v188, 0
	v_add_f32_e64 v117, v189, 0
	v_add_f32_e64 v116, v190, v116
	v_add_f32_e64 v117, v191, v117
	v_add_f32_e64 v116, v192, v116
	v_add_f32_e64 v117, v193, v117
	v_pk_add_f32 v[180:181], v[120:121], v[116:117]
	v_pk_fma_f32 v[116:117], v[122:123], s[96:97], v[162:163] op_sel_hi:[1,0,0]
	s_nop 0
	v_exp_f32_e32 v116, v116
	v_exp_f32_e32 v117, v117
	v_cndmask_b32_e32 v118, 0, v116, vcc
	v_cmp_lt_f32_e32 vcc, s33, v123
	v_cndmask_b32_e64 v182, v116, v118, s[8:9]
	s_nop 0
	v_cndmask_b32_e32 v119, 0, v117, vcc
	v_cndmask_b32_e64 v183, v117, v119, s[8:9]
	v_pk_fma_f32 v[118:119], v[124:125], s[96:97], v[162:163] op_sel_hi:[1,0,0]
	v_cmp_lt_f32_e32 vcc, s33, v124
	v_exp_f32_e32 v117, v118
	v_exp_f32_e32 v118, v119
	v_cvt_pk_bf16_f32 v116, v182, v183
	v_cndmask_b32_e32 v119, 0, v117, vcc
	v_cmp_lt_f32_e32 vcc, s33, v125
	v_cndmask_b32_e64 v124, v117, v119, s[8:9]
	s_nop 0
	v_cndmask_b32_e32 v120, 0, v118, vcc
	v_cndmask_b32_e64 v125, v118, v120, s[8:9]
	v_pk_fma_f32 v[118:119], v[126:127], s[96:97], v[162:163] op_sel_hi:[1,0,0]
	v_cmp_lt_f32_e32 vcc, s33, v126
	v_exp_f32_e32 v118, v118
	v_exp_f32_e32 v119, v119
	v_cvt_pk_bf16_f32 v117, v124, v125
	v_cndmask_b32_e32 v120, 0, v118, vcc
	v_cmp_lt_f32_e32 vcc, s33, v127
	v_cndmask_b32_e64 v126, v118, v120, s[8:9]
	s_nop 0
	v_cndmask_b32_e32 v121, 0, v119, vcc
	v_cndmask_b32_e64 v127, v119, v121, s[8:9]
	v_pk_fma_f32 v[120:121], v[128:129], s[96:97], v[162:163] op_sel_hi:[1,0,0]
	v_cmp_lt_f32_e32 vcc, s33, v128
	v_exp_f32_e32 v119, v120
	v_exp_f32_e32 v120, v121
	v_cvt_pk_bf16_f32 v118, v126, v127
	v_cndmask_b32_e32 v121, 0, v119, vcc
	v_cmp_lt_f32_e32 vcc, s33, v129
	v_cndmask_b32_e64 v128, v119, v121, s[8:9]
	s_nop 0
	v_cndmask_b32_e32 v122, 0, v120, vcc
	v_cndmask_b32_e64 v129, v120, v122, s[8:9]
	s_nop 0
	v_cvt_pk_bf16_f32 v119, v128, v129
	v_cmp_lt_f32_e32 vcc, s33, v98
	s_nop 0
	v_mfma_f32_32x32x16_bf16 v[82:97], v[224:227], v[116:119], v[82:97]
	s_waitcnt lgkmcnt(0)
; #define MFMA(a, b, c) __builtin_amdgcn_mfma_f32_32x32x16_bf16((a), (b), (c), 0, 0, 0)
; template <int N> DI void wait_vmcnt() { asm volatile("s_waitcnt vmcnt(%0)" ::"n"(N) : "memory"); }
;     ...
; #pragma unroll
;   for (int ks = 0; ks < 2; ++ks)
; #pragma unroll
;     for (int st = 0; st < 2; ++st) {
;       union { unsigned u[4]; bf16x8 v; } pf;
; #pragma unroll
;       for (int j = 0; j < 4; ++j) {
;         const int i0 = 8 * st + 2 * j;
;         f32x2v t = {S[ks][i0], S[ks][i0 + 1]};
;         t = __builtin_elementwise_fma(t, c2v, mcv);
;         f32x2v pv;
;         if (variant == 1) { pv = t; } else {
;         pv.x = __builtin_amdgcn_exp2f(t.x);
;         pv.y = __builtin_amdgcn_exp2f(t.y);
;         }
;         if (MODE != 0) {
;           if (need_mask) {
;             pv.x = (S[ks][i0] > -1e29f) ? pv.x : 0.f;
;             pv.y = (S[ks][i0 + 1] > -1e29f) ? pv.y : 0.f;
;           }
;         }
;         rs2 += pv;
;         pf.u[j] = __builtin_bit_cast(unsigned, __builtin_convertvector(pv, hwbf16x2));
;       }
; #pragma unroll
;       for (int d = 0; d < DV / 32; ++d) {
;         const char* vp = base + C::KBYTES + (d * 32 + lr) * C::VSTR + (ks * 32 + 16 * st + 4 * lh) * 2;
;         const s16x4 lo = *(const s16x4*)vp, hi = *(const s16x4*)(vp + 16);
;         const bf16x8 vf = __builtin_shufflevector(lo, hi, 0, 1, 2, 3, 4, 5, 6, 7);
;         O[d] = MFMA(vf, pf.v, O[d]);
;       }
;     }
;   float rs = rs2.x + rs2.y;
;   rs += __shfl_xor(rs, 32);
;   l += rs;
;     ...
;   asm volatile("s_waitcnt vmcnt(0)" ::: "memory");
; #pragma unroll
;   for (int t = 0; t < NST - 1; ++t)
;     if (t < ntile) FA_ISSUE(t, t)
;   int stage = 0;
;   for (int t = 0; t < ntile; ++t) {
;     int ahead = ((ntile < t + NST - 1) ? ntile : t + NST - 1) - (t + 1);
;     if (NST == 4 && ahead >= 2) wait_vmcnt<2 * NI>();
;     else if (ahead >= 1) wait_vmcnt<NI>();
;     else wait_vmcnt<0>();
;     raw_barrier();
;     if (t + NST - 1 < ntile) {
;       const int sn = (stage == 0) ? NST - 1 : stage - 1;
;       FA_ISSUE(t + NST - 1, sn)
	v_mfma_f32_32x32x16_bf16 v[66:81], v[228:231], v[116:119], v[66:81]
	v_fma_f32 v118, v98, s96, v162
	v_fma_f32 v119, v99, s96, v162
	v_fma_f32 v120, v100, s96, v162
	v_fma_f32 v121, v101, s96, v162
	v_exp_f32_e32 v118, v118
	v_exp_f32_e32 v119, v119
	v_pk_add_f32 v[116:117], v[182:183], v[180:181]
	v_cndmask_b32_e32 v98, 0, v118, vcc
	v_cmp_lt_f32_e32 vcc, s33, v99
	v_pk_add_f32 v[116:117], v[124:125], v[116:117]
	v_cndmask_b32_e64 v118, v118, v98, s[8:9]
	v_cndmask_b32_e32 v99, 0, v119, vcc
	v_cndmask_b32_e64 v119, v119, v99, s[8:9]
	v_exp_f32_e32 v99, v120
	v_exp_f32_e32 v120, v121
	v_cmp_lt_f32_e32 vcc, s33, v100
	v_cvt_pk_bf16_f32 v98, v118, v119
	v_pk_add_f32 v[116:117], v[126:127], v[116:117]
	v_cndmask_b32_e32 v100, 0, v99, vcc
	v_cmp_lt_f32_e32 vcc, s33, v101
	v_pk_add_f32 v[116:117], v[128:129], v[116:117]
	s_nop 0
	v_cndmask_b32_e32 v101, 0, v120, vcc
	v_cndmask_b32_e64 v121, v120, v101, s[8:9]
	v_cndmask_b32_e64 v120, v99, v100, s[8:9]
	v_pk_fma_f32 v[100:101], v[102:103], s[96:97], v[162:163] op_sel_hi:[1,0,0]
	v_cmp_lt_f32_e32 vcc, s33, v102
	v_exp_f32_e32 v100, v100
	v_exp_f32_e32 v101, v101
	v_cvt_pk_bf16_f32 v99, v120, v121
	v_cndmask_b32_e32 v102, 0, v100, vcc
	v_cmp_lt_f32_e32 vcc, s33, v103
	v_cndmask_b32_e64 v122, v100, v102, s[8:9]
	s_nop 0
	v_cndmask_b32_e32 v103, 0, v101, vcc
	v_cndmask_b32_e64 v123, v101, v103, s[8:9]
	v_pk_fma_f32 v[102:103], v[104:105], s[96:97], v[162:163] op_sel_hi:[1,0,0]
	v_cmp_lt_f32_e32 vcc, s33, v104
	v_exp_f32_e32 v101, v102
	v_exp_f32_e32 v102, v103
	v_cvt_pk_bf16_f32 v100, v122, v123
	v_cndmask_b32_e32 v103, 0, v101, vcc
	v_cmp_lt_f32_e32 vcc, s33, v105
	v_cndmask_b32_e64 v124, v101, v103, s[8:9]
	s_nop 0
	v_cndmask_b32_e32 v104, 0, v102, vcc
	v_cndmask_b32_e64 v125, v102, v104, s[8:9]
	s_nop 0
	v_cvt_pk_bf16_f32 v101, v124, v125
	v_cmp_lt_f32_e32 vcc, s33, v106
	s_waitcnt lgkmcnt(0)
	v_mfma_f32_32x32x16_bf16 v[82:97], v[232:235], v[98:101], v[82:97]
	s_nop 0
	s_waitcnt lgkmcnt(0)
	v_mfma_f32_32x32x16_bf16 v[66:81], v[236:239], v[98:101], v[66:81]
	v_add_f32_e64 v98, v118, v116
	v_add_f32_e64 v99, v119, v117
	v_add_f32_e64 v98, v120, v98
	v_add_f32_e64 v99, v121, v99
	v_add_f32_e64 v98, v122, v98
	v_add_f32_e64 v99, v123, v99
	v_pk_add_f32 v[116:117], v[124:125], v[98:99]
	v_pk_fma_f32 v[98:99], v[106:107], s[96:97], v[162:163] op_sel_hi:[1,0,0]
	s_nop 0
	v_exp_f32_e32 v98, v98
	v_exp_f32_e32 v99, v99
	v_cndmask_b32_e32 v100, 0, v98, vcc
	v_cmp_lt_f32_e32 vcc, s33, v107
	v_cndmask_b32_e64 v106, v98, v100, s[8:9]
	s_nop 0
	v_cndmask_b32_e32 v101, 0, v99, vcc
	v_cndmask_b32_e64 v107, v99, v101, s[8:9]
	v_pk_fma_f32 v[100:101], v[108:109], s[96:97], v[162:163] op_sel_hi:[1,0,0]
	v_cmp_lt_f32_e32 vcc, s33, v108
	v_exp_f32_e32 v99, v100
	v_exp_f32_e32 v100, v101
	v_cvt_pk_bf16_f32 v98, v106, v107
	v_cndmask_b32_e32 v101, 0, v99, vcc
	v_cmp_lt_f32_e32 vcc, s33, v109
	v_cndmask_b32_e64 v108, v99, v101, s[8:9]
	s_nop 0
	v_cndmask_b32_e32 v102, 0, v100, vcc
	v_cndmask_b32_e64 v109, v100, v102, s[8:9]
	v_pk_fma_f32 v[100:101], v[110:111], s[96:97], v[162:163] op_sel_hi:[1,0,0]
	v_cmp_lt_f32_e32 vcc, s33, v110
	v_exp_f32_e32 v100, v100
	v_exp_f32_e32 v101, v101
	v_cvt_pk_bf16_f32 v99, v108, v109
	v_cndmask_b32_e32 v102, 0, v100, vcc
	v_cmp_lt_f32_e32 vcc, s33, v111
	v_cndmask_b32_e64 v110, v100, v102, s[8:9]
	s_nop 0
	v_cndmask_b32_e32 v103, 0, v101, vcc
	v_cndmask_b32_e64 v111, v101, v103, s[8:9]
	v_pk_fma_f32 v[102:103], v[112:113], s[96:97], v[162:163] op_sel_hi:[1,0,0]
	v_cmp_lt_f32_e32 vcc, s33, v112
	v_exp_f32_e32 v101, v102
	v_exp_f32_e32 v102, v103
	v_cvt_pk_bf16_f32 v100, v110, v111
	v_cndmask_b32_e32 v103, 0, v101, vcc
	v_cmp_lt_f32_e32 vcc, s33, v113
	v_cndmask_b32_e64 v112, v101, v103, s[8:9]
	s_nop 0
	v_cndmask_b32_e32 v104, 0, v102, vcc
	v_cndmask_b32_e64 v113, v102, v104, s[8:9]
	s_nop 0
	v_cvt_pk_bf16_f32 v101, v112, v113
	s_waitcnt lgkmcnt(0)
	s_nop 0
	v_mfma_f32_32x32x16_bf16 v[82:97], v[240:243], v[98:101], v[82:97]
	s_nop 0
	s_waitcnt lgkmcnt(0)
	v_mfma_f32_32x32x16_bf16 v[66:81], v[244:247], v[98:101], v[66:81]
	v_add_f32_e64 v98, v106, v116
	v_add_f32_e64 v99, v107, v117
	v_add_f32_e64 v98, v108, v98
	v_add_f32_e64 v99, v109, v99
	v_add_f32_e64 v98, v110, v98
	v_add_f32_e64 v99, v111, v99
	v_pk_add_f32 v[98:99], v[112:113], v[98:99]
	s_nop 0
	v_add_f32_e32 v98, v98, v99
	ds_bpermute_b32 v99, v165, v98
	s_cmp_gt_u32 s19, 5
	s_cbranch_scc1 .Ldma_m_win1
	v_readfirstlane_b32 s99, v169
	s_add_i32 m0, s99, s98
	v_readfirstlane_b32 s99, v171
	global_load_lds_dwordx4 v[158:159], off
	s_add_i32 m0, s99, s98
	s_nop 0
	global_load_lds_dwordx4 v[156:157], off

; #define MFMA(a, b, c) __builtin_amdgcn_mfma_f32_32x32x16_bf16((a), (b), (c), 0, 0, 0)
; template <int N> DI void wait_vmcnt() { asm volatile("s_waitcnt vmcnt(%0)" ::"n"(N) : "memory"); }
;     ...
; #pragma unroll
;   for (int ks = 0; ks < 2; ++ks)
; #pragma unroll
;     for (int st = 0; st < 2; ++st) {
;       union { unsigned u[4]; bf16x8 v; } pf;
; #pragma unroll
;       for (int j = 0; j < 4; ++j) {
;         const int i0 = 8 * st + 2 * j;
;         f32x2v t = {S[ks][i0], S[ks][i0 + 1]};
;         t = __builtin_elementwise_fma(t, c2v, mcv);
;         f32x2v pv;
;         if (variant == 1) { pv = t; } else {
;         pv.x = __builtin_amdgcn_exp2f(t.x);
;         pv.y = __builtin_amdgcn_exp2f(t.y);
;         }
;         if (MODE != 0) {
;           if (need_mask) {
;             pv.x = (S[ks][i0] > -1e29f) ? pv.x : 0.f;
;             pv.y = (S[ks][i0 + 1] > -1e29f) ? pv.y : 0.f;
;           }
;         }
;         rs2 += pv;
;         pf.u[j] = __builtin_bit_cast(unsigned, __builtin_convertvector(pv, hwbf16x2));
;       }
; #pragma unroll
;       for (int d = 0; d < DV / 32; ++d) {
;         const char* vp = base + C::KBYTES + (d * 32 + lr) * C::VSTR + (ks * 32 + 16 * st + 4 * lh) * 2;
;         const s16x4 lo = *(const s16x4*)vp, hi = *(const s16x4*)(vp + 16);
;         const bf16x8 vf = __builtin_shufflevector(lo, hi, 0, 1, 2, 3, 4, 5, 6, 7);
;         O[d] = MFMA(vf, pf.v, O[d]);
;       }
;     }
;   float rs = rs2.x + rs2.y;
;   rs += __shfl_xor(rs, 32);
;   l += rs;
;     ...
;   asm volatile("s_waitcnt vmcnt(0)" ::: "memory");
; #pragma unroll
;   for (int t = 0; t < NST - 1; ++t)
;     if (t < ntile) FA_ISSUE(t, t)
;   int stage = 0;
;   for (int t = 0; t < ntile; ++t) {
;     int ahead = ((ntile < t + NST - 1) ? ntile : t + NST - 1) - (t + 1);
;     if (NST == 4 && ahead >= 2) wait_vmcnt<2 * NI>();
;     else if (ahead >= 1) wait_vmcnt<NI>();
;     else wait_vmcnt<0>();
;     raw_barrier();
;     if (t + NST - 1 < ntile) {
;       const int sn = (stage == 0) ? NST - 1 : stage - 1;
;       FA_ISSUE(t + NST - 1, sn)
.Lfast_win1:
	v_mul_f32_e32 v162, 0xbe38aa3b, v162
	v_pk_fma_f32 v[180:181], v[114:115], s[96:97], v[162:163] op_sel_hi:[1,0,0]
	v_exp_f32_e32 v188, v180
	v_exp_f32_e32 v189, v181
	v_pk_fma_f32 v[114:115], v[116:117], s[96:97], v[162:163] op_sel_hi:[1,0,0]
	v_exp_f32_e32 v190, v114
	v_exp_f32_e32 v191, v115
	v_cvt_pk_bf16_f32 v180, v188, v189
	v_pk_fma_f32 v[114:115], v[118:119], s[96:97], v[162:163] op_sel_hi:[1,0,0]
	v_exp_f32_e32 v192, v114
	v_exp_f32_e32 v193, v115
	v_cvt_pk_bf16_f32 v181, v190, v191
	v_pk_fma_f32 v[114:115], v[120:121], s[96:97], v[162:163] op_sel_hi:[1,0,0]
	v_exp_f32_e32 v120, v114
	v_exp_f32_e32 v121, v115
	v_cvt_pk_bf16_f32 v182, v192, v193
	v_cvt_pk_bf16_f32 v183, v120, v121
	s_waitcnt lgkmcnt(0)
	s_nop 0
	v_mfma_f32_32x32x16_bf16 v[82:97], v[216:219], v[180:183], v[82:97]
	s_waitcnt lgkmcnt(0)
	v_mfma_f32_32x32x16_bf16 v[66:81], v[220:223], v[180:183], v[66:81]
	v_add_f32_e64 v116, v188, 0
	v_add_f32_e64 v117, v189, 0
	v_add_f32_e64 v116, v190, v116
	v_add_f32_e64 v117, v191, v117
	v_add_f32_e64 v116, v192, v116
	v_add_f32_e64 v117, v193, v117
	v_pk_add_f32 v[180:181], v[120:121], v[116:117]
	v_pk_fma_f32 v[116:117], v[122:123], s[96:97], v[162:163] op_sel_hi:[1,0,0]
	v_exp_f32_e32 v182, v116
	v_exp_f32_e32 v183, v117
	v_pk_fma_f32 v[118:119], v[124:125], s[96:97], v[162:163] op_sel_hi:[1,0,0]
	v_exp_f32_e32 v124, v118
	v_exp_f32_e32 v125, v119
	v_cvt_pk_bf16_f32 v116, v182, v183
	v_pk_fma_f32 v[118:119], v[126:127], s[96:97], v[162:163] op_sel_hi:[1,0,0]
	v_exp_f32_e32 v126, v118
	v_exp_f32_e32 v127, v119
	v_cvt_pk_bf16_f32 v117, v124, v125
	v_pk_fma_f32 v[120:121], v[128:129], s[96:97], v[162:163] op_sel_hi:[1,0,0]
	v_exp_f32_e32 v128, v120
	v_exp_f32_e32 v129, v121
	v_cvt_pk_bf16_f32 v118, v126, v127
	v_cvt_pk_bf16_f32 v119, v128, v129
	s_nop 1
	v_mfma_f32_32x32x16_bf16 v[82:97], v[224:227], v[116:119], v[82:97]
	s_waitcnt lgkmcnt(0)
	v_mfma_f32_32x32x16_bf16 v[66:81], v[228:231], v[116:119], v[66:81]
	v_fma_f32 v118, v98, s96, v162
	v_fma_f32 v119, v99, s96, v162
	v_fma_f32 v120, v100, s96, v162
	v_fma_f32 v121, v101, s96, v162
	v_exp_f32_e32 v118, v118
	v_exp_f32_e32 v119, v119
	v_pk_add_f32 v[116:117], v[182:183], v[180:181]
	v_pk_add_f32 v[116:117], v[124:125], v[116:117]
	v_exp_f32_e32 v120, v120
	v_exp_f32_e32 v121, v121
	v_cvt_pk_bf16_f32 v98, v118, v119
	v_pk_add_f32 v[116:117], v[126:127], v[116:117]
	v_pk_add_f32 v[116:117], v[128:129], v[116:117]
	v_pk_fma_f32 v[100:101], v[102:103], s[96:97], v[162:163] op_sel_hi:[1,0,0]
	v_exp_f32_e32 v122, v100
	v_exp_f32_e32 v123, v101
	v_cvt_pk_bf16_f32 v99, v120, v121
	v_pk_fma_f32 v[102:103], v[104:105], s[96:97], v[162:163] op_sel_hi:[1,0,0]
	v_exp_f32_e32 v124, v102
	v_exp_f32_e32 v125, v103
	v_cvt_pk_bf16_f32 v100, v122, v123
	v_cvt_pk_bf16_f32 v101, v124, v125
	s_waitcnt lgkmcnt(0)
	s_nop 0
	v_mfma_f32_32x32x16_bf16 v[82:97], v[232:235], v[98:101], v[82:97]
	s_waitcnt lgkmcnt(0)
	v_mfma_f32_32x32x16_bf16 v[66:81], v[236:239], v[98:101], v[66:81]
	v_add_f32_e64 v98, v118, v116
	v_add_f32_e64 v99, v119, v117
	v_add_f32_e64 v98, v120, v98
	v_add_f32_e64 v99, v121, v99
	v_add_f32_e64 v98, v122, v98
	v_add_f32_e64 v99, v123, v99
	v_pk_add_f32 v[116:117], v[124:125], v[98:99]
	v_pk_fma_f32 v[98:99], v[106:107], s[96:97], v[162:163] op_sel_hi:[1,0,0]
	v_exp_f32_e32 v106, v98
	v_exp_f32_e32 v107, v99
	v_pk_fma_f32 v[100:101], v[108:109], s[96:97], v[162:163] op_sel_hi:[1,0,0]
	v_exp_f32_e32 v108, v100
	v_exp_f32_e32 v109, v101
	v_cvt_pk_bf16_f32 v98, v106, v107
	v_pk_fma_f32 v[100:101], v[110:111], s[96:97], v[162:163] op_sel_hi:[1,0,0]
	v_exp_f32_e32 v110, v100
	v_exp_f32_e32 v111, v101
	v_cvt_pk_bf16_f32 v99, v108, v109
	v_pk_fma_f32 v[102:103], v[112:113], s[96:97], v[162:163] op_sel_hi:[1,0,0]
	v_exp_f32_e32 v112, v102
	v_exp_f32_e32 v113, v103
	v_cvt_pk_bf16_f32 v100, v110, v111
	v_cvt_pk_bf16_f32 v101, v112, v113
	s_waitcnt lgkmcnt(0)
	s_nop 0
	v_mfma_f32_32x32x16_bf16 v[82:97], v[240:243], v[98:101], v[82:97]
	s_waitcnt lgkmcnt(0)
	v_mfma_f32_32x32x16_bf16 v[66:81], v[244:247], v[98:101], v[66:81]
	v_add_f32_e64 v98, v106, v116
	v_add_f32_e64 v99, v107, v117
	v_add_f32_e64 v98, v108, v98
	v_add_f32_e64 v99, v109, v99
	v_add_f32_e64 v98, v110, v98
	v_add_f32_e64 v99, v111, v99
	v_pk_add_f32 v[98:99], v[112:113], v[98:99]
	v_add_f32_e32 v98, v98, v99
	ds_bpermute_b32 v99, v165, v98
	s_cmp_gt_u32 s19, 5
	s_cbranch_scc1 .Ldma_f_win1
	v_readfirstlane_b32 s99, v169
	s_add_i32 m0, s99, s98
	v_readfirstlane_b32 s99, v171
	global_load_lds_dwordx4 v[158:159], off
	s_add_i32 m0, s99, s98
	s_nop 0
	global_load_lds_dwordx4 v[156:157], off

; template <int N> DI void wait_vmcnt() { asm volatile("s_waitcnt vmcnt(%0)" ::"n"(N) : "memory"); }
;     ...
;   float mx = fmaxf(S[0][0], S[0][1]);
; #pragma unroll
;   for (int ks = 0; ks < 2; ++ks)
; #pragma unroll
;     for (int i = (ks ? 0 : 2); i < 16; i += 2) mx = fmaxf(fmaxf(mx, S[ks][i]), S[ks][i + 1]);
;   mx = fmaxf(mx, __shfl_xor(mx, 32));
;   if (MODE == 2) mx = selbit ? mx : -1e30f;
;   const float mn = fmaxf(m, mx);
;   if (__any((mn - m) * c2 > 8.f)) {
;     const float alpha = __builtin_amdgcn_exp2f((m - mn) * c2);
;     m = mn;
;     l *= alpha;
; #pragma unroll
;     for (int d = 0; d < DV / 32; ++d) O[d] = O[d] * alpha;
;   }
;     ...
;   asm volatile("s_waitcnt vmcnt(0)" ::: "memory");
; #pragma unroll
;   for (int t = 0; t < NST - 1; ++t)
;     if (t < ntile) FA_ISSUE(t, t)
;   int stage = 0;
;   for (int t = 0; t < ntile; ++t) {
;     int ahead = ((ntile < t + NST - 1) ? ntile : t + NST - 1) - (t + 1);
;     if (NST == 4 && ahead >= 2) wait_vmcnt<2 * NI>();
;     else if (ahead >= 1) wait_vmcnt<NI>();
;     else wait_vmcnt<0>();
;     raw_barrier();
;     if (t + NST - 1 < ntile) {
;       const int sn = (stage == 0) ? NST - 1 : stage - 1;
;       FA_ISSUE(t + NST - 1, sn)
.LBB0_470:
	s_nop 0
	v_max_f32_e32 v162, v115, v115
	v_max_f32_e32 v179, v114, v114
	v_max_f32_e32 v162, v179, v162
	v_max3_f32 v162, v162, v116, v117
	v_max3_f32 v162, v162, v118, v119
	v_max3_f32 v162, v162, v120, v121
	v_max3_f32 v162, v162, v122, v123
	v_max3_f32 v162, v162, v124, v125
	v_max3_f32 v162, v162, v126, v127
	v_max3_f32 v162, v162, v128, v129
	v_max3_f32 v162, v162, v98, v99
	v_max3_f32 v162, v162, v100, v101
	v_max3_f32 v162, v162, v102, v103
	v_max3_f32 v162, v162, v104, v105
	v_max3_f32 v162, v162, v106, v107
	v_max3_f32 v162, v162, v108, v109
	v_max3_f32 v162, v162, v110, v111
	v_max3_f32 v162, v162, v112, v113
	ds_bpermute_b32 v179, v165, v162
	ds_read2_b64 v[216:219], v243 offset0:128 offset1:130
	ds_read2_b64 v[220:223], v247 offset0:192 offset1:194
	ds_read2_b64 v[224:227], v243 offset0:132 offset1:134
	ds_read2_b64 v[228:231], v247 offset0:196 offset1:198
	ds_read2_b64 v[232:235], v243 offset0:136 offset1:138
	ds_read2_b64 v[236:239], v247 offset0:200 offset1:202
	ds_read2_b64 v[240:243], v243 offset0:140 offset1:142
	ds_read2_b64 v[244:247], v247 offset0:204 offset1:206
	s_cmp_gt_u32 s19, 5
	s_cbranch_scc1 .Ldma_x_win1
	s_add_i32 s98, s0, 0xffffb800
	s_cmp_lg_u32 s21, 0
	s_cselect_b32 s98, s98, 0xd800
	v_readfirstlane_b32 s99, v170
	s_add_i32 m0, s99, s98
	s_nop 0
	global_load_lds_dwordx4 v[160:161], off
.Ldma_x_win1:
	s_waitcnt lgkmcnt(8)
	v_max3_f32 v162, v178, v162, v179
	v_sub_f32_e32 v179, v162, v178
	v_mul_f32_e32 v179, 0x3e38aa3b, v179
	v_cmp_lt_f32_e32 vcc, s51, v179
	s_cbranch_vccnz .LBB0_454
	v_mov_b32_e32 v162, v178
	s_branch .LBB0_455

;     ...
;   float mx = fmaxf(S[0][0], S[0][1]);
; #pragma unroll
;   for (int ks = 0; ks < 2; ++ks)
; #pragma unroll
;     for (int i = (ks ? 0 : 2); i < 16; i += 2) mx = fmaxf(fmaxf(mx, S[ks][i]), S[ks][i + 1]);
;   mx = fmaxf(mx, __shfl_xor(mx, 32));
;   if (MODE == 2) mx = selbit ? mx : -1e30f;
;   const float mn = fmaxf(m, mx);
;   if (__any((mn - m) * c2 > 8.f)) {
;     const float alpha = __builtin_amdgcn_exp2f((m - mn) * c2);
;     m = mn;
;     l *= alpha;
; #pragma unroll
;     for (int d = 0; d < DV / 32; ++d) O[d] = O[d] * alpha;
;   }
;   float mc = m * c2;
;   if (MODE == 2) mc = selbit ? mc : 1e30f;
;   const f32x2v c2v = {c2, c2}, mcv = {-mc, -mc};
;   f32x2v rs2 = {0.f, 0.f};
; #pragma unroll
;   for (int ks = 0; ks < 2; ++ks)
; #pragma unroll
;     for (int st = 0; st < 2; ++st) {
;       union { unsigned u[4]; bf16x8 v; } pf;
; #pragma unroll
;       for (int j = 0; j < 4; ++j) {
;         const int i0 = 8 * st + 2 * j;
;         f32x2v t = {S[ks][i0], S[ks][i0 + 1]};
;         t = __builtin_elementwise_fma(t, c2v, mcv);
;         f32x2v pv;
;         if (variant == 1) { pv = t; } else {
;         pv.x = __builtin_amdgcn_exp2f(t.x);
;         pv.y = __builtin_amdgcn_exp2f(t.y);
;         }
;         if (MODE != 0) {
;           if (need_mask) {
;             pv.x = (S[ks][i0] > -1e29f) ? pv.x : 0.f;
;             pv.y = (S[ks][i0 + 1] > -1e29f) ? pv.y : 0.f;
;           }
;         }
;         rs2 += pv;
;         pf.u[j] = __builtin_bit_cast(unsigned, __builtin_convertvector(pv, hwbf16x2));
;       }
; #pragma unroll
;       for (int d = 0; d < DV / 32; ++d) {
;         const char* vp = base + C::KBYTES + (d * 32 + lr) * C::VSTR + (ks * 32 + 16 * st + 4 * lh) * 2;
;         const s16x4 lo = *(const s16x4*)vp, hi = *(const s16x4*)(vp + 16);
;         const bf16x8 vf = __builtin_shufflevector(lo, hi, 0, 1, 2, 3, 4, 5, 6, 7);
;         O[d] = MFMA(vf, pf.v, O[d]);
;     ...
;   asm volatile("s_waitcnt vmcnt(0)" ::: "memory");
; #pragma unroll
;   for (int t = 0; t < NST - 1; ++t)
;     if (t < ntile) FA_ISSUE(t, t)
;   int stage = 0;
;   for (int t = 0; t < ntile; ++t) {
;     int ahead = ((ntile < t + NST - 1) ? ntile : t + NST - 1) - (t + 1);
;     if (NST == 4 && ahead >= 2) wait_vmcnt<2 * NI>();
;     else if (ahead >= 1) wait_vmcnt<NI>();
;     else wait_vmcnt<0>();
;     raw_barrier();
;     if (t + NST - 1 < ntile) {
.LBB0_485:
	s_or_b64 exec, exec, s[12:13]
	v_max_f32_e32 v104, v51, v51
	v_max_f32_e32 v117, v50, v50
	v_max_f32_e32 v104, v117, v104
	v_max3_f32 v104, v104, v52, v53
	v_max3_f32 v104, v104, v54, v55
	v_max3_f32 v104, v104, v56, v57
	v_max3_f32 v104, v104, v58, v59
	v_max3_f32 v104, v104, v60, v61
	v_max3_f32 v104, v104, v62, v63
	v_max3_f32 v104, v104, v64, v65
	v_max3_f32 v104, v104, v34, v35
	v_max3_f32 v104, v104, v36, v37
	v_max3_f32 v104, v104, v38, v39
	v_max3_f32 v104, v104, v40, v41
	v_max3_f32 v104, v104, v42, v43
	v_max3_f32 v104, v104, v44, v45
	v_max3_f32 v104, v104, v46, v47
	v_max3_f32 v104, v104, v48, v49
	ds_bpermute_b32 v117, v165, v104
	ds_read2_b64 v[216:219], v131 offset0:128 offset1:130
	ds_read2_b64 v[220:223], v130 offset0:192 offset1:194
	ds_read2_b64 v[224:227], v131 offset0:132 offset1:134
	ds_read2_b64 v[228:231], v130 offset0:196 offset1:198
	ds_read2_b64 v[232:235], v131 offset0:136 offset1:138
	ds_read2_b64 v[236:239], v130 offset0:200 offset1:202
	ds_read2_b64 v[240:243], v131 offset0:140 offset1:142
	ds_read2_b64 v[244:247], v130 offset0:204 offset1:206
	s_cmp_ge_u32 s17, s18
	s_cbranch_scc1 .Ldma_x_mla2
	s_add_i32 s98, s6, 0xffffa800
	s_cmp_lg_u32 s44, 0
	s_cselect_b32 s98, s98, 0x10800
	v_readfirstlane_b32 s99, v107
	s_add_i32 m0, s99, s98
	s_nop 0
	global_load_lds_dwordx4 v[102:103], off
.Ldma_x_mla2:
	s_waitcnt lgkmcnt(8)
	v_max3_f32 v104, v116, v104, v117
	v_sub_f32_e32 v117, v104, v116
	v_mul_f32_e32 v117, 0x3e16c740, v117
	v_cmp_lt_f32_e32 vcc, s51, v117
	s_cbranch_vccz .LBB0_502
	v_sub_f32_e32 v116, v116, v104
	v_mul_f32_e32 v116, 0x3e16c740, v116
	v_exp_f32_e32 v116, v116
	s_nop 0
	v_mul_f32_e32 v109, v109, v116
	v_pk_mul_f32 v[16:17], v[16:17], v[116:117] op_sel_hi:[1,0]
	v_pk_mul_f32 v[14:15], v[14:15], v[116:117] op_sel_hi:[1,0]
	v_pk_mul_f32 v[12:13], v[12:13], v[116:117] op_sel_hi:[1,0]
	v_pk_mul_f32 v[10:11], v[10:11], v[116:117] op_sel_hi:[1,0]
	v_pk_mul_f32 v[8:9], v[8:9], v[116:117] op_sel_hi:[1,0]
	v_pk_mul_f32 v[6:7], v[6:7], v[116:117] op_sel_hi:[1,0]
	v_pk_mul_f32 v[4:5], v[4:5], v[116:117] op_sel_hi:[1,0]
	v_pk_mul_f32 v[2:3], v[2:3], v[116:117] op_sel_hi:[1,0]
	v_pk_mul_f32 v[32:33], v[32:33], v[116:117] op_sel_hi:[1,0]
	v_pk_mul_f32 v[30:31], v[30:31], v[116:117] op_sel_hi:[1,0]
	v_pk_mul_f32 v[28:29], v[28:29], v[116:117] op_sel_hi:[1,0]
	v_pk_mul_f32 v[26:27], v[26:27], v[116:117] op_sel_hi:[1,0]
	v_pk_mul_f32 v[24:25], v[24:25], v[116:117] op_sel_hi:[1,0]
	v_pk_mul_f32 v[22:23], v[22:23], v[116:117] op_sel_hi:[1,0]
	v_pk_mul_f32 v[20:21], v[20:21], v[116:117] op_sel_hi:[1,0]
	v_pk_mul_f32 v[18:19], v[18:19], v[116:117] op_sel_hi:[1,0]
	v_mov_b32_e32 v116, v104
.LBB0_487:
	s_cmp_eq_u64 s[8:9], 0
	s_cbranch_scc1 .Lfast_mla2
	v_mul_f32_e32 v104, 0xbe16c740, v104
	s_mov_b32 s12, 0x3e16c740
	v_pk_fma_f32 v[118:119], v[50:51], s[12:13], v[104:105] op_sel_hi:[1,0,0]
	v_cmp_lt_f32_e32 vcc, s33, v50
	v_exp_f32_e32 v117, v118
	v_exp_f32_e32 v118, v119
	v_cndmask_b32_e32 v50, 0, v117, vcc
	v_cmp_lt_f32_e32 vcc, s33, v51
	v_cndmask_b32_e64 v126, v117, v50, s[8:9]
	s_nop 0
	v_cndmask_b32_e32 v51, 0, v118, vcc
	v_cndmask_b32_e64 v127, v118, v51, s[8:9]
	v_pk_fma_f32 v[50:51], v[52:53], s[12:13], v[104:105] op_sel_hi:[1,0,0]
	v_cmp_lt_f32_e32 vcc, s33, v52
	v_exp_f32_e32 v50, v50
	v_exp_f32_e32 v51, v51
	v_cvt_pk_bf16_f32 v118, v126, v127
	v_cndmask_b32_e32 v52, 0, v50, vcc
	v_cmp_lt_f32_e32 vcc, s33, v53
	v_cndmask_b32_e64 v128, v50, v52, s[8:9]
	s_nop 0
	v_cndmask_b32_e32 v53, 0, v51, vcc
	v_cndmask_b32_e64 v129, v51, v53, s[8:9]
	v_pk_fma_f32 v[50:51], v[54:55], s[12:13], v[104:105] op_sel_hi:[1,0,0]
	v_cmp_lt_f32_e32 vcc, s33, v54
	v_exp_f32_e32 v50, v50
	v_exp_f32_e32 v51, v51
	v_cvt_pk_bf16_f32 v119, v128, v129
	v_cndmask_b32_e32 v52, 0, v50, vcc
	v_cmp_lt_f32_e32 vcc, s33, v55
	v_cndmask_b32_e64 v130, v50, v52, s[8:9]
	s_nop 0
	v_cndmask_b32_e32 v53, 0, v51, vcc
	v_cndmask_b32_e64 v131, v51, v53, s[8:9]
	v_pk_fma_f32 v[50:51], v[56:57], s[12:13], v[104:105] op_sel_hi:[1,0,0]
	v_cmp_lt_f32_e32 vcc, s33, v56
	v_exp_f32_e32 v50, v50
	v_exp_f32_e32 v51, v51
	v_cvt_pk_bf16_f32 v120, v130, v131
	v_cndmask_b32_e32 v52, 0, v50, vcc
	v_cmp_lt_f32_e32 vcc, s33, v57
	v_cndmask_b32_e64 v56, v50, v52, s[8:9]
	s_nop 0
	v_cndmask_b32_e32 v53, 0, v51, vcc
	v_cndmask_b32_e64 v57, v51, v53, s[8:9]
	v_cvt_pk_bf16_f32 v121, v56, v57
	v_cmp_lt_f32_e32 vcc, s33, v58
	s_waitcnt lgkmcnt(0)
	v_mfma_f32_32x32x16_bf16 v[18:33], v[216:219], v[118:121], v[18:33]
	s_waitcnt lgkmcnt(0)
; #define MFMA(a, b, c) __builtin_amdgcn_mfma_f32_32x32x16_bf16((a), (b), (c), 0, 0, 0)
; template <int N> DI void wait_vmcnt() { asm volatile("s_waitcnt vmcnt(%0)" ::"n"(N) : "memory"); }
;     ...
; #pragma unroll
;   for (int ks = 0; ks < 2; ++ks)
; #pragma unroll
;     for (int st = 0; st < 2; ++st) {
;       union { unsigned u[4]; bf16x8 v; } pf;
; #pragma unroll
;       for (int j = 0; j < 4; ++j) {
;         const int i0 = 8 * st + 2 * j;
;         f32x2v t = {S[ks][i0], S[ks][i0 + 1]};
;         t = __builtin_elementwise_fma(t, c2v, mcv);
;         f32x2v pv;
;         if (variant == 1) { pv = t; } else {
;         pv.x = __builtin_amdgcn_exp2f(t.x);
;         pv.y = __builtin_amdgcn_exp2f(t.y);
;         }
;         if (MODE != 0) {
;           if (need_mask) {
;             pv.x = (S[ks][i0] > -1e29f) ? pv.x : 0.f;
;             pv.y = (S[ks][i0 + 1] > -1e29f) ? pv.y : 0.f;
;           }
;         }
;         rs2 += pv;
;         pf.u[j] = __builtin_bit_cast(unsigned, __builtin_convertvector(pv, hwbf16x2));
;       }
; #pragma unroll
;       for (int d = 0; d < DV / 32; ++d) {
;         const char* vp = base + C::KBYTES + (d * 32 + lr) * C::VSTR + (ks * 32 + 16 * st + 4 * lh) * 2;
;         const s16x4 lo = *(const s16x4*)vp, hi = *(const s16x4*)(vp + 16);
;         const bf16x8 vf = __builtin_shufflevector(lo, hi, 0, 1, 2, 3, 4, 5, 6, 7);
;         O[d] = MFMA(vf, pf.v, O[d]);
;       }
;     }
;   float rs = rs2.x + rs2.y;
;   rs += __shfl_xor(rs, 32);
;   l += rs;
;     ...
;   asm volatile("s_waitcnt vmcnt(0)" ::: "memory");
; #pragma unroll
;   for (int t = 0; t < NST - 1; ++t)
;     if (t < ntile) FA_ISSUE(t, t)
;   int stage = 0;
;   for (int t = 0; t < ntile; ++t) {
;     int ahead = ((ntile < t + NST - 1) ? ntile : t + NST - 1) - (t + 1);
;     if (NST == 4 && ahead >= 2) wait_vmcnt<2 * NI>();
;     else if (ahead >= 1) wait_vmcnt<NI>();
;     else wait_vmcnt<0>();
;     raw_barrier();
;     if (t + NST - 1 < ntile) {
;       const int sn = (stage == 0) ? NST - 1 : stage - 1;
;       FA_ISSUE(t + NST - 1, sn)
	v_mfma_f32_32x32x16_bf16 v[2:17], v[220:223], v[118:121], v[2:17]
	v_add_f32_e64 v52, v126, 0
	v_add_f32_e64 v53, v127, 0
	v_add_f32_e64 v52, v128, v52
	v_add_f32_e64 v53, v129, v53
	v_add_f32_e64 v52, v130, v52
	v_add_f32_e64 v53, v131, v53
	v_pk_add_f32 v[118:119], v[56:57], v[52:53]
	v_pk_fma_f32 v[52:53], v[58:59], s[12:13], v[104:105] op_sel_hi:[1,0,0]
	s_nop 0
	v_exp_f32_e32 v52, v52
	v_exp_f32_e32 v53, v53
	v_cndmask_b32_e32 v54, 0, v52, vcc
	v_cmp_lt_f32_e32 vcc, s33, v59
	v_cndmask_b32_e64 v120, v52, v54, s[8:9]
	s_nop 0
	v_cndmask_b32_e32 v55, 0, v53, vcc
	v_cndmask_b32_e64 v121, v53, v55, s[8:9]
	v_pk_fma_f32 v[54:55], v[60:61], s[12:13], v[104:105] op_sel_hi:[1,0,0]
	v_cmp_lt_f32_e32 vcc, s33, v60
	v_exp_f32_e32 v53, v54
	v_exp_f32_e32 v54, v55
	v_cvt_pk_bf16_f32 v52, v120, v121
	v_cndmask_b32_e32 v55, 0, v53, vcc
	v_cmp_lt_f32_e32 vcc, s33, v61
	v_cndmask_b32_e64 v60, v53, v55, s[8:9]
	s_nop 0
	v_cndmask_b32_e32 v56, 0, v54, vcc
	v_cndmask_b32_e64 v61, v54, v56, s[8:9]
	v_pk_fma_f32 v[54:55], v[62:63], s[12:13], v[104:105] op_sel_hi:[1,0,0]
	v_cmp_lt_f32_e32 vcc, s33, v62
	v_exp_f32_e32 v54, v54
	v_exp_f32_e32 v55, v55
	v_cvt_pk_bf16_f32 v53, v60, v61
	v_cndmask_b32_e32 v56, 0, v54, vcc
	v_cmp_lt_f32_e32 vcc, s33, v63
	v_cndmask_b32_e64 v62, v54, v56, s[8:9]
	s_nop 0
	v_cndmask_b32_e32 v57, 0, v55, vcc
	v_cndmask_b32_e64 v63, v55, v57, s[8:9]
	v_pk_fma_f32 v[56:57], v[64:65], s[12:13], v[104:105] op_sel_hi:[1,0,0]
	v_cmp_lt_f32_e32 vcc, s33, v64
	v_exp_f32_e32 v55, v56
	v_exp_f32_e32 v56, v57
	v_cvt_pk_bf16_f32 v54, v62, v63
	v_cndmask_b32_e32 v57, 0, v55, vcc
	v_cmp_lt_f32_e32 vcc, s33, v65
	v_cndmask_b32_e64 v64, v55, v57, s[8:9]
	s_nop 0
	v_cndmask_b32_e32 v58, 0, v56, vcc
	v_cndmask_b32_e64 v65, v56, v58, s[8:9]
	v_cvt_pk_bf16_f32 v55, v64, v65
	v_cmp_lt_f32_e32 vcc, s33, v34
	s_nop 0
	v_mfma_f32_32x32x16_bf16 v[18:33], v[224:227], v[52:55], v[18:33]
	s_waitcnt lgkmcnt(0)
	v_mfma_f32_32x32x16_bf16 v[2:17], v[228:231], v[52:55], v[2:17]
	v_fma_f32 v54, v34, s12, v104
	v_fma_f32 v55, v35, s12, v104
	v_fma_f32 v56, v36, s12, v104
	v_fma_f32 v57, v37, s12, v104
	v_exp_f32_e32 v54, v54
	v_exp_f32_e32 v55, v55
	v_pk_add_f32 v[52:53], v[120:121], v[118:119]
	v_cndmask_b32_e32 v34, 0, v54, vcc
	v_cmp_lt_f32_e32 vcc, s33, v35
	v_pk_add_f32 v[52:53], v[60:61], v[52:53]
	v_cndmask_b32_e64 v54, v54, v34, s[8:9]
	v_cndmask_b32_e32 v35, 0, v55, vcc
	v_cndmask_b32_e64 v55, v55, v35, s[8:9]
	v_exp_f32_e32 v35, v56
	v_exp_f32_e32 v56, v57
	v_cmp_lt_f32_e32 vcc, s33, v36
	v_cvt_pk_bf16_f32 v34, v54, v55
	v_pk_add_f32 v[52:53], v[62:63], v[52:53]
	v_cndmask_b32_e32 v36, 0, v35, vcc
	v_cmp_lt_f32_e32 vcc, s33, v37
	v_pk_add_f32 v[52:53], v[64:65], v[52:53]
	s_nop 0
	v_cndmask_b32_e32 v37, 0, v56, vcc
	v_cndmask_b32_e64 v57, v56, v37, s[8:9]
	v_cndmask_b32_e64 v56, v35, v36, s[8:9]
	v_pk_fma_f32 v[36:37], v[38:39], s[12:13], v[104:105] op_sel_hi:[1,0,0]
	v_cmp_lt_f32_e32 vcc, s33, v38
	v_exp_f32_e32 v36, v36
	v_exp_f32_e32 v37, v37
	v_cvt_pk_bf16_f32 v35, v56, v57
	v_cndmask_b32_e32 v38, 0, v36, vcc
	v_cmp_lt_f32_e32 vcc, s33, v39
	v_cndmask_b32_e64 v58, v36, v38, s[8:9]
	s_nop 0
	v_cndmask_b32_e32 v39, 0, v37, vcc
	v_cndmask_b32_e64 v59, v37, v39, s[8:9]
	v_pk_fma_f32 v[38:39], v[40:41], s[12:13], v[104:105] op_sel_hi:[1,0,0]
	v_cmp_lt_f32_e32 vcc, s33, v40
	v_exp_f32_e32 v37, v38
	v_exp_f32_e32 v38, v39
	v_cvt_pk_bf16_f32 v36, v58, v59
	v_cndmask_b32_e32 v39, 0, v37, vcc
	v_cmp_lt_f32_e32 vcc, s33, v41
	v_cndmask_b32_e64 v60, v37, v39, s[8:9]
	s_nop 0
	v_cndmask_b32_e32 v40, 0, v38, vcc
	v_cndmask_b32_e64 v61, v38, v40, s[8:9]
	v_cvt_pk_bf16_f32 v37, v60, v61
	v_cmp_lt_f32_e32 vcc, s33, v42
	s_waitcnt lgkmcnt(0)
	v_mfma_f32_32x32x16_bf16 v[18:33], v[232:235], v[34:37], v[18:33]
	s_waitcnt lgkmcnt(0)
	v_mfma_f32_32x32x16_bf16 v[2:17], v[236:239], v[34:37], v[2:17]
	v_add_f32_e64 v34, v54, v52
	v_add_f32_e64 v35, v55, v53
	v_add_f32_e64 v34, v56, v34
	v_add_f32_e64 v35, v57, v35
	v_add_f32_e64 v34, v58, v34
	v_add_f32_e64 v35, v59, v35
	v_pk_add_f32 v[52:53], v[60:61], v[34:35]
	v_pk_fma_f32 v[34:35], v[42:43], s[12:13], v[104:105] op_sel_hi:[1,0,0]
	s_nop 0
	v_exp_f32_e32 v34, v34
	v_exp_f32_e32 v35, v35
	v_cndmask_b32_e32 v36, 0, v34, vcc
	v_cmp_lt_f32_e32 vcc, s33, v43
	v_cndmask_b32_e64 v42, v34, v36, s[8:9]
	s_nop 0
	v_cndmask_b32_e32 v37, 0, v35, vcc
	v_cndmask_b32_e64 v43, v35, v37, s[8:9]
	v_pk_fma_f32 v[36:37], v[44:45], s[12:13], v[104:105] op_sel_hi:[1,0,0]
	v_cmp_lt_f32_e32 vcc, s33, v44
	v_exp_f32_e32 v35, v36
	v_exp_f32_e32 v36, v37
	v_cvt_pk_bf16_f32 v34, v42, v43
	v_cndmask_b32_e32 v37, 0, v35, vcc
	v_cmp_lt_f32_e32 vcc, s33, v45
	v_cndmask_b32_e64 v44, v35, v37, s[8:9]
	s_nop 0
	v_cndmask_b32_e32 v38, 0, v36, vcc
	v_cndmask_b32_e64 v45, v36, v38, s[8:9]
	v_pk_fma_f32 v[36:37], v[46:47], s[12:13], v[104:105] op_sel_hi:[1,0,0]
	v_cmp_lt_f32_e32 vcc, s33, v46
	v_exp_f32_e32 v36, v36
	v_exp_f32_e32 v37, v37
	v_cvt_pk_bf16_f32 v35, v44, v45
	v_cndmask_b32_e32 v38, 0, v36, vcc
	v_cmp_lt_f32_e32 vcc, s33, v47
	v_cndmask_b32_e64 v46, v36, v38, s[8:9]
	s_nop 0
	v_cndmask_b32_e32 v39, 0, v37, vcc
	v_cndmask_b32_e64 v47, v37, v39, s[8:9]
	v_pk_fma_f32 v[38:39], v[48:49], s[12:13], v[104:105] op_sel_hi:[1,0,0]
	v_cmp_lt_f32_e32 vcc, s33, v48
	v_exp_f32_e32 v37, v38
	v_exp_f32_e32 v38, v39
	v_cvt_pk_bf16_f32 v36, v46, v47
	v_cndmask_b32_e32 v39, 0, v37, vcc
	v_cmp_lt_f32_e32 vcc, s33, v49
	v_cndmask_b32_e64 v48, v37, v39, s[8:9]
	s_nop 0
	v_cndmask_b32_e32 v40, 0, v38, vcc
	v_cndmask_b32_e64 v49, v38, v40, s[8:9]
	v_cvt_pk_bf16_f32 v37, v48, v49
	s_waitcnt lgkmcnt(0)
	s_nop 0
	v_mfma_f32_32x32x16_bf16 v[18:33], v[240:243], v[34:37], v[18:33]
	s_waitcnt lgkmcnt(0)
	v_mfma_f32_32x32x16_bf16 v[2:17], v[244:247], v[34:37], v[2:17]
	v_add_f32_e64 v34, v42, v52
	v_add_f32_e64 v35, v43, v53
	v_add_f32_e64 v34, v44, v34
	v_add_f32_e64 v35, v45, v35
	v_add_f32_e64 v34, v46, v34
	v_add_f32_e64 v35, v47, v35
	v_pk_add_f32 v[34:35], v[48:49], v[34:35]
	s_nop 0
	v_add_f32_e32 v34, v34, v35
	ds_bpermute_b32 v35, v165, v34
	s_cmp_ge_u32 s17, s18
	s_cbranch_scc1 .Ldma_m_mla2
	v_readfirstlane_b32 s99, v93
	s_add_i32 m0, s99, s98
	v_readfirstlane_b32 s99, v108
	global_load_lds_dwordx4 v[100:101], off
	s_add_i32 m0, s99, s98
	s_nop 0
	global_load_lds_dwordx4 v[98:99], off

; #define MFMA(a, b, c) __builtin_amdgcn_mfma_f32_32x32x16_bf16((a), (b), (c), 0, 0, 0)
; template <int N> DI void wait_vmcnt() { asm volatile("s_waitcnt vmcnt(%0)" ::"n"(N) : "memory"); }
;     ...
;   float mc = m * c2;
;   if (MODE == 2) mc = selbit ? mc : 1e30f;
;   const f32x2v c2v = {c2, c2}, mcv = {-mc, -mc};
;   f32x2v rs2 = {0.f, 0.f};
; #pragma unroll
;   for (int ks = 0; ks < 2; ++ks)
; #pragma unroll
;     for (int st = 0; st < 2; ++st) {
;       union { unsigned u[4]; bf16x8 v; } pf;
; #pragma unroll
;       for (int j = 0; j < 4; ++j) {
;         const int i0 = 8 * st + 2 * j;
;         f32x2v t = {S[ks][i0], S[ks][i0 + 1]};
;         t = __builtin_elementwise_fma(t, c2v, mcv);
;         f32x2v pv;
;         if (variant == 1) { pv = t; } else {
;         pv.x = __builtin_amdgcn_exp2f(t.x);
;         pv.y = __builtin_amdgcn_exp2f(t.y);
;         }
;         if (MODE != 0) {
;           if (need_mask) {
;             pv.x = (S[ks][i0] > -1e29f) ? pv.x : 0.f;
;             pv.y = (S[ks][i0 + 1] > -1e29f) ? pv.y : 0.f;
;           }
;         }
;         rs2 += pv;
;         pf.u[j] = __builtin_bit_cast(unsigned, __builtin_convertvector(pv, hwbf16x2));
;       }
; #pragma unroll
;       for (int d = 0; d < DV / 32; ++d) {
;         const char* vp = base + C::KBYTES + (d * 32 + lr) * C::VSTR + (ks * 32 + 16 * st + 4 * lh) * 2;
;         const s16x4 lo = *(const s16x4*)vp, hi = *(const s16x4*)(vp + 16);
;         const bf16x8 vf = __builtin_shufflevector(lo, hi, 0, 1, 2, 3, 4, 5, 6, 7);
;         O[d] = MFMA(vf, pf.v, O[d]);
;       }
;     }
;   float rs = rs2.x + rs2.y;
;   rs += __shfl_xor(rs, 32);
;   l += rs;
;     ...
;   asm volatile("s_waitcnt vmcnt(0)" ::: "memory");
; #pragma unroll
;   for (int t = 0; t < NST - 1; ++t)
;     if (t < ntile) FA_ISSUE(t, t)
;   int stage = 0;
;   for (int t = 0; t < ntile; ++t) {
;     int ahead = ((ntile < t + NST - 1) ? ntile : t + NST - 1) - (t + 1);
;     if (NST == 4 && ahead >= 2) wait_vmcnt<2 * NI>();
;     else if (ahead >= 1) wait_vmcnt<NI>();
;     else wait_vmcnt<0>();
;     raw_barrier();
;     if (t + NST - 1 < ntile) {
;       const int sn = (stage == 0) ? NST - 1 : stage - 1;
;       FA_ISSUE(t + NST - 1, sn)
.Lfast_mla2:
	v_mul_f32_e32 v104, 0xbe16c740, v104
	s_mov_b32 s12, 0x3e16c740
	v_pk_fma_f32 v[118:119], v[50:51], s[12:13], v[104:105] op_sel_hi:[1,0,0]
	v_exp_f32_e32 v126, v118
	v_exp_f32_e32 v127, v119
	v_pk_fma_f32 v[50:51], v[52:53], s[12:13], v[104:105] op_sel_hi:[1,0,0]
	v_exp_f32_e32 v128, v50
	v_exp_f32_e32 v129, v51
	v_cvt_pk_bf16_f32 v118, v126, v127
	v_pk_fma_f32 v[50:51], v[54:55], s[12:13], v[104:105] op_sel_hi:[1,0,0]
	v_exp_f32_e32 v130, v50
	v_exp_f32_e32 v131, v51
	v_cvt_pk_bf16_f32 v119, v128, v129
	v_pk_fma_f32 v[50:51], v[56:57], s[12:13], v[104:105] op_sel_hi:[1,0,0]
	v_exp_f32_e32 v56, v50
	v_exp_f32_e32 v57, v51
	v_cvt_pk_bf16_f32 v120, v130, v131
	v_cvt_pk_bf16_f32 v121, v56, v57
	s_waitcnt lgkmcnt(0)
	s_nop 0
	v_mfma_f32_32x32x16_bf16 v[18:33], v[216:219], v[118:121], v[18:33]
	s_waitcnt lgkmcnt(0)
	v_mfma_f32_32x32x16_bf16 v[2:17], v[220:223], v[118:121], v[2:17]
	v_add_f32_e64 v52, v126, 0
	v_add_f32_e64 v53, v127, 0
	v_add_f32_e64 v52, v128, v52
	v_add_f32_e64 v53, v129, v53
	v_add_f32_e64 v52, v130, v52
	v_add_f32_e64 v53, v131, v53
	v_pk_add_f32 v[118:119], v[56:57], v[52:53]
	v_pk_fma_f32 v[52:53], v[58:59], s[12:13], v[104:105] op_sel_hi:[1,0,0]
	v_exp_f32_e32 v120, v52
	v_exp_f32_e32 v121, v53
	v_pk_fma_f32 v[54:55], v[60:61], s[12:13], v[104:105] op_sel_hi:[1,0,0]
	v_exp_f32_e32 v60, v54
	v_exp_f32_e32 v61, v55
	v_cvt_pk_bf16_f32 v52, v120, v121
	v_pk_fma_f32 v[54:55], v[62:63], s[12:13], v[104:105] op_sel_hi:[1,0,0]
	v_exp_f32_e32 v62, v54
	v_exp_f32_e32 v63, v55
	v_cvt_pk_bf16_f32 v53, v60, v61
	v_pk_fma_f32 v[56:57], v[64:65], s[12:13], v[104:105] op_sel_hi:[1,0,0]
	v_exp_f32_e32 v64, v56
	v_exp_f32_e32 v65, v57
	v_cvt_pk_bf16_f32 v54, v62, v63
	v_cvt_pk_bf16_f32 v55, v64, v65
	s_nop 1
	v_mfma_f32_32x32x16_bf16 v[18:33], v[224:227], v[52:55], v[18:33]
	s_waitcnt lgkmcnt(0)
	v_mfma_f32_32x32x16_bf16 v[2:17], v[228:231], v[52:55], v[2:17]
	v_fma_f32 v54, v34, s12, v104
	v_fma_f32 v55, v35, s12, v104
	v_fma_f32 v56, v36, s12, v104
	v_fma_f32 v57, v37, s12, v104
	v_exp_f32_e32 v54, v54
	v_exp_f32_e32 v55, v55
	v_pk_add_f32 v[52:53], v[120:121], v[118:119]
	v_pk_add_f32 v[52:53], v[60:61], v[52:53]
	v_exp_f32_e32 v56, v56
	v_exp_f32_e32 v57, v57
	v_cvt_pk_bf16_f32 v34, v54, v55
	v_pk_add_f32 v[52:53], v[62:63], v[52:53]
	v_pk_add_f32 v[52:53], v[64:65], v[52:53]
	v_pk_fma_f32 v[36:37], v[38:39], s[12:13], v[104:105] op_sel_hi:[1,0,0]
	v_exp_f32_e32 v58, v36
	v_exp_f32_e32 v59, v37
	v_cvt_pk_bf16_f32 v35, v56, v57
	v_pk_fma_f32 v[38:39], v[40:41], s[12:13], v[104:105] op_sel_hi:[1,0,0]
	v_exp_f32_e32 v60, v38
	v_exp_f32_e32 v61, v39
	v_cvt_pk_bf16_f32 v36, v58, v59
	v_cvt_pk_bf16_f32 v37, v60, v61
	s_waitcnt lgkmcnt(0)
	s_nop 0
	v_mfma_f32_32x32x16_bf16 v[18:33], v[232:235], v[34:37], v[18:33]
	s_waitcnt lgkmcnt(0)
	v_mfma_f32_32x32x16_bf16 v[2:17], v[236:239], v[34:37], v[2:17]
	v_add_f32_e64 v34, v54, v52
	v_add_f32_e64 v35, v55, v53
	v_add_f32_e64 v34, v56, v34
	v_add_f32_e64 v35, v57, v35
	v_add_f32_e64 v34, v58, v34
	v_add_f32_e64 v35, v59, v35
	v_pk_add_f32 v[52:53], v[60:61], v[34:35]
	v_pk_fma_f32 v[34:35], v[42:43], s[12:13], v[104:105] op_sel_hi:[1,0,0]
	v_exp_f32_e32 v42, v34
	v_exp_f32_e32 v43, v35
	v_pk_fma_f32 v[36:37], v[44:45], s[12:13], v[104:105] op_sel_hi:[1,0,0]
	v_exp_f32_e32 v44, v36
	v_exp_f32_e32 v45, v37
	v_cvt_pk_bf16_f32 v34, v42, v43
	v_pk_fma_f32 v[36:37], v[46:47], s[12:13], v[104:105] op_sel_hi:[1,0,0]
	v_exp_f32_e32 v46, v36
	v_exp_f32_e32 v47, v37
	v_cvt_pk_bf16_f32 v35, v44, v45
	v_pk_fma_f32 v[38:39], v[48:49], s[12:13], v[104:105] op_sel_hi:[1,0,0]
	v_exp_f32_e32 v48, v38
	v_exp_f32_e32 v49, v39
	v_cvt_pk_bf16_f32 v36, v46, v47
	v_cvt_pk_bf16_f32 v37, v48, v49
	s_waitcnt lgkmcnt(0)
	s_nop 0
	v_mfma_f32_32x32x16_bf16 v[18:33], v[240:243], v[34:37], v[18:33]
	s_waitcnt lgkmcnt(0)
	v_mfma_f32_32x32x16_bf16 v[2:17], v[244:247], v[34:37], v[2:17]
	v_add_f32_e64 v34, v42, v52
	v_add_f32_e64 v35, v43, v53
	v_add_f32_e64 v34, v44, v34
	v_add_f32_e64 v35, v45, v35
	v_add_f32_e64 v34, v46, v34
	v_add_f32_e64 v35, v47, v35
	v_pk_add_f32 v[34:35], v[48:49], v[34:35]
	v_add_f32_e32 v34, v34, v35
	ds_bpermute_b32 v35, v165, v34
	s_cmp_ge_u32 s17, s18
	s_cbranch_scc1 .Ldma_f_mla2
	v_readfirstlane_b32 s99, v93
	s_add_i32 m0, s99, s98
	v_readfirstlane_b32 s99, v108
	global_load_lds_dwordx4 v[100:101], off
	s_add_i32 m0, s99, s98
	s_nop 0
	global_load_lds_dwordx4 v[98:99], off

; #define MFMA(a, b, c) __builtin_amdgcn_mfma_f32_32x32x16_bf16((a), (b), (c), 0, 0, 0)
;     ...
;   float mc = m * c2;
;   if (MODE == 2) mc = selbit ? mc : 1e30f;
;   const f32x2v c2v = {c2, c2}, mcv = {-mc, -mc};
;   f32x2v rs2 = {0.f, 0.f};
; #pragma unroll
;   for (int ks = 0; ks < 2; ++ks)
; #pragma unroll
;     for (int st = 0; st < 2; ++st) {
;       union { unsigned u[4]; bf16x8 v; } pf;
; #pragma unroll
;       for (int j = 0; j < 4; ++j) {
;         const int i0 = 8 * st + 2 * j;
;         f32x2v t = {S[ks][i0], S[ks][i0 + 1]};
;         t = __builtin_elementwise_fma(t, c2v, mcv);
;         f32x2v pv;
;         if (variant == 1) { pv = t; } else {
;         pv.x = __builtin_amdgcn_exp2f(t.x);
;         pv.y = __builtin_amdgcn_exp2f(t.y);
;         }
;         if (MODE != 0) {
;           if (need_mask) {
;             pv.x = (S[ks][i0] > -1e29f) ? pv.x : 0.f;
;             pv.y = (S[ks][i0 + 1] > -1e29f) ? pv.y : 0.f;
;           }
;         }
;         rs2 += pv;
;         pf.u[j] = __builtin_bit_cast(unsigned, __builtin_convertvector(pv, hwbf16x2));
;       }
; #pragma unroll
;       for (int d = 0; d < DV / 32; ++d) {
;         const char* vp = base + C::KBYTES + (d * 32 + lr) * C::VSTR + (ks * 32 + 16 * st + 4 * lh) * 2;
;         const s16x4 lo = *(const s16x4*)vp, hi = *(const s16x4*)(vp + 16);
;         const bf16x8 vf = __builtin_shufflevector(lo, hi, 0, 1, 2, 3, 4, 5, 6, 7);
;         O[d] = MFMA(vf, pf.v, O[d]);
.LBB0_549:
	s_cmp_eq_u64 s[8:9], 0
	s_cbranch_scc1 .Lfast_sel2
	v_mul_f32_e32 v14, 0xbe38aa3b, v14
	v_cndmask_b32_e64 v14, v208, v14, s[10:11]
	v_pk_fma_f32 v[120:121], v[96:97], s[96:97], v[14:15] op_sel_hi:[1,0,0]
	v_cmp_lt_f32_e32 vcc, s33, v96
	v_exp_f32_e32 v119, v120
	v_exp_f32_e32 v120, v121
	v_cndmask_b32_e32 v96, 0, v119, vcc
	v_cmp_lt_f32_e32 vcc, s33, v97
	v_cndmask_b32_e64 v128, v119, v96, s[8:9]
	s_nop 0
	v_cndmask_b32_e32 v97, 0, v120, vcc
	v_cndmask_b32_e64 v129, v120, v97, s[8:9]
	v_pk_fma_f32 v[96:97], v[98:99], s[96:97], v[14:15] op_sel_hi:[1,0,0]
	v_cmp_lt_f32_e32 vcc, s33, v98
	v_exp_f32_e32 v96, v96
	v_exp_f32_e32 v97, v97
	v_cvt_pk_bf16_f32 v120, v128, v129
	v_cndmask_b32_e32 v98, 0, v96, vcc
	v_cmp_lt_f32_e32 vcc, s33, v99
	v_cndmask_b32_e64 v130, v96, v98, s[8:9]
	s_nop 0
	v_cndmask_b32_e32 v99, 0, v97, vcc
	v_cndmask_b32_e64 v131, v97, v99, s[8:9]
	v_pk_fma_f32 v[96:97], v[100:101], s[96:97], v[14:15] op_sel_hi:[1,0,0]
	v_cmp_lt_f32_e32 vcc, s33, v100
	v_exp_f32_e32 v96, v96
	v_exp_f32_e32 v97, v97
	v_cvt_pk_bf16_f32 v121, v130, v131
	v_cndmask_b32_e32 v98, 0, v96, vcc
	v_cmp_lt_f32_e32 vcc, s33, v101
	v_cndmask_b32_e64 v132, v96, v98, s[8:9]
	s_nop 0
	v_cndmask_b32_e32 v99, 0, v97, vcc
	v_cndmask_b32_e64 v133, v97, v99, s[8:9]
	v_pk_fma_f32 v[96:97], v[102:103], s[96:97], v[14:15] op_sel_hi:[1,0,0]
	v_cmp_lt_f32_e32 vcc, s33, v102
	v_exp_f32_e32 v96, v96
	v_exp_f32_e32 v97, v97
	v_cvt_pk_bf16_f32 v122, v132, v133
	v_cndmask_b32_e32 v98, 0, v96, vcc
	v_cmp_lt_f32_e32 vcc, s33, v103
	v_cndmask_b32_e64 v102, v96, v98, s[8:9]
	s_nop 0
	v_cndmask_b32_e32 v99, 0, v97, vcc
	v_cndmask_b32_e64 v103, v97, v99, s[8:9]
	s_nop 0
	s_nop 0
	s_nop 0
	s_nop 0
	v_cvt_pk_bf16_f32 v123, v102, v103
	s_nop 0
	v_cmp_lt_f32_e32 vcc, s33, v104
	s_waitcnt lgkmcnt(0)
	v_mfma_f32_32x32x16_bf16 v[64:79], v[216:219], v[120:123], v[64:79]
	s_nop 0
	s_waitcnt lgkmcnt(0)
	v_mfma_f32_32x32x16_bf16 v[48:63], v[220:223], v[120:123], v[48:63]
	v_add_f32_e64 v98, v128, 0
	v_add_f32_e64 v99, v129, 0
	v_add_f32_e64 v98, v130, v98
	v_add_f32_e64 v99, v131, v99
	v_add_f32_e64 v98, v132, v98
	v_add_f32_e64 v99, v133, v99
	v_pk_add_f32 v[120:121], v[102:103], v[98:99]
	v_pk_fma_f32 v[98:99], v[104:105], s[96:97], v[14:15] op_sel_hi:[1,0,0]
	s_nop 0
	v_exp_f32_e32 v98, v98
	v_exp_f32_e32 v99, v99
	v_cndmask_b32_e32 v100, 0, v98, vcc
	v_cmp_lt_f32_e32 vcc, s33, v105
	v_cndmask_b32_e64 v122, v98, v100, s[8:9]
	s_nop 0
	v_cndmask_b32_e32 v101, 0, v99, vcc
	v_cndmask_b32_e64 v123, v99, v101, s[8:9]
	v_pk_fma_f32 v[100:101], v[106:107], s[96:97], v[14:15] op_sel_hi:[1,0,0]
	v_cmp_lt_f32_e32 vcc, s33, v106
	v_exp_f32_e32 v99, v100
	v_exp_f32_e32 v100, v101
	v_cvt_pk_bf16_f32 v98, v122, v123
	v_cndmask_b32_e32 v101, 0, v99, vcc
	v_cmp_lt_f32_e32 vcc, s33, v107
	v_cndmask_b32_e64 v106, v99, v101, s[8:9]
	s_nop 0
	v_cndmask_b32_e32 v102, 0, v100, vcc
	v_cndmask_b32_e64 v107, v100, v102, s[8:9]
	v_pk_fma_f32 v[100:101], v[108:109], s[96:97], v[14:15] op_sel_hi:[1,0,0]
	v_cmp_lt_f32_e32 vcc, s33, v108
	v_exp_f32_e32 v100, v100
	v_exp_f32_e32 v101, v101
	v_cvt_pk_bf16_f32 v99, v106, v107
	v_cndmask_b32_e32 v102, 0, v100, vcc
	v_cmp_lt_f32_e32 vcc, s33, v109
	v_cndmask_b32_e64 v108, v100, v102, s[8:9]
	s_nop 0
	v_cndmask_b32_e32 v103, 0, v101, vcc
	v_cndmask_b32_e64 v109, v101, v103, s[8:9]
	v_pk_fma_f32 v[102:103], v[110:111], s[96:97], v[14:15] op_sel_hi:[1,0,0]
	v_cmp_lt_f32_e32 vcc, s33, v110
	v_exp_f32_e32 v101, v102
	v_exp_f32_e32 v102, v103
	v_cvt_pk_bf16_f32 v100, v108, v109
	v_cndmask_b32_e32 v103, 0, v101, vcc
	v_cmp_lt_f32_e32 vcc, s33, v111
	v_cndmask_b32_e64 v110, v101, v103, s[8:9]
	s_nop 0
	v_cndmask_b32_e32 v104, 0, v102, vcc
	v_cndmask_b32_e64 v111, v102, v104, s[8:9]
	s_nop 0
	v_cvt_pk_bf16_f32 v101, v110, v111
	v_cmp_lt_f32_e32 vcc, s33, v80
	s_nop 0
	v_mfma_f32_32x32x16_bf16 v[64:79], v[224:227], v[98:101], v[64:79]
	s_waitcnt lgkmcnt(0)
; #define MFMA(a, b, c) __builtin_amdgcn_mfma_f32_32x32x16_bf16((a), (b), (c), 0, 0, 0)
; template <int N> DI void wait_vmcnt() { asm volatile("s_waitcnt vmcnt(%0)" ::"n"(N) : "memory"); }
;     ...
; #pragma unroll
;   for (int ks = 0; ks < 2; ++ks)
; #pragma unroll
;     for (int st = 0; st < 2; ++st) {
;       union { unsigned u[4]; bf16x8 v; } pf;
; #pragma unroll
;       for (int j = 0; j < 4; ++j) {
;         const int i0 = 8 * st + 2 * j;
;         f32x2v t = {S[ks][i0], S[ks][i0 + 1]};
;         t = __builtin_elementwise_fma(t, c2v, mcv);
;         f32x2v pv;
;         if (variant == 1) { pv = t; } else {
;         pv.x = __builtin_amdgcn_exp2f(t.x);
;         pv.y = __builtin_amdgcn_exp2f(t.y);
;         }
;         if (MODE != 0) {
;           if (need_mask) {
;             pv.x = (S[ks][i0] > -1e29f) ? pv.x : 0.f;
;             pv.y = (S[ks][i0 + 1] > -1e29f) ? pv.y : 0.f;
;           }
;         }
;         rs2 += pv;
;         pf.u[j] = __builtin_bit_cast(unsigned, __builtin_convertvector(pv, hwbf16x2));
;       }
; #pragma unroll
;       for (int d = 0; d < DV / 32; ++d) {
;         const char* vp = base + C::KBYTES + (d * 32 + lr) * C::VSTR + (ks * 32 + 16 * st + 4 * lh) * 2;
;         const s16x4 lo = *(const s16x4*)vp, hi = *(const s16x4*)(vp + 16);
;         const bf16x8 vf = __builtin_shufflevector(lo, hi, 0, 1, 2, 3, 4, 5, 6, 7);
;         O[d] = MFMA(vf, pf.v, O[d]);
;       }
;     }
;   float rs = rs2.x + rs2.y;
;   rs += __shfl_xor(rs, 32);
;   l += rs;
;     ...
;   asm volatile("s_waitcnt vmcnt(0)" ::: "memory");
; #pragma unroll
;   for (int t = 0; t < NST - 1; ++t)
;     if (t < ntile) FA_ISSUE(t, t)
;   int stage = 0;
;   for (int t = 0; t < ntile; ++t) {
;     int ahead = ((ntile < t + NST - 1) ? ntile : t + NST - 1) - (t + 1);
;     if (NST == 4 && ahead >= 2) wait_vmcnt<2 * NI>();
;     else if (ahead >= 1) wait_vmcnt<NI>();
;     else wait_vmcnt<0>();
;     raw_barrier();
;     if (t + NST - 1 < ntile) {
;       const int sn = (stage == 0) ? NST - 1 : stage - 1;
;       FA_ISSUE(t + NST - 1, sn)
	v_mfma_f32_32x32x16_bf16 v[48:63], v[228:231], v[98:101], v[48:63]
	v_fma_f32 v100, v80, s96, v14
	v_fma_f32 v101, v81, s96, v14
	v_fma_f32 v102, v82, s96, v14
	v_fma_f32 v103, v83, s96, v14
	v_exp_f32_e32 v100, v100
	v_exp_f32_e32 v101, v101
	v_pk_add_f32 v[98:99], v[122:123], v[120:121]
	v_cndmask_b32_e32 v80, 0, v100, vcc
	v_cmp_lt_f32_e32 vcc, s33, v81
	v_pk_add_f32 v[98:99], v[106:107], v[98:99]
	v_cndmask_b32_e64 v100, v100, v80, s[8:9]
	v_cndmask_b32_e32 v81, 0, v101, vcc
	v_cndmask_b32_e64 v101, v101, v81, s[8:9]
	v_exp_f32_e32 v81, v102
	v_exp_f32_e32 v102, v103
	v_cmp_lt_f32_e32 vcc, s33, v82
	v_cvt_pk_bf16_f32 v80, v100, v101
	v_pk_add_f32 v[98:99], v[108:109], v[98:99]
	v_cndmask_b32_e32 v82, 0, v81, vcc
	v_cmp_lt_f32_e32 vcc, s33, v83
	v_pk_add_f32 v[98:99], v[110:111], v[98:99]
	s_nop 0
	v_cndmask_b32_e32 v83, 0, v102, vcc
	v_cndmask_b32_e64 v103, v102, v83, s[8:9]
	v_cndmask_b32_e64 v102, v81, v82, s[8:9]
	v_pk_fma_f32 v[82:83], v[84:85], s[96:97], v[14:15] op_sel_hi:[1,0,0]
	v_cmp_lt_f32_e32 vcc, s33, v84
	v_exp_f32_e32 v82, v82
	v_exp_f32_e32 v83, v83
	v_cvt_pk_bf16_f32 v81, v102, v103
	v_cndmask_b32_e32 v84, 0, v82, vcc
	v_cmp_lt_f32_e32 vcc, s33, v85
	v_cndmask_b32_e64 v104, v82, v84, s[8:9]
	s_nop 0
	v_cndmask_b32_e32 v85, 0, v83, vcc
	v_cndmask_b32_e64 v105, v83, v85, s[8:9]
	v_pk_fma_f32 v[84:85], v[86:87], s[96:97], v[14:15] op_sel_hi:[1,0,0]
	v_cmp_lt_f32_e32 vcc, s33, v86
	v_exp_f32_e32 v83, v84
	v_exp_f32_e32 v84, v85
	v_cvt_pk_bf16_f32 v82, v104, v105
	v_cndmask_b32_e32 v85, 0, v83, vcc
	v_cmp_lt_f32_e32 vcc, s33, v87
	v_cndmask_b32_e64 v106, v83, v85, s[8:9]
	s_nop 0
	v_cndmask_b32_e32 v86, 0, v84, vcc
	v_cndmask_b32_e64 v107, v84, v86, s[8:9]
	s_nop 0
	v_cvt_pk_bf16_f32 v83, v106, v107
	v_cmp_lt_f32_e32 vcc, s33, v88
	s_waitcnt lgkmcnt(0)
	v_mfma_f32_32x32x16_bf16 v[64:79], v[232:235], v[80:83], v[64:79]
	s_nop 0
	s_waitcnt lgkmcnt(0)
	v_mfma_f32_32x32x16_bf16 v[48:63], v[236:239], v[80:83], v[48:63]
	v_add_f32_e64 v80, v100, v98
	v_add_f32_e64 v81, v101, v99
	v_add_f32_e64 v80, v102, v80
	v_add_f32_e64 v81, v103, v81
	v_add_f32_e64 v80, v104, v80
	v_add_f32_e64 v81, v105, v81
	v_pk_add_f32 v[98:99], v[106:107], v[80:81]
	v_pk_fma_f32 v[80:81], v[88:89], s[96:97], v[14:15] op_sel_hi:[1,0,0]
	s_nop 0
	v_exp_f32_e32 v80, v80
	v_exp_f32_e32 v81, v81
	v_cndmask_b32_e32 v82, 0, v80, vcc
	v_cmp_lt_f32_e32 vcc, s33, v89
	v_cndmask_b32_e64 v88, v80, v82, s[8:9]
	s_nop 0
	v_cndmask_b32_e32 v83, 0, v81, vcc
	v_cndmask_b32_e64 v89, v81, v83, s[8:9]
	v_pk_fma_f32 v[82:83], v[90:91], s[96:97], v[14:15] op_sel_hi:[1,0,0]
	v_cmp_lt_f32_e32 vcc, s33, v90
	v_exp_f32_e32 v81, v82
	v_exp_f32_e32 v82, v83
	v_cvt_pk_bf16_f32 v80, v88, v89
	v_cndmask_b32_e32 v83, 0, v81, vcc
	v_cmp_lt_f32_e32 vcc, s33, v91
	v_cndmask_b32_e64 v90, v81, v83, s[8:9]
	s_nop 0
	v_cndmask_b32_e32 v84, 0, v82, vcc
	v_cndmask_b32_e64 v91, v82, v84, s[8:9]
	v_pk_fma_f32 v[82:83], v[92:93], s[96:97], v[14:15] op_sel_hi:[1,0,0]
	v_cmp_lt_f32_e32 vcc, s33, v92
	v_exp_f32_e32 v82, v82
	v_exp_f32_e32 v83, v83
	v_cvt_pk_bf16_f32 v81, v90, v91
	v_cndmask_b32_e32 v84, 0, v82, vcc
	v_cmp_lt_f32_e32 vcc, s33, v93
	v_cndmask_b32_e64 v92, v82, v84, s[8:9]
	s_nop 0
	v_cndmask_b32_e32 v85, 0, v83, vcc
	v_cndmask_b32_e64 v93, v83, v85, s[8:9]
	v_pk_fma_f32 v[84:85], v[94:95], s[96:97], v[14:15] op_sel_hi:[1,0,0]
	v_cmp_lt_f32_e32 vcc, s33, v94
	v_exp_f32_e32 v14, v84
	v_exp_f32_e32 v83, v85
	v_cvt_pk_bf16_f32 v82, v92, v93
	v_cndmask_b32_e32 v84, 0, v14, vcc
	v_cmp_lt_f32_e32 vcc, s33, v95
	v_cndmask_b32_e64 v94, v14, v84, s[8:9]
	s_nop 0
	v_cndmask_b32_e32 v85, 0, v83, vcc
	v_cndmask_b32_e64 v95, v83, v85, s[8:9]
	s_nop 0
	v_cvt_pk_bf16_f32 v83, v94, v95
	s_waitcnt lgkmcnt(0)
	s_nop 0
	v_mfma_f32_32x32x16_bf16 v[64:79], v[240:243], v[80:83], v[64:79]
	s_nop 0
	s_waitcnt lgkmcnt(0)
	v_mfma_f32_32x32x16_bf16 v[48:63], v[244:247], v[80:83], v[48:63]
	v_add_f32_e64 v80, v88, v98
	v_add_f32_e64 v81, v89, v99
	v_add_f32_e64 v80, v90, v80
	v_add_f32_e64 v81, v91, v81
	v_add_f32_e64 v80, v92, v80
	v_add_f32_e64 v81, v93, v81
	v_pk_add_f32 v[80:81], v[94:95], v[80:81]
	s_nop 0
	v_add_f32_e32 v14, v80, v81
	ds_bpermute_b32 v80, v165, v14
	s_add_i32 s99, s0, 3
	s_cmp_gt_u32 s99, s41
	s_cbranch_scc1 .Ldma_m_sel2
	v_readfirstlane_b32 s99, v15
	s_add_i32 m0, s99, s98
	v_readfirstlane_b32 s99, v113
	global_load_lds_dwordx4 v[10:11], off
	s_add_i32 m0, s99, s98
	s_nop 0
	global_load_lds_dwordx4 v[8:9], off

; #define MFMA(a, b, c) __builtin_amdgcn_mfma_f32_32x32x16_bf16((a), (b), (c), 0, 0, 0)
; template <int N> DI void wait_vmcnt() { asm volatile("s_waitcnt vmcnt(%0)" ::"n"(N) : "memory"); }
;     ...
;   float mc = m * c2;
;   if (MODE == 2) mc = selbit ? mc : 1e30f;
;   const f32x2v c2v = {c2, c2}, mcv = {-mc, -mc};
;   f32x2v rs2 = {0.f, 0.f};
; #pragma unroll
;   for (int ks = 0; ks < 2; ++ks)
; #pragma unroll
;     for (int st = 0; st < 2; ++st) {
;       union { unsigned u[4]; bf16x8 v; } pf;
; #pragma unroll
;       for (int j = 0; j < 4; ++j) {
;         const int i0 = 8 * st + 2 * j;
;         f32x2v t = {S[ks][i0], S[ks][i0 + 1]};
;         t = __builtin_elementwise_fma(t, c2v, mcv);
;         f32x2v pv;
;         if (variant == 1) { pv = t; } else {
;         pv.x = __builtin_amdgcn_exp2f(t.x);
;         pv.y = __builtin_amdgcn_exp2f(t.y);
;         }
;         if (MODE != 0) {
;           if (need_mask) {
;             pv.x = (S[ks][i0] > -1e29f) ? pv.x : 0.f;
;             pv.y = (S[ks][i0 + 1] > -1e29f) ? pv.y : 0.f;
;           }
;         }
;         rs2 += pv;
;         pf.u[j] = __builtin_bit_cast(unsigned, __builtin_convertvector(pv, hwbf16x2));
;       }
; #pragma unroll
;       for (int d = 0; d < DV / 32; ++d) {
;         const char* vp = base + C::KBYTES + (d * 32 + lr) * C::VSTR + (ks * 32 + 16 * st + 4 * lh) * 2;
;         const s16x4 lo = *(const s16x4*)vp, hi = *(const s16x4*)(vp + 16);
;         const bf16x8 vf = __builtin_shufflevector(lo, hi, 0, 1, 2, 3, 4, 5, 6, 7);
;         O[d] = MFMA(vf, pf.v, O[d]);
;       }
;     }
;   float rs = rs2.x + rs2.y;
;   rs += __shfl_xor(rs, 32);
;   l += rs;
;     ...
;   asm volatile("s_waitcnt vmcnt(0)" ::: "memory");
; #pragma unroll
;   for (int t = 0; t < NST - 1; ++t)
;     if (t < ntile) FA_ISSUE(t, t)
;   int stage = 0;
;   for (int t = 0; t < ntile; ++t) {
;     int ahead = ((ntile < t + NST - 1) ? ntile : t + NST - 1) - (t + 1);
;     if (NST == 4 && ahead >= 2) wait_vmcnt<2 * NI>();
;     else if (ahead >= 1) wait_vmcnt<NI>();
;     else wait_vmcnt<0>();
;     raw_barrier();
;     if (t + NST - 1 < ntile) {
;       const int sn = (stage == 0) ? NST - 1 : stage - 1;
;       FA_ISSUE(t + NST - 1, sn)
.Lfast_sel2:
	v_mul_f32_e32 v14, 0xbe38aa3b, v14
	v_cndmask_b32_e64 v14, v208, v14, s[10:11]
	v_pk_fma_f32 v[120:121], v[96:97], s[96:97], v[14:15] op_sel_hi:[1,0,0]
	v_exp_f32_e32 v128, v120
	v_exp_f32_e32 v129, v121
	v_pk_fma_f32 v[96:97], v[98:99], s[96:97], v[14:15] op_sel_hi:[1,0,0]
	v_exp_f32_e32 v130, v96
	v_exp_f32_e32 v131, v97
	v_cvt_pk_bf16_f32 v120, v128, v129
	v_pk_fma_f32 v[96:97], v[100:101], s[96:97], v[14:15] op_sel_hi:[1,0,0]
	v_exp_f32_e32 v132, v96
	v_exp_f32_e32 v133, v97
	v_cvt_pk_bf16_f32 v121, v130, v131
	v_pk_fma_f32 v[96:97], v[102:103], s[96:97], v[14:15] op_sel_hi:[1,0,0]
	v_exp_f32_e32 v102, v96
	v_exp_f32_e32 v103, v97
	v_cvt_pk_bf16_f32 v122, v132, v133
	v_cvt_pk_bf16_f32 v123, v102, v103
	s_waitcnt lgkmcnt(0)
	s_nop 0
	v_mfma_f32_32x32x16_bf16 v[64:79], v[216:219], v[120:123], v[64:79]
	s_waitcnt lgkmcnt(0)
	v_mfma_f32_32x32x16_bf16 v[48:63], v[220:223], v[120:123], v[48:63]
	v_add_f32_e64 v98, v128, 0
	v_add_f32_e64 v99, v129, 0
	v_add_f32_e64 v98, v130, v98
	v_add_f32_e64 v99, v131, v99
	v_add_f32_e64 v98, v132, v98
	v_add_f32_e64 v99, v133, v99
	v_pk_add_f32 v[120:121], v[102:103], v[98:99]
	v_pk_fma_f32 v[98:99], v[104:105], s[96:97], v[14:15] op_sel_hi:[1,0,0]
	v_exp_f32_e32 v122, v98
	v_exp_f32_e32 v123, v99
	v_pk_fma_f32 v[100:101], v[106:107], s[96:97], v[14:15] op_sel_hi:[1,0,0]
	v_exp_f32_e32 v106, v100
	v_exp_f32_e32 v107, v101
	v_cvt_pk_bf16_f32 v98, v122, v123
	v_pk_fma_f32 v[100:101], v[108:109], s[96:97], v[14:15] op_sel_hi:[1,0,0]
	v_exp_f32_e32 v108, v100
	v_exp_f32_e32 v109, v101
	v_cvt_pk_bf16_f32 v99, v106, v107
	v_pk_fma_f32 v[102:103], v[110:111], s[96:97], v[14:15] op_sel_hi:[1,0,0]
	v_exp_f32_e32 v110, v102
	v_exp_f32_e32 v111, v103
	v_cvt_pk_bf16_f32 v100, v108, v109
	v_cvt_pk_bf16_f32 v101, v110, v111
	s_nop 1
	v_mfma_f32_32x32x16_bf16 v[64:79], v[224:227], v[98:101], v[64:79]
	s_waitcnt lgkmcnt(0)
	v_mfma_f32_32x32x16_bf16 v[48:63], v[228:231], v[98:101], v[48:63]
	v_fma_f32 v100, v80, s96, v14
	v_fma_f32 v101, v81, s96, v14
	v_fma_f32 v102, v82, s96, v14
	v_fma_f32 v103, v83, s96, v14
	v_exp_f32_e32 v100, v100
	v_exp_f32_e32 v101, v101
	v_pk_add_f32 v[98:99], v[122:123], v[120:121]
	v_pk_add_f32 v[98:99], v[106:107], v[98:99]
	v_exp_f32_e32 v102, v102
	v_exp_f32_e32 v103, v103
	v_cvt_pk_bf16_f32 v80, v100, v101
	v_pk_add_f32 v[98:99], v[108:109], v[98:99]
	v_pk_add_f32 v[98:99], v[110:111], v[98:99]
	v_pk_fma_f32 v[82:83], v[84:85], s[96:97], v[14:15] op_sel_hi:[1,0,0]
	v_exp_f32_e32 v104, v82
	v_exp_f32_e32 v105, v83
	v_cvt_pk_bf16_f32 v81, v102, v103
	v_pk_fma_f32 v[84:85], v[86:87], s[96:97], v[14:15] op_sel_hi:[1,0,0]
	v_exp_f32_e32 v106, v84
	v_exp_f32_e32 v107, v85
	v_cvt_pk_bf16_f32 v82, v104, v105
	v_cvt_pk_bf16_f32 v83, v106, v107
	s_waitcnt lgkmcnt(0)
	s_nop 0
	v_mfma_f32_32x32x16_bf16 v[64:79], v[232:235], v[80:83], v[64:79]
	s_waitcnt lgkmcnt(0)
	v_mfma_f32_32x32x16_bf16 v[48:63], v[236:239], v[80:83], v[48:63]
	v_add_f32_e64 v80, v100, v98
	v_add_f32_e64 v81, v101, v99
	v_add_f32_e64 v80, v102, v80
	v_add_f32_e64 v81, v103, v81
	v_add_f32_e64 v80, v104, v80
	v_add_f32_e64 v81, v105, v81
	v_pk_add_f32 v[98:99], v[106:107], v[80:81]
	v_pk_fma_f32 v[80:81], v[88:89], s[96:97], v[14:15] op_sel_hi:[1,0,0]
	v_exp_f32_e32 v88, v80
	v_exp_f32_e32 v89, v81
	v_pk_fma_f32 v[82:83], v[90:91], s[96:97], v[14:15] op_sel_hi:[1,0,0]
	v_exp_f32_e32 v90, v82
	v_exp_f32_e32 v91, v83
	v_cvt_pk_bf16_f32 v80, v88, v89
	v_pk_fma_f32 v[82:83], v[92:93], s[96:97], v[14:15] op_sel_hi:[1,0,0]
	v_exp_f32_e32 v92, v82
	v_exp_f32_e32 v93, v83
	v_cvt_pk_bf16_f32 v81, v90, v91
	v_pk_fma_f32 v[84:85], v[94:95], s[96:97], v[14:15] op_sel_hi:[1,0,0]
	v_exp_f32_e32 v94, v84
	v_exp_f32_e32 v95, v85
	v_cvt_pk_bf16_f32 v82, v92, v93
	v_cvt_pk_bf16_f32 v83, v94, v95
	s_waitcnt lgkmcnt(0)
	s_nop 0
	v_mfma_f32_32x32x16_bf16 v[64:79], v[240:243], v[80:83], v[64:79]
	s_waitcnt lgkmcnt(0)
	v_mfma_f32_32x32x16_bf16 v[48:63], v[244:247], v[80:83], v[48:63]
	v_add_f32_e64 v80, v88, v98
	v_add_f32_e64 v81, v89, v99
	v_add_f32_e64 v80, v90, v80
	v_add_f32_e64 v81, v91, v81
	v_add_f32_e64 v80, v92, v80
	v_add_f32_e64 v81, v93, v81
	v_pk_add_f32 v[80:81], v[94:95], v[80:81]
	v_add_f32_e32 v14, v80, v81
	ds_bpermute_b32 v80, v165, v14
	s_add_i32 s99, s0, 3
	s_cmp_gt_u32 s99, s41
	s_cbranch_scc1 .Ldma_f_sel2
	v_readfirstlane_b32 s99, v15
	s_add_i32 m0, s99, s98
	v_readfirstlane_b32 s99, v113
	global_load_lds_dwordx4 v[10:11], off
	s_add_i32 m0, s99, s98
	s_nop 0
	global_load_lds_dwordx4 v[8:9], off

; template <int N> DI void wait_vmcnt() { asm volatile("s_waitcnt vmcnt(%0)" ::"n"(N) : "memory"); }
;     ...
;   float mx = fmaxf(S[0][0], S[0][1]);
; #pragma unroll
;   for (int ks = 0; ks < 2; ++ks)
; #pragma unroll
;     for (int i = (ks ? 0 : 2); i < 16; i += 2) mx = fmaxf(fmaxf(mx, S[ks][i]), S[ks][i + 1]);
;   mx = fmaxf(mx, __shfl_xor(mx, 32));
;   if (MODE == 2) mx = selbit ? mx : -1e30f;
;   const float mn = fmaxf(m, mx);
;   if (__any((mn - m) * c2 > 8.f)) {
;     const float alpha = __builtin_amdgcn_exp2f((m - mn) * c2);
;     m = mn;
;     l *= alpha;
; #pragma unroll
;     for (int d = 0; d < DV / 32; ++d) O[d] = O[d] * alpha;
;   }
;     ...
;   asm volatile("s_waitcnt vmcnt(0)" ::: "memory");
; #pragma unroll
;   for (int t = 0; t < NST - 1; ++t)
;     if (t < ntile) FA_ISSUE(t, t)
;   int stage = 0;
;   for (int t = 0; t < ntile; ++t) {
;     int ahead = ((ntile < t + NST - 1) ? ntile : t + NST - 1) - (t + 1);
;     if (NST == 4 && ahead >= 2) wait_vmcnt<2 * NI>();
;     else if (ahead >= 1) wait_vmcnt<NI>();
;     else wait_vmcnt<0>();
;     raw_barrier();
;     if (t + NST - 1 < ntile) {
;       const int sn = (stage == 0) ? NST - 1 : stage - 1;
;       FA_ISSUE(t + NST - 1, sn)
.LBB0_564:
	s_nop 0
	v_max_f32_e32 v14, v97, v97
	v_max_f32_e32 v119, v96, v96
	v_max_f32_e32 v14, v119, v14
	v_max3_f32 v14, v14, v98, v99
	v_max3_f32 v14, v14, v100, v101
	v_max3_f32 v14, v14, v102, v103
	v_max3_f32 v14, v14, v104, v105
	v_max3_f32 v14, v14, v106, v107
	v_max3_f32 v14, v14, v108, v109
	v_max3_f32 v14, v14, v110, v111
	v_max3_f32 v14, v14, v80, v81
	v_max3_f32 v14, v14, v82, v83
	v_max3_f32 v14, v14, v84, v85
	v_max3_f32 v14, v14, v86, v87
	v_max3_f32 v14, v14, v88, v89
	v_max3_f32 v14, v14, v90, v91
	v_max3_f32 v14, v14, v92, v93
	v_max3_f32 v14, v14, v94, v95
	ds_bpermute_b32 v119, v165, v14
	ds_read2_b64 v[216:219], v243 offset0:128 offset1:130
	ds_read2_b64 v[220:223], v247 offset0:192 offset1:194
	ds_read2_b64 v[224:227], v243 offset0:132 offset1:134
	ds_read2_b64 v[228:231], v247 offset0:196 offset1:198
	ds_read2_b64 v[232:235], v243 offset0:136 offset1:138
	ds_read2_b64 v[236:239], v247 offset0:200 offset1:202
	ds_read2_b64 v[240:243], v243 offset0:140 offset1:142
	ds_read2_b64 v[244:247], v247 offset0:204 offset1:206
	s_add_i32 s98, s0, 3
	s_cmp_gt_u32 s98, s41
	s_cbranch_scc1 .Ldma_x_sel2
	s_add_i32 s98, s6, 0xffffb800
	s_cmp_lg_u32 s45, 0
	s_cselect_b32 s98, s98, 0xd800
	v_readfirstlane_b32 s99, v112
	s_add_i32 m0, s99, s98
	s_nop 0
	global_load_lds_dwordx4 v[12:13], off
.Ldma_x_sel2:
	s_waitcnt lgkmcnt(8)
	v_max_f32_e32 v119, v119, v119
	v_max_f32_e32 v14, v14, v119
	v_cndmask_b32_e64 v14, v208, v14, s[10:11]
	v_max_f32_e32 v119, v118, v118
	v_max_f32_e32 v14, v119, v14
	v_sub_f32_e32 v119, v14, v118
	v_mul_f32_e32 v119, 0x3e38aa3b, v119
	v_cmp_lt_f32_e32 vcc, s51, v119
	s_cbranch_vccnz .LBB0_548
	v_mov_b32_e32 v14, v118
	s_branch .LBB0_549

; #define MFMA(a, b, c) __builtin_amdgcn_mfma_f32_32x32x16_bf16((a), (b), (c), 0, 0, 0)
;     ...
;   float mc = m * c2;
;   if (MODE == 2) mc = selbit ? mc : 1e30f;
;   const f32x2v c2v = {c2, c2}, mcv = {-mc, -mc};
;   f32x2v rs2 = {0.f, 0.f};
; #pragma unroll
;   for (int ks = 0; ks < 2; ++ks)
; #pragma unroll
;     for (int st = 0; st < 2; ++st) {
;       union { unsigned u[4]; bf16x8 v; } pf;
; #pragma unroll
;       for (int j = 0; j < 4; ++j) {
;         const int i0 = 8 * st + 2 * j;
;         f32x2v t = {S[ks][i0], S[ks][i0 + 1]};
;         t = __builtin_elementwise_fma(t, c2v, mcv);
;         f32x2v pv;
;         if (variant == 1) { pv = t; } else {
;         pv.x = __builtin_amdgcn_exp2f(t.x);
;         pv.y = __builtin_amdgcn_exp2f(t.y);
;         }
;         if (MODE != 0) {
;           if (need_mask) {
;             pv.x = (S[ks][i0] > -1e29f) ? pv.x : 0.f;
;             pv.y = (S[ks][i0 + 1] > -1e29f) ? pv.y : 0.f;
;           }
;         }
;         rs2 += pv;
;         pf.u[j] = __builtin_bit_cast(unsigned, __builtin_convertvector(pv, hwbf16x2));
;       }
; #pragma unroll
;       for (int d = 0; d < DV / 32; ++d) {
;         const char* vp = base + C::KBYTES + (d * 32 + lr) * C::VSTR + (ks * 32 + 16 * st + 4 * lh) * 2;
;         const s16x4 lo = *(const s16x4*)vp, hi = *(const s16x4*)(vp + 16);
;         const bf16x8 vf = __builtin_shufflevector(lo, hi, 0, 1, 2, 3, 4, 5, 6, 7);
;         O[d] = MFMA(vf, pf.v, O[d]);
.LBB0_585:
	s_cmp_eq_u64 s[8:9], 0
	s_cbranch_scc1 .Lfast_win2
	v_mul_f32_e32 v12, 0xbe38aa3b, v12
	v_pk_fma_f32 v[176:177], v[128:129], s[96:97], v[12:13] op_sel_hi:[1,0,0]
	v_cmp_lt_f32_e32 vcc, s33, v128
	v_exp_f32_e32 v176, v176
	v_exp_f32_e32 v177, v177
	v_cndmask_b32_e32 v128, 0, v176, vcc
	v_cmp_lt_f32_e32 vcc, s33, v129
	v_cndmask_b32_e64 v184, v176, v128, s[8:9]
	s_nop 0
	v_cndmask_b32_e32 v129, 0, v177, vcc
	v_cndmask_b32_e64 v185, v177, v129, s[8:9]
	v_pk_fma_f32 v[128:129], v[130:131], s[96:97], v[12:13] op_sel_hi:[1,0,0]
	v_cmp_lt_f32_e32 vcc, s33, v130
	v_exp_f32_e32 v128, v128
	v_exp_f32_e32 v129, v129
	v_cvt_pk_bf16_f32 v176, v184, v185
	v_cndmask_b32_e32 v130, 0, v128, vcc
	v_cmp_lt_f32_e32 vcc, s33, v131
	v_cndmask_b32_e64 v186, v128, v130, s[8:9]
	s_nop 0
	v_cndmask_b32_e32 v131, 0, v129, vcc
	v_cndmask_b32_e64 v187, v129, v131, s[8:9]
	v_pk_fma_f32 v[128:129], v[132:133], s[96:97], v[12:13] op_sel_hi:[1,0,0]
	v_cmp_lt_f32_e32 vcc, s33, v132
	v_exp_f32_e32 v128, v128
	v_exp_f32_e32 v129, v129
	v_cvt_pk_bf16_f32 v177, v186, v187
	v_cndmask_b32_e32 v130, 0, v128, vcc
	v_cmp_lt_f32_e32 vcc, s33, v133
	v_cndmask_b32_e64 v188, v128, v130, s[8:9]
	s_nop 0
	v_cndmask_b32_e32 v131, 0, v129, vcc
	v_cndmask_b32_e64 v189, v129, v131, s[8:9]
	v_pk_fma_f32 v[128:129], v[134:135], s[96:97], v[12:13] op_sel_hi:[1,0,0]
	v_cmp_lt_f32_e32 vcc, s33, v134
	v_exp_f32_e32 v128, v128
	v_exp_f32_e32 v129, v129
	v_cvt_pk_bf16_f32 v178, v188, v189
	v_cndmask_b32_e32 v130, 0, v128, vcc
	v_cmp_lt_f32_e32 vcc, s33, v135
	v_cndmask_b32_e64 v134, v128, v130, s[8:9]
	s_nop 0
	v_cndmask_b32_e32 v131, 0, v129, vcc
	v_cndmask_b32_e64 v135, v129, v131, s[8:9]
	s_nop 0
	s_nop 0
	s_nop 0
	s_nop 0
	v_cvt_pk_bf16_f32 v179, v134, v135
	s_nop 0
	v_cmp_lt_f32_e32 vcc, s33, v136
	s_waitcnt lgkmcnt(0)
	v_mfma_f32_32x32x16_bf16 v[96:111], v[216:219], v[176:179], v[96:111]
	s_nop 0
	s_waitcnt lgkmcnt(0)
	v_mfma_f32_32x32x16_bf16 v[80:95], v[220:223], v[176:179], v[80:95]
	v_add_f32_e64 v130, v184, 0
	v_add_f32_e64 v131, v185, 0
	v_add_f32_e64 v130, v186, v130
	v_add_f32_e64 v131, v187, v131
	v_add_f32_e64 v130, v188, v130
	v_add_f32_e64 v131, v189, v131
	v_pk_add_f32 v[176:177], v[134:135], v[130:131]
	v_pk_fma_f32 v[130:131], v[136:137], s[96:97], v[12:13] op_sel_hi:[1,0,0]
	s_nop 0
	v_exp_f32_e32 v130, v130
	v_exp_f32_e32 v131, v131
	v_cndmask_b32_e32 v132, 0, v130, vcc
	v_cmp_lt_f32_e32 vcc, s33, v137
	v_cndmask_b32_e64 v178, v130, v132, s[8:9]
	s_nop 0
	v_cndmask_b32_e32 v133, 0, v131, vcc
	v_cndmask_b32_e64 v179, v131, v133, s[8:9]
	v_pk_fma_f32 v[132:133], v[138:139], s[96:97], v[12:13] op_sel_hi:[1,0,0]
	v_cmp_lt_f32_e32 vcc, s33, v138
	v_exp_f32_e32 v131, v132
	v_exp_f32_e32 v132, v133
	v_cvt_pk_bf16_f32 v130, v178, v179
	v_cndmask_b32_e32 v133, 0, v131, vcc
	v_cmp_lt_f32_e32 vcc, s33, v139
	v_cndmask_b32_e64 v138, v131, v133, s[8:9]
	s_nop 0
	v_cndmask_b32_e32 v134, 0, v132, vcc
	v_cndmask_b32_e64 v139, v132, v134, s[8:9]
	v_pk_fma_f32 v[132:133], v[140:141], s[96:97], v[12:13] op_sel_hi:[1,0,0]
	v_cmp_lt_f32_e32 vcc, s33, v140
	v_exp_f32_e32 v132, v132
	v_exp_f32_e32 v133, v133
	v_cvt_pk_bf16_f32 v131, v138, v139
	v_cndmask_b32_e32 v134, 0, v132, vcc
	v_cmp_lt_f32_e32 vcc, s33, v141
	v_cndmask_b32_e64 v140, v132, v134, s[8:9]
	s_nop 0
	v_cndmask_b32_e32 v135, 0, v133, vcc
	v_cndmask_b32_e64 v141, v133, v135, s[8:9]
	v_pk_fma_f32 v[134:135], v[142:143], s[96:97], v[12:13] op_sel_hi:[1,0,0]
	v_cmp_lt_f32_e32 vcc, s33, v142
	v_exp_f32_e32 v133, v134
	v_exp_f32_e32 v134, v135
	v_cvt_pk_bf16_f32 v132, v140, v141
	v_cndmask_b32_e32 v135, 0, v133, vcc
	v_cmp_lt_f32_e32 vcc, s33, v143
	v_cndmask_b32_e64 v142, v133, v135, s[8:9]
	s_nop 0
	v_cndmask_b32_e32 v136, 0, v134, vcc
	v_cndmask_b32_e64 v143, v134, v136, s[8:9]
	s_nop 0
	v_cvt_pk_bf16_f32 v133, v142, v143
	v_cmp_lt_f32_e32 vcc, s33, v112
	s_nop 0
	v_mfma_f32_32x32x16_bf16 v[96:111], v[224:227], v[130:133], v[96:111]
	s_waitcnt lgkmcnt(0)
; #define MFMA(a, b, c) __builtin_amdgcn_mfma_f32_32x32x16_bf16((a), (b), (c), 0, 0, 0)
; template <int N> DI void wait_vmcnt() { asm volatile("s_waitcnt vmcnt(%0)" ::"n"(N) : "memory"); }
;     ...
; #pragma unroll
;   for (int ks = 0; ks < 2; ++ks)
; #pragma unroll
;     for (int st = 0; st < 2; ++st) {
;       union { unsigned u[4]; bf16x8 v; } pf;
; #pragma unroll
;       for (int j = 0; j < 4; ++j) {
;         const int i0 = 8 * st + 2 * j;
;         f32x2v t = {S[ks][i0], S[ks][i0 + 1]};
;         t = __builtin_elementwise_fma(t, c2v, mcv);
;         f32x2v pv;
;         if (variant == 1) { pv = t; } else {
;         pv.x = __builtin_amdgcn_exp2f(t.x);
;         pv.y = __builtin_amdgcn_exp2f(t.y);
;         }
;         if (MODE != 0) {
;           if (need_mask) {
;             pv.x = (S[ks][i0] > -1e29f) ? pv.x : 0.f;
;             pv.y = (S[ks][i0 + 1] > -1e29f) ? pv.y : 0.f;
;           }
;         }
;         rs2 += pv;
;         pf.u[j] = __builtin_bit_cast(unsigned, __builtin_convertvector(pv, hwbf16x2));
;       }
; #pragma unroll
;       for (int d = 0; d < DV / 32; ++d) {
;         const char* vp = base + C::KBYTES + (d * 32 + lr) * C::VSTR + (ks * 32 + 16 * st + 4 * lh) * 2;
;         const s16x4 lo = *(const s16x4*)vp, hi = *(const s16x4*)(vp + 16);
;         const bf16x8 vf = __builtin_shufflevector(lo, hi, 0, 1, 2, 3, 4, 5, 6, 7);
;         O[d] = MFMA(vf, pf.v, O[d]);
;       }
;     }
;   float rs = rs2.x + rs2.y;
;   rs += __shfl_xor(rs, 32);
;   l += rs;
;     ...
;   asm volatile("s_waitcnt vmcnt(0)" ::: "memory");
; #pragma unroll
;   for (int t = 0; t < NST - 1; ++t)
;     if (t < ntile) FA_ISSUE(t, t)
;   int stage = 0;
;   for (int t = 0; t < ntile; ++t) {
;     int ahead = ((ntile < t + NST - 1) ? ntile : t + NST - 1) - (t + 1);
;     if (NST == 4 && ahead >= 2) wait_vmcnt<2 * NI>();
;     else if (ahead >= 1) wait_vmcnt<NI>();
;     else wait_vmcnt<0>();
;     raw_barrier();
;     if (t + NST - 1 < ntile) {
;       const int sn = (stage == 0) ? NST - 1 : stage - 1;
;       FA_ISSUE(t + NST - 1, sn)
	v_mfma_f32_32x32x16_bf16 v[80:95], v[228:231], v[130:133], v[80:95]
	v_fma_f32 v132, v112, s96, v12
	v_fma_f32 v133, v113, s96, v12
	v_fma_f32 v134, v114, s96, v12
	v_fma_f32 v135, v115, s96, v12
	v_exp_f32_e32 v132, v132
	v_exp_f32_e32 v133, v133
	v_pk_add_f32 v[130:131], v[178:179], v[176:177]
	v_cndmask_b32_e32 v112, 0, v132, vcc
	v_cmp_lt_f32_e32 vcc, s33, v113
	v_pk_add_f32 v[130:131], v[138:139], v[130:131]
	v_cndmask_b32_e64 v132, v132, v112, s[8:9]
	v_cndmask_b32_e32 v113, 0, v133, vcc
	v_cndmask_b32_e64 v133, v133, v113, s[8:9]
	v_exp_f32_e32 v113, v134
	v_exp_f32_e32 v134, v135
	v_cmp_lt_f32_e32 vcc, s33, v114
	v_cvt_pk_bf16_f32 v112, v132, v133
	v_pk_add_f32 v[130:131], v[140:141], v[130:131]
	v_cndmask_b32_e32 v114, 0, v113, vcc
	v_cmp_lt_f32_e32 vcc, s33, v115
	v_pk_add_f32 v[130:131], v[142:143], v[130:131]
	s_nop 0
	v_cndmask_b32_e32 v115, 0, v134, vcc
	v_cndmask_b32_e64 v135, v134, v115, s[8:9]
	v_cndmask_b32_e64 v134, v113, v114, s[8:9]
	v_pk_fma_f32 v[114:115], v[116:117], s[96:97], v[12:13] op_sel_hi:[1,0,0]
	v_cmp_lt_f32_e32 vcc, s33, v116
	v_exp_f32_e32 v114, v114
	v_exp_f32_e32 v115, v115
	v_cvt_pk_bf16_f32 v113, v134, v135
	v_cndmask_b32_e32 v116, 0, v114, vcc
	v_cmp_lt_f32_e32 vcc, s33, v117
	v_cndmask_b32_e64 v136, v114, v116, s[8:9]
	s_nop 0
	v_cndmask_b32_e32 v117, 0, v115, vcc
	v_cndmask_b32_e64 v137, v115, v117, s[8:9]
	v_pk_fma_f32 v[116:117], v[118:119], s[96:97], v[12:13] op_sel_hi:[1,0,0]
	v_cmp_lt_f32_e32 vcc, s33, v118
	v_exp_f32_e32 v115, v116
	v_exp_f32_e32 v116, v117
	v_cvt_pk_bf16_f32 v114, v136, v137
	v_cndmask_b32_e32 v117, 0, v115, vcc
	v_cmp_lt_f32_e32 vcc, s33, v119
	v_cndmask_b32_e64 v138, v115, v117, s[8:9]
	s_nop 0
	v_cndmask_b32_e32 v118, 0, v116, vcc
	v_cndmask_b32_e64 v139, v116, v118, s[8:9]
	s_nop 0
	v_cvt_pk_bf16_f32 v115, v138, v139
	v_cmp_lt_f32_e32 vcc, s33, v120
	s_waitcnt lgkmcnt(0)
	v_mfma_f32_32x32x16_bf16 v[96:111], v[232:235], v[112:115], v[96:111]
	s_nop 0
	s_waitcnt lgkmcnt(0)
	v_mfma_f32_32x32x16_bf16 v[80:95], v[236:239], v[112:115], v[80:95]
	v_add_f32_e64 v112, v132, v130
	v_add_f32_e64 v113, v133, v131
	v_add_f32_e64 v112, v134, v112
	v_add_f32_e64 v113, v135, v113
	v_add_f32_e64 v112, v136, v112
	v_add_f32_e64 v113, v137, v113
	v_pk_add_f32 v[130:131], v[138:139], v[112:113]
	v_pk_fma_f32 v[112:113], v[120:121], s[96:97], v[12:13] op_sel_hi:[1,0,0]
	s_nop 0
	v_exp_f32_e32 v112, v112
	v_exp_f32_e32 v113, v113
	v_cndmask_b32_e32 v114, 0, v112, vcc
	v_cmp_lt_f32_e32 vcc, s33, v121
	v_cndmask_b32_e64 v120, v112, v114, s[8:9]
	s_nop 0
	v_cndmask_b32_e32 v115, 0, v113, vcc
	v_cndmask_b32_e64 v121, v113, v115, s[8:9]
	v_pk_fma_f32 v[114:115], v[122:123], s[96:97], v[12:13] op_sel_hi:[1,0,0]
	v_cmp_lt_f32_e32 vcc, s33, v122
	v_exp_f32_e32 v113, v114
	v_exp_f32_e32 v114, v115
	v_cvt_pk_bf16_f32 v112, v120, v121
	v_cndmask_b32_e32 v115, 0, v113, vcc
	v_cmp_lt_f32_e32 vcc, s33, v123
	v_cndmask_b32_e64 v122, v113, v115, s[8:9]
	s_nop 0
	v_cndmask_b32_e32 v116, 0, v114, vcc
	v_cndmask_b32_e64 v123, v114, v116, s[8:9]
	v_pk_fma_f32 v[114:115], v[124:125], s[96:97], v[12:13] op_sel_hi:[1,0,0]
	v_cmp_lt_f32_e32 vcc, s33, v124
	v_exp_f32_e32 v114, v114
	v_exp_f32_e32 v115, v115
	v_cvt_pk_bf16_f32 v113, v122, v123
	v_cndmask_b32_e32 v116, 0, v114, vcc
	v_cmp_lt_f32_e32 vcc, s33, v125
	v_cndmask_b32_e64 v124, v114, v116, s[8:9]
	s_nop 0
	v_cndmask_b32_e32 v117, 0, v115, vcc
	v_cndmask_b32_e64 v125, v115, v117, s[8:9]
	v_pk_fma_f32 v[116:117], v[126:127], s[96:97], v[12:13] op_sel_hi:[1,0,0]
	v_cmp_lt_f32_e32 vcc, s33, v126
	v_exp_f32_e32 v12, v116
	v_exp_f32_e32 v115, v117
	v_cvt_pk_bf16_f32 v114, v124, v125
	v_cndmask_b32_e32 v116, 0, v12, vcc
	v_cmp_lt_f32_e32 vcc, s33, v127
	v_cndmask_b32_e64 v126, v12, v116, s[8:9]
	s_nop 0
	v_cndmask_b32_e32 v117, 0, v115, vcc
	v_cndmask_b32_e64 v127, v115, v117, s[8:9]
	s_nop 0
	v_cvt_pk_bf16_f32 v115, v126, v127
	s_waitcnt lgkmcnt(0)
	s_nop 0
	v_mfma_f32_32x32x16_bf16 v[96:111], v[240:243], v[112:115], v[96:111]
	s_nop 0
	s_waitcnt lgkmcnt(0)
	v_mfma_f32_32x32x16_bf16 v[80:95], v[244:247], v[112:115], v[80:95]
	v_add_f32_e64 v112, v120, v130
	v_add_f32_e64 v113, v121, v131
	v_add_f32_e64 v112, v122, v112
	v_add_f32_e64 v113, v123, v113
	v_add_f32_e64 v112, v124, v112
	v_add_f32_e64 v113, v125, v113
	v_pk_add_f32 v[112:113], v[126:127], v[112:113]
	s_nop 0
	v_add_f32_e32 v12, v112, v113
	ds_bpermute_b32 v112, v165, v12
	s_cmp_ge_i32 s21, s16
	s_cbranch_scc1 .Ldma_m_win2
	v_readfirstlane_b32 s99, v13
	s_add_i32 m0, s99, s98
	v_readfirstlane_b32 s99, v169
	global_load_lds_dwordx4 v[8:9], off
	s_add_i32 m0, s99, s98
	s_nop 0
	global_load_lds_dwordx4 v[6:7], off

; #define MFMA(a, b, c) __builtin_amdgcn_mfma_f32_32x32x16_bf16((a), (b), (c), 0, 0, 0)
; template <int N> DI void wait_vmcnt() { asm volatile("s_waitcnt vmcnt(%0)" ::"n"(N) : "memory"); }
;     ...
;   float mc = m * c2;
;   if (MODE == 2) mc = selbit ? mc : 1e30f;
;   const f32x2v c2v = {c2, c2}, mcv = {-mc, -mc};
;   f32x2v rs2 = {0.f, 0.f};
; #pragma unroll
;   for (int ks = 0; ks < 2; ++ks)
; #pragma unroll
;     for (int st = 0; st < 2; ++st) {
;       union { unsigned u[4]; bf16x8 v; } pf;
; #pragma unroll
;       for (int j = 0; j < 4; ++j) {
;         const int i0 = 8 * st + 2 * j;
;         f32x2v t = {S[ks][i0], S[ks][i0 + 1]};
;         t = __builtin_elementwise_fma(t, c2v, mcv);
;         f32x2v pv;
;         if (variant == 1) { pv = t; } else {
;         pv.x = __builtin_amdgcn_exp2f(t.x);
;         pv.y = __builtin_amdgcn_exp2f(t.y);
;         }
;         if (MODE != 0) {
;           if (need_mask) {
;             pv.x = (S[ks][i0] > -1e29f) ? pv.x : 0.f;
;             pv.y = (S[ks][i0 + 1] > -1e29f) ? pv.y : 0.f;
;           }
;         }
;         rs2 += pv;
;         pf.u[j] = __builtin_bit_cast(unsigned, __builtin_convertvector(pv, hwbf16x2));
;       }
; #pragma unroll
;       for (int d = 0; d < DV / 32; ++d) {
;         const char* vp = base + C::KBYTES + (d * 32 + lr) * C::VSTR + (ks * 32 + 16 * st + 4 * lh) * 2;
;         const s16x4 lo = *(const s16x4*)vp, hi = *(const s16x4*)(vp + 16);
;         const bf16x8 vf = __builtin_shufflevector(lo, hi, 0, 1, 2, 3, 4, 5, 6, 7);
;         O[d] = MFMA(vf, pf.v, O[d]);
;       }
;     }
;   float rs = rs2.x + rs2.y;
;   rs += __shfl_xor(rs, 32);
;   l += rs;
;     ...
;   asm volatile("s_waitcnt vmcnt(0)" ::: "memory");
; #pragma unroll
;   for (int t = 0; t < NST - 1; ++t)
;     if (t < ntile) FA_ISSUE(t, t)
;   int stage = 0;
;   for (int t = 0; t < ntile; ++t) {
;     int ahead = ((ntile < t + NST - 1) ? ntile : t + NST - 1) - (t + 1);
;     if (NST == 4 && ahead >= 2) wait_vmcnt<2 * NI>();
;     else if (ahead >= 1) wait_vmcnt<NI>();
;     else wait_vmcnt<0>();
;     raw_barrier();
;     if (t + NST - 1 < ntile) {
;       const int sn = (stage == 0) ? NST - 1 : stage - 1;
;       FA_ISSUE(t + NST - 1, sn)
.Lfast_win2:
	v_mul_f32_e32 v12, 0xbe38aa3b, v12
	v_pk_fma_f32 v[176:177], v[128:129], s[96:97], v[12:13] op_sel_hi:[1,0,0]
	v_exp_f32_e32 v184, v176
	v_exp_f32_e32 v185, v177
	v_pk_fma_f32 v[128:129], v[130:131], s[96:97], v[12:13] op_sel_hi:[1,0,0]
	v_exp_f32_e32 v186, v128
	v_exp_f32_e32 v187, v129
	v_cvt_pk_bf16_f32 v176, v184, v185
	v_pk_fma_f32 v[128:129], v[132:133], s[96:97], v[12:13] op_sel_hi:[1,0,0]
	v_exp_f32_e32 v188, v128
	v_exp_f32_e32 v189, v129
	v_cvt_pk_bf16_f32 v177, v186, v187
	v_pk_fma_f32 v[128:129], v[134:135], s[96:97], v[12:13] op_sel_hi:[1,0,0]
	v_exp_f32_e32 v134, v128
	v_exp_f32_e32 v135, v129
	v_cvt_pk_bf16_f32 v178, v188, v189
	v_cvt_pk_bf16_f32 v179, v134, v135
	s_waitcnt lgkmcnt(0)
	s_nop 0
	v_mfma_f32_32x32x16_bf16 v[96:111], v[216:219], v[176:179], v[96:111]
	s_waitcnt lgkmcnt(0)
	v_mfma_f32_32x32x16_bf16 v[80:95], v[220:223], v[176:179], v[80:95]
	v_add_f32_e64 v130, v184, 0
	v_add_f32_e64 v131, v185, 0
	v_add_f32_e64 v130, v186, v130
	v_add_f32_e64 v131, v187, v131
	v_add_f32_e64 v130, v188, v130
	v_add_f32_e64 v131, v189, v131
	v_pk_add_f32 v[176:177], v[134:135], v[130:131]
	v_pk_fma_f32 v[130:131], v[136:137], s[96:97], v[12:13] op_sel_hi:[1,0,0]
	v_exp_f32_e32 v178, v130
	v_exp_f32_e32 v179, v131
	v_pk_fma_f32 v[132:133], v[138:139], s[96:97], v[12:13] op_sel_hi:[1,0,0]
	v_exp_f32_e32 v138, v132
	v_exp_f32_e32 v139, v133
	v_cvt_pk_bf16_f32 v130, v178, v179
	v_pk_fma_f32 v[132:133], v[140:141], s[96:97], v[12:13] op_sel_hi:[1,0,0]
	v_exp_f32_e32 v140, v132
	v_exp_f32_e32 v141, v133
	v_cvt_pk_bf16_f32 v131, v138, v139
	v_pk_fma_f32 v[134:135], v[142:143], s[96:97], v[12:13] op_sel_hi:[1,0,0]
	v_exp_f32_e32 v142, v134
	v_exp_f32_e32 v143, v135
	v_cvt_pk_bf16_f32 v132, v140, v141
	v_cvt_pk_bf16_f32 v133, v142, v143
	s_nop 1
	v_mfma_f32_32x32x16_bf16 v[96:111], v[224:227], v[130:133], v[96:111]
	s_waitcnt lgkmcnt(0)
	v_mfma_f32_32x32x16_bf16 v[80:95], v[228:231], v[130:133], v[80:95]
	v_fma_f32 v132, v112, s96, v12
	v_fma_f32 v133, v113, s96, v12
	v_fma_f32 v134, v114, s96, v12
	v_fma_f32 v135, v115, s96, v12
	v_exp_f32_e32 v132, v132
	v_exp_f32_e32 v133, v133
	v_pk_add_f32 v[130:131], v[178:179], v[176:177]
	v_pk_add_f32 v[130:131], v[138:139], v[130:131]
	v_exp_f32_e32 v134, v134
	v_exp_f32_e32 v135, v135
	v_cvt_pk_bf16_f32 v112, v132, v133
	v_pk_add_f32 v[130:131], v[140:141], v[130:131]
	v_pk_add_f32 v[130:131], v[142:143], v[130:131]
	v_pk_fma_f32 v[114:115], v[116:117], s[96:97], v[12:13] op_sel_hi:[1,0,0]
	v_exp_f32_e32 v136, v114
	v_exp_f32_e32 v137, v115
	v_cvt_pk_bf16_f32 v113, v134, v135
	v_pk_fma_f32 v[116:117], v[118:119], s[96:97], v[12:13] op_sel_hi:[1,0,0]
	v_exp_f32_e32 v138, v116
	v_exp_f32_e32 v139, v117
	v_cvt_pk_bf16_f32 v114, v136, v137
	v_cvt_pk_bf16_f32 v115, v138, v139
	s_waitcnt lgkmcnt(0)
	s_nop 0
	v_mfma_f32_32x32x16_bf16 v[96:111], v[232:235], v[112:115], v[96:111]
	s_waitcnt lgkmcnt(0)
	v_mfma_f32_32x32x16_bf16 v[80:95], v[236:239], v[112:115], v[80:95]
	v_add_f32_e64 v112, v132, v130
	v_add_f32_e64 v113, v133, v131
	v_add_f32_e64 v112, v134, v112
	v_add_f32_e64 v113, v135, v113
	v_add_f32_e64 v112, v136, v112
	v_add_f32_e64 v113, v137, v113
	v_pk_add_f32 v[130:131], v[138:139], v[112:113]
	v_pk_fma_f32 v[112:113], v[120:121], s[96:97], v[12:13] op_sel_hi:[1,0,0]
	v_exp_f32_e32 v120, v112
	v_exp_f32_e32 v121, v113
	v_pk_fma_f32 v[114:115], v[122:123], s[96:97], v[12:13] op_sel_hi:[1,0,0]
	v_exp_f32_e32 v122, v114
	v_exp_f32_e32 v123, v115
	v_cvt_pk_bf16_f32 v112, v120, v121
	v_pk_fma_f32 v[114:115], v[124:125], s[96:97], v[12:13] op_sel_hi:[1,0,0]
	v_exp_f32_e32 v124, v114
	v_exp_f32_e32 v125, v115
	v_cvt_pk_bf16_f32 v113, v122, v123
	v_pk_fma_f32 v[116:117], v[126:127], s[96:97], v[12:13] op_sel_hi:[1,0,0]
	v_exp_f32_e32 v126, v116
	v_exp_f32_e32 v127, v117
	v_cvt_pk_bf16_f32 v114, v124, v125
	v_cvt_pk_bf16_f32 v115, v126, v127
	s_waitcnt lgkmcnt(0)
	s_nop 0
	v_mfma_f32_32x32x16_bf16 v[96:111], v[240:243], v[112:115], v[96:111]
	s_waitcnt lgkmcnt(0)
	v_mfma_f32_32x32x16_bf16 v[80:95], v[244:247], v[112:115], v[80:95]
	v_add_f32_e64 v112, v120, v130
	v_add_f32_e64 v113, v121, v131
	v_add_f32_e64 v112, v122, v112
	v_add_f32_e64 v113, v123, v113
	v_add_f32_e64 v112, v124, v112
	v_add_f32_e64 v113, v125, v113
	v_pk_add_f32 v[112:113], v[126:127], v[112:113]
	v_add_f32_e32 v12, v112, v113
	ds_bpermute_b32 v112, v165, v12
	s_cmp_ge_i32 s21, s16
	s_cbranch_scc1 .Ldma_f_win2
	v_readfirstlane_b32 s99, v13
	s_add_i32 m0, s99, s98
	v_readfirstlane_b32 s99, v169
	global_load_lds_dwordx4 v[8:9], off
	s_add_i32 m0, s99, s98
	s_nop 0
	global_load_lds_dwordx4 v[6:7], off

; template <int N> DI void wait_vmcnt() { asm volatile("s_waitcnt vmcnt(%0)" ::"n"(N) : "memory"); }
;     ...
;   float mx = fmaxf(S[0][0], S[0][1]);
; #pragma unroll
;   for (int ks = 0; ks < 2; ++ks)
; #pragma unroll
;     for (int i = (ks ? 0 : 2); i < 16; i += 2) mx = fmaxf(fmaxf(mx, S[ks][i]), S[ks][i + 1]);
;   mx = fmaxf(mx, __shfl_xor(mx, 32));
;   if (MODE == 2) mx = selbit ? mx : -1e30f;
;   const float mn = fmaxf(m, mx);
;   if (__any((mn - m) * c2 > 8.f)) {
;     const float alpha = __builtin_amdgcn_exp2f((m - mn) * c2);
;     m = mn;
;     l *= alpha;
; #pragma unroll
;     for (int d = 0; d < DV / 32; ++d) O[d] = O[d] * alpha;
;   }
;     ...
;   asm volatile("s_waitcnt vmcnt(0)" ::: "memory");
; #pragma unroll
;   for (int t = 0; t < NST - 1; ++t)
;     if (t < ntile) FA_ISSUE(t, t)
;   int stage = 0;
;   for (int t = 0; t < ntile; ++t) {
;     int ahead = ((ntile < t + NST - 1) ? ntile : t + NST - 1) - (t + 1);
;     if (NST == 4 && ahead >= 2) wait_vmcnt<2 * NI>();
;     else if (ahead >= 1) wait_vmcnt<NI>();
;     else wait_vmcnt<0>();
;     raw_barrier();
;     if (t + NST - 1 < ntile) {
;       const int sn = (stage == 0) ? NST - 1 : stage - 1;
;       FA_ISSUE(t + NST - 1, sn)
.LBB0_600:
	s_nop 0
	v_max_f32_e32 v12, v129, v129
	v_max_f32_e32 v176, v128, v128
	v_max_f32_e32 v12, v176, v12
	v_max3_f32 v12, v12, v130, v131
	v_max3_f32 v12, v12, v132, v133
	v_max3_f32 v12, v12, v134, v135
	v_max3_f32 v12, v12, v136, v137
	v_max3_f32 v12, v12, v138, v139
	v_max3_f32 v12, v12, v140, v141
	v_max3_f32 v12, v12, v142, v143
	v_max3_f32 v12, v12, v112, v113
	v_max3_f32 v12, v12, v114, v115
	v_max3_f32 v12, v12, v116, v117
	v_max3_f32 v12, v12, v118, v119
	v_max3_f32 v12, v12, v120, v121
	v_max3_f32 v12, v12, v122, v123
	v_max3_f32 v12, v12, v124, v125
	v_max3_f32 v12, v12, v126, v127
	ds_bpermute_b32 v176, v165, v12
	ds_read2_b64 v[216:219], v243 offset0:128 offset1:130
	ds_read2_b64 v[220:223], v247 offset0:192 offset1:194
	ds_read2_b64 v[224:227], v243 offset0:132 offset1:134
	ds_read2_b64 v[228:231], v247 offset0:196 offset1:198
	ds_read2_b64 v[232:235], v243 offset0:136 offset1:138
	ds_read2_b64 v[236:239], v247 offset0:200 offset1:202
	ds_read2_b64 v[240:243], v243 offset0:140 offset1:142
	ds_read2_b64 v[244:247], v247 offset0:204 offset1:206
	s_cmp_ge_i32 s21, s16
	s_cbranch_scc1 .Ldma_x_win2
	s_add_i32 s98, s0, 0xffffb800
	s_cmp_lg_u32 s22, 0
	s_cselect_b32 s98, s98, 0xd800
	v_readfirstlane_b32 s99, v15
	s_add_i32 m0, s99, s98
	s_nop 0
	global_load_lds_dwordx4 v[10:11], off
.Ldma_x_win2:
	s_waitcnt lgkmcnt(8)
	v_max3_f32 v12, v14, v12, v176
	v_sub_f32_e32 v176, v12, v14
	v_mul_f32_e32 v176, 0x3e38aa3b, v176
	v_cmp_lt_f32_e32 vcc, s51, v176
	s_cbranch_vccnz .LBB0_584
	v_mov_b32_e32 v12, v14
	s_branch .LBB0_585
